# K-loop load segments re-emitted: 4 LDS-DMA per phase, SGPR-base addressing, m0 from ldsw+constant, kstep via instruction offset, ds_reads as m0 wait states (no s_nop, no VALU), merged waits; plus xgen
# baseline (speedup 1.0000x reference)
; #define PG8_STAGE(bufoff, gbase, voff) do { _Pragma("unroll") for (int _i = 0; _i < 2; ++_i) \
;         __builtin_amdgcn_global_load_lds((const unsigned*)((const char*)(gbase) + (voff)[_i]), (LAS unsigned*)(lds + (bufoff) + ldsw + _i * 8192), 16, 0, 0); } while (0)
; #define PG8_LDA(dst, b, h) do { _Pragma("unroll") for (int m = 0; m < 4; ++m) _Pragma("unroll") for (int k = 0; k < 2; ++k) dst[m][k] = *(const LAS bf16x8*)(lds + PG8_SA(b, h) + aoff + m * 2048 + k * 1024); } while (0)
; #define PG8_LDB(dst, b, h) do { _Pragma("unroll") for (int n = 0; n < 2; ++n) _Pragma("unroll") for (int k = 0; k < 2; ++k) dst[n][k] = *(const LAS bf16x8*)(lds + PG8_SB(b, h) + boff + n * 2048 + k * 1024); } while (0)
; #define PG8_MMA(ai, bj, At, Bt) do { __builtin_amdgcn_s_setprio(1); _Pragma("unroll") for (int m = 0; m < 4; ++m) _Pragma("unroll") for (int n = 0; n < 2; ++n) _Pragma("unroll") for (int k = 0; k < 2; ++k) \
;         acc[ai][bj][m][n] = __builtin_amdgcn_mfma_f32_16x16x32_bf16(Bt[n][k], At[m][k], acc[ai][bj][m][n], 0, 0, 0); __builtin_amdgcn_s_setprio(0); } while (0)
; #define PG8_WAIT_V(n) asm volatile("s_waitcnt vmcnt(" #n ")" ::: "memory")
; #define PG8_WAIT_L(n) asm volatile("s_waitcnt lgkmcnt(" #n ")" ::: "memory")
; #define PG8_BAR __builtin_amdgcn_s_barrier()
; #define PG8_SCHED __builtin_amdgcn_sched_barrier(0)
; template <class Epi, bool ALIGN_EPI = true>
; __device__ __forceinline__ void gemm_phase(LAS unsigned char* lds, const Gemm g, const Sched& S, const Epi& E) {
;     ...
;             const int rflag = __builtin_amdgcn_readfirstlane(t | (int)(ui == 0));
;             PG8_LDB(B0, 0, 0); PG8_LDB(B1, 0, 1); PG8_SCHED; PG8_LDA(At, 0, 0); PG8_STAGE(PG8_SA(1, 1), a1 + hstepA, voffA);
;             if constexpr (Epi::NSTORES > 0) PG8_WAIT_RELAX(rflag, 8 + Epi::NSTORES); else PG8_WAIT_V(8);
;             PG8_WAIT_L(0); PG8_BAR; PG8_MMA(0, 0, At, B0); PG8_MMA(0, 1, At, B1); PG8_BAR; PG8_SCHED;
;             PG8_LDA(At, 0, 1); PG8_STAGE(PG8_SB(0, 0), b2, voffB); PG8_STAGE(PG8_SB(0, 1), b2 + hstepB, voffB); PG8_STAGE(PG8_SA(0, 0), a2, voffA);
;             if constexpr (Epi::NSTORES > 0) PG8_WAIT_RELAX(rflag, 8 + Epi::NSTORES); else PG8_WAIT_V(8);
;             PG8_WAIT_L(0); PG8_BAR; PG8_MMA(1, 0, At, B0); PG8_MMA(1, 1, At, B1); PG8_BAR; PG8_SCHED;
.LBB0_500:
	s_add_i32 s22, s6, 2
	s_add_u32 s7, s4, 0xfff80080
	s_addc_u32 s14, s5, -1
	s_cmp_eq_u32 s94, s6
	v_add_u32_e32 v182, s6, v2
	s_cselect_b32 s15, s16, s14
	s_cselect_b32 s14, s17, s7
	s_waitcnt lgkmcnt(0)
	s_cselect_b32 s7, s18, s21
	s_cselect_b32 s6, s19, s20
	v_readfirstlane_b32 s53, v182
	s_add_u32 s100, s4, 0xfff80000
	s_addc_u32 s101, s5, -1
	ds_read_b128 v[134:137], v185
	ds_read_b128 v[138:141], v185 offset:1024
	ds_read_b128 v[142:145], v185 offset:2048
	ds_read_b128 v[146:149], v185 offset:3072
	ds_read_b128 v[162:165], v185 offset:16384
	ds_read_b128 v[166:169], v185 offset:17408
	ds_read_b128 v[170:173], v185 offset:18432
	ds_read_b128 v[174:177], v185 offset:19456
	ds_read_b128 v[178:181], v186
	ds_read_b128 v[188:191], v186 offset:1024
	ds_read_b128 v[192:195], v186 offset:2048
	ds_read_b128 v[206:209], v186 offset:3072
	s_mov_b32 m0, s92
	ds_read_b128 v[224:227], v186 offset:4096
	global_load_lds_dwordx4 v158, s[100:101]
	s_mov_b32 m0, s93
	ds_read_b128 v[228:231], v186 offset:5120
	global_load_lds_dwordx4 v160, s[100:101]
	s_add_i32 m0, s50, 0xc000
	ds_read_b128 v[232:235], v186 offset:6144
	global_load_lds_dwordx4 v158, s[4:5]
	s_add_i32 m0, s50, 0xe000
	ds_read_b128 v[236:239], v186 offset:7168
	global_load_lds_dwordx4 v160, s[4:5]
	s_cmp_eq_u32 s53, 0
	s_cbranch_scc1 .Lrw6
	s_waitcnt vmcnt(8)
.Lrw6:
	s_waitcnt vmcnt(24) lgkmcnt(0)
	s_barrier
	s_setprio 1
	v_mfma_f32_16x16x32_bf16 v[130:133], v[134:137], v[178:181], v[130:133]
	v_mfma_f32_16x16x32_bf16 v[126:129], v[142:145], v[178:181], v[126:129]
	v_mfma_f32_16x16x32_bf16 v[122:125], v[134:137], v[192:195], v[122:125]
	v_mfma_f32_16x16x32_bf16 v[118:121], v[142:145], v[192:195], v[118:121]
	v_mfma_f32_16x16x32_bf16 v[114:117], v[134:137], v[224:227], v[114:117]
	v_mfma_f32_16x16x32_bf16 v[110:113], v[142:145], v[224:227], v[110:113]
	v_mfma_f32_16x16x32_bf16 v[106:109], v[134:137], v[232:235], v[106:109]
	v_mfma_f32_16x16x32_bf16 v[102:105], v[142:145], v[232:235], v[102:105]
	v_mfma_f32_16x16x32_bf16 v[130:133], v[138:141], v[188:191], v[130:133]
	v_mfma_f32_16x16x32_bf16 v[126:129], v[146:149], v[188:191], v[126:129]
	v_mfma_f32_16x16x32_bf16 v[122:125], v[138:141], v[206:209], v[122:125]
	v_mfma_f32_16x16x32_bf16 v[118:121], v[146:149], v[206:209], v[118:121]
	v_mfma_f32_16x16x32_bf16 v[114:117], v[138:141], v[228:231], v[114:117]
	v_mfma_f32_16x16x32_bf16 v[110:113], v[146:149], v[228:231], v[110:113]
	v_mfma_f32_16x16x32_bf16 v[106:109], v[138:141], v[236:239], v[106:109]
	v_mfma_f32_16x16x32_bf16 v[102:105], v[146:149], v[236:239], v[102:105]
	s_setprio 0
	s_setprio 1
	v_mfma_f32_16x16x32_bf16 v[98:101], v[162:165], v[178:181], v[98:101]
	v_mfma_f32_16x16x32_bf16 v[94:97], v[170:173], v[178:181], v[94:97]
	v_mfma_f32_16x16x32_bf16 v[90:93], v[162:165], v[192:195], v[90:93]
	v_mfma_f32_16x16x32_bf16 v[86:89], v[170:173], v[192:195], v[86:89]
	v_mfma_f32_16x16x32_bf16 v[82:85], v[162:165], v[224:227], v[82:85]
	v_mfma_f32_16x16x32_bf16 v[78:81], v[170:173], v[224:227], v[78:81]
	v_mfma_f32_16x16x32_bf16 v[74:77], v[162:165], v[232:235], v[74:77]
	v_mfma_f32_16x16x32_bf16 v[70:73], v[170:173], v[232:235], v[70:73]
	v_mfma_f32_16x16x32_bf16 v[98:101], v[166:169], v[188:191], v[98:101]
	v_mfma_f32_16x16x32_bf16 v[94:97], v[174:177], v[188:191], v[94:97]
	v_mfma_f32_16x16x32_bf16 v[90:93], v[166:169], v[206:209], v[90:93]
	v_mfma_f32_16x16x32_bf16 v[86:89], v[174:177], v[206:209], v[86:89]
	v_mfma_f32_16x16x32_bf16 v[82:85], v[166:169], v[228:231], v[82:85]
	v_mfma_f32_16x16x32_bf16 v[78:81], v[174:177], v[228:231], v[78:81]
	v_mfma_f32_16x16x32_bf16 v[74:77], v[166:169], v[236:239], v[74:77]
	v_mfma_f32_16x16x32_bf16 v[70:73], v[174:177], v[236:239], v[70:73]
	s_setprio 0
	s_barrier
	s_add_u32 s24, s6, 0x80000
	s_addc_u32 s25, s7, 0
	ds_read_b128 v[178:181], v186 offset:16384
	ds_read_b128 v[188:191], v186 offset:17408
	ds_read_b128 v[192:195], v186 offset:18432
	ds_read_b128 v[206:209], v186 offset:19456
	s_add_i32 m0, s27, 0x10000
	ds_read_b128 v[224:227], v186 offset:20480
	global_load_lds_dwordx4 v152, s[6:7]
	s_add_i32 m0, s27, 0x12000
	ds_read_b128 v[228:231], v186 offset:21504
	global_load_lds_dwordx4 v156, s[6:7]
	s_add_i32 m0, s27, 0x14000
	ds_read_b128 v[232:235], v186 offset:22528
	global_load_lds_dwordx4 v152, s[24:25]
	s_add_i32 m0, s27, 0x16000
	ds_read_b128 v[236:239], v186 offset:23552
	global_load_lds_dwordx4 v156, s[24:25]
	s_waitcnt vmcnt(6) lgkmcnt(0)
; #define PG8_STAGE(bufoff, gbase, voff) do { _Pragma("unroll") for (int _i = 0; _i < 2; ++_i) \
;         __builtin_amdgcn_global_load_lds((const unsigned*)((const char*)(gbase) + (voff)[_i]), (LAS unsigned*)(lds + (bufoff) + ldsw + _i * 8192), 16, 0, 0); } while (0)
; #define PG8_LDA(dst, b, h) do { _Pragma("unroll") for (int m = 0; m < 4; ++m) _Pragma("unroll") for (int k = 0; k < 2; ++k) dst[m][k] = *(const LAS bf16x8*)(lds + PG8_SA(b, h) + aoff + m * 2048 + k * 1024); } while (0)
; #define PG8_LDB(dst, b, h) do { _Pragma("unroll") for (int n = 0; n < 2; ++n) _Pragma("unroll") for (int k = 0; k < 2; ++k) dst[n][k] = *(const LAS bf16x8*)(lds + PG8_SB(b, h) + boff + n * 2048 + k * 1024); } while (0)
; #define PG8_MMA(ai, bj, At, Bt) do { __builtin_amdgcn_s_setprio(1); _Pragma("unroll") for (int m = 0; m < 4; ++m) _Pragma("unroll") for (int n = 0; n < 2; ++n) _Pragma("unroll") for (int k = 0; k < 2; ++k) \
;         acc[ai][bj][m][n] = __builtin_amdgcn_mfma_f32_16x16x32_bf16(Bt[n][k], At[m][k], acc[ai][bj][m][n], 0, 0, 0); __builtin_amdgcn_s_setprio(0); } while (0)
; #define PG8_WAIT_V(n) asm volatile("s_waitcnt vmcnt(" #n ")" ::: "memory")
; #define PG8_WAIT_L(n) asm volatile("s_waitcnt lgkmcnt(" #n ")" ::: "memory")
; #define PG8_BAR __builtin_amdgcn_s_barrier()
; #define PG8_SCHED __builtin_amdgcn_sched_barrier(0)
; template <class Epi, bool ALIGN_EPI = true>
; __device__ __forceinline__ void gemm_phase(LAS unsigned char* lds, const Gemm g, const Sched& S, const Epi& E) {
;     ...
;             PG8_WAIT_L(0); PG8_BAR; PG8_MMA(1, 0, At, B0); PG8_MMA(1, 1, At, B1); PG8_BAR; PG8_SCHED;
;             PG8_LDB(B0, 1, 0); PG8_LDB(B1, 1, 1); PG8_SCHED; PG8_LDA(At, 1, 0); PG8_STAGE(PG8_SA(0, 1), a2 + hstepA, voffA);
;             PG8_WAIT_V(8); PG8_WAIT_L(0); PG8_BAR; PG8_MMA(0, 0, At, B0); PG8_MMA(0, 1, At, B1); PG8_BAR; PG8_SCHED;
;             PG8_LDA(At, 1, 1); PG8_STAGE(PG8_SB(1, 0), b3, voffB); PG8_STAGE(PG8_SB(1, 1), b3 + hstepB, voffB); PG8_STAGE(PG8_SA(1, 0), a3, voffA);
.Lrw7:
	s_barrier
	s_setprio 1
	v_mfma_f32_16x16x32_bf16 v[66:69], v[134:137], v[178:181], v[66:69]
	v_mfma_f32_16x16x32_bf16 v[62:65], v[142:145], v[178:181], v[62:65]
	v_mfma_f32_16x16x32_bf16 v[58:61], v[134:137], v[192:195], v[58:61]
	v_mfma_f32_16x16x32_bf16 v[54:57], v[142:145], v[192:195], v[54:57]
	v_mfma_f32_16x16x32_bf16 v[50:53], v[134:137], v[224:227], v[50:53]
	v_mfma_f32_16x16x32_bf16 v[46:49], v[142:145], v[224:227], v[46:49]
	v_mfma_f32_16x16x32_bf16 v[42:45], v[134:137], v[232:235], v[42:45]
	v_mfma_f32_16x16x32_bf16 v[38:41], v[142:145], v[232:235], v[38:41]
	v_mfma_f32_16x16x32_bf16 v[66:69], v[138:141], v[188:191], v[66:69]
	v_mfma_f32_16x16x32_bf16 v[62:65], v[146:149], v[188:191], v[62:65]
	v_mfma_f32_16x16x32_bf16 v[58:61], v[138:141], v[206:209], v[58:61]
	v_mfma_f32_16x16x32_bf16 v[54:57], v[146:149], v[206:209], v[54:57]
	v_mfma_f32_16x16x32_bf16 v[50:53], v[138:141], v[228:231], v[50:53]
	v_mfma_f32_16x16x32_bf16 v[46:49], v[146:149], v[228:231], v[46:49]
	v_mfma_f32_16x16x32_bf16 v[42:45], v[138:141], v[236:239], v[42:45]
	v_mfma_f32_16x16x32_bf16 v[38:41], v[146:149], v[236:239], v[38:41]
	s_setprio 0
	s_setprio 1
	v_mfma_f32_16x16x32_bf16 v[34:37], v[162:165], v[178:181], v[34:37]
	v_mfma_f32_16x16x32_bf16 v[30:33], v[170:173], v[178:181], v[30:33]
	v_mfma_f32_16x16x32_bf16 v[26:29], v[162:165], v[192:195], v[26:29]
	v_mfma_f32_16x16x32_bf16 v[22:25], v[170:173], v[192:195], v[22:25]
	v_mfma_f32_16x16x32_bf16 v[18:21], v[162:165], v[224:227], v[18:21]
	v_mfma_f32_16x16x32_bf16 v[14:17], v[170:173], v[224:227], v[14:17]
	v_mfma_f32_16x16x32_bf16 v[10:13], v[162:165], v[232:235], v[10:13]
	v_mfma_f32_16x16x32_bf16 v[4:7], v[170:173], v[232:235], v[6:9]
	v_mfma_f32_16x16x32_bf16 v[34:37], v[166:169], v[188:191], v[34:37]
	v_mfma_f32_16x16x32_bf16 v[30:33], v[174:177], v[188:191], v[30:33]
	v_mfma_f32_16x16x32_bf16 v[26:29], v[166:169], v[206:209], v[26:29]
	v_mfma_f32_16x16x32_bf16 v[22:25], v[174:177], v[206:209], v[22:25]
	v_mfma_f32_16x16x32_bf16 v[18:21], v[166:169], v[228:231], v[18:21]
	v_mfma_f32_16x16x32_bf16 v[14:17], v[174:177], v[228:231], v[14:17]
	v_mfma_f32_16x16x32_bf16 v[10:13], v[166:169], v[236:239], v[10:13]
	v_mfma_f32_16x16x32_bf16 v[4:7], v[174:177], v[236:239], v[4:7]
	s_setprio 0
	s_barrier
	s_mov_b64 s[100:101], s[14:15]
	s_add_u32 s14, s14, 0x80000
	s_addc_u32 s15, s15, 0
	ds_read_b128 v[134:137], v185 offset:32768
	ds_read_b128 v[138:141], v185 offset:33792
	ds_read_b128 v[142:145], v185 offset:34816
	ds_read_b128 v[146:149], v185 offset:35840
	ds_read_b128 v[162:165], v185 offset:49152
	ds_read_b128 v[166:169], v185 offset:50176
	ds_read_b128 v[170:173], v185 offset:51200
	ds_read_b128 v[174:177], v185 offset:52224
	ds_read_b128 v[178:181], v186 offset:32768
	ds_read_b128 v[188:191], v186 offset:33792
	ds_read_b128 v[192:195], v186 offset:34816
	ds_read_b128 v[206:209], v186 offset:35840
	s_mov_b32 m0, s50
	ds_read_b128 v[224:227], v186 offset:36864
	global_load_lds_dwordx4 v150, s[100:101]
	s_mov_b32 m0, s51
	ds_read_b128 v[228:231], v186 offset:37888
	global_load_lds_dwordx4 v154, s[100:101]
	s_mov_b32 m0, s36
	ds_read_b128 v[232:235], v186 offset:38912
	global_load_lds_dwordx4 v150, s[14:15]
	s_mov_b32 m0, s37
	ds_read_b128 v[236:239], v186 offset:39936
	global_load_lds_dwordx4 v154, s[14:15]
	s_waitcnt vmcnt(8) lgkmcnt(0)
	s_barrier
; #define PG8_STAGE(bufoff, gbase, voff) do { _Pragma("unroll") for (int _i = 0; _i < 2; ++_i) \
;         __builtin_amdgcn_global_load_lds((const unsigned*)((const char*)(gbase) + (voff)[_i]), (LAS unsigned*)(lds + (bufoff) + ldsw + _i * 8192), 16, 0, 0); } while (0)
; #define PG8_LDA(dst, b, h) do { _Pragma("unroll") for (int m = 0; m < 4; ++m) _Pragma("unroll") for (int k = 0; k < 2; ++k) dst[m][k] = *(const LAS bf16x8*)(lds + PG8_SA(b, h) + aoff + m * 2048 + k * 1024); } while (0)
; #define PG8_MMA(ai, bj, At, Bt) do { __builtin_amdgcn_s_setprio(1); _Pragma("unroll") for (int m = 0; m < 4; ++m) _Pragma("unroll") for (int n = 0; n < 2; ++n) _Pragma("unroll") for (int k = 0; k < 2; ++k) \
;         acc[ai][bj][m][n] = __builtin_amdgcn_mfma_f32_16x16x32_bf16(Bt[n][k], At[m][k], acc[ai][bj][m][n], 0, 0, 0); __builtin_amdgcn_s_setprio(0); } while (0)
; #define PG8_WAIT_V(n) asm volatile("s_waitcnt vmcnt(" #n ")" ::: "memory")
; #define PG8_WAIT_L(n) asm volatile("s_waitcnt lgkmcnt(" #n ")" ::: "memory")
; #define PG8_BAR __builtin_amdgcn_s_barrier()
; #define PG8_SCHED __builtin_amdgcn_sched_barrier(0)
; template <class Epi, bool ALIGN_EPI = true>
; __device__ __forceinline__ void gemm_phase(LAS unsigned char* lds, const Gemm g, const Sched& S, const Epi& E) {
;     ...
;             PG8_LDA(At, 1, 1); PG8_STAGE(PG8_SB(1, 0), b3, voffB); PG8_STAGE(PG8_SB(1, 1), b3 + hstepB, voffB); PG8_STAGE(PG8_SA(1, 0), a3, voffA);
;             PG8_WAIT_V(8); PG8_WAIT_L(0); PG8_BAR; PG8_MMA(1, 0, At, B0); PG8_MMA(1, 1, At, B1); PG8_BAR; PG8_SCHED;
;         }
	s_setprio 1
	v_mfma_f32_16x16x32_bf16 v[130:133], v[134:137], v[178:181], v[130:133]
	v_mfma_f32_16x16x32_bf16 v[126:129], v[142:145], v[178:181], v[126:129]
	v_mfma_f32_16x16x32_bf16 v[122:125], v[134:137], v[192:195], v[122:125]
	v_mfma_f32_16x16x32_bf16 v[118:121], v[142:145], v[192:195], v[118:121]
	v_mfma_f32_16x16x32_bf16 v[114:117], v[134:137], v[224:227], v[114:117]
	v_mfma_f32_16x16x32_bf16 v[110:113], v[142:145], v[224:227], v[110:113]
	v_mfma_f32_16x16x32_bf16 v[106:109], v[134:137], v[232:235], v[106:109]
	v_mfma_f32_16x16x32_bf16 v[102:105], v[142:145], v[232:235], v[102:105]
	v_mfma_f32_16x16x32_bf16 v[130:133], v[138:141], v[188:191], v[130:133]
	v_mfma_f32_16x16x32_bf16 v[126:129], v[146:149], v[188:191], v[126:129]
	v_mfma_f32_16x16x32_bf16 v[122:125], v[138:141], v[206:209], v[122:125]
	v_mfma_f32_16x16x32_bf16 v[118:121], v[146:149], v[206:209], v[118:121]
	v_mfma_f32_16x16x32_bf16 v[114:117], v[138:141], v[228:231], v[114:117]
	v_mfma_f32_16x16x32_bf16 v[110:113], v[146:149], v[228:231], v[110:113]
	v_mfma_f32_16x16x32_bf16 v[106:109], v[138:141], v[236:239], v[106:109]
	v_mfma_f32_16x16x32_bf16 v[102:105], v[146:149], v[236:239], v[102:105]
	s_setprio 0
	s_setprio 1
	v_mfma_f32_16x16x32_bf16 v[98:101], v[162:165], v[178:181], v[98:101]
	v_mfma_f32_16x16x32_bf16 v[94:97], v[170:173], v[178:181], v[94:97]
	v_mfma_f32_16x16x32_bf16 v[90:93], v[162:165], v[192:195], v[90:93]
	v_mfma_f32_16x16x32_bf16 v[86:89], v[170:173], v[192:195], v[86:89]
	v_mfma_f32_16x16x32_bf16 v[82:85], v[162:165], v[224:227], v[82:85]
	v_mfma_f32_16x16x32_bf16 v[78:81], v[170:173], v[224:227], v[78:81]
	v_mfma_f32_16x16x32_bf16 v[74:77], v[162:165], v[232:235], v[74:77]
	v_mfma_f32_16x16x32_bf16 v[70:73], v[170:173], v[232:235], v[70:73]
	v_mfma_f32_16x16x32_bf16 v[98:101], v[166:169], v[188:191], v[98:101]
	v_mfma_f32_16x16x32_bf16 v[94:97], v[174:177], v[188:191], v[94:97]
	v_mfma_f32_16x16x32_bf16 v[90:93], v[166:169], v[206:209], v[90:93]
	v_mfma_f32_16x16x32_bf16 v[86:89], v[174:177], v[206:209], v[86:89]
	v_mfma_f32_16x16x32_bf16 v[82:85], v[166:169], v[228:231], v[82:85]
	v_mfma_f32_16x16x32_bf16 v[78:81], v[174:177], v[228:231], v[78:81]
	v_mfma_f32_16x16x32_bf16 v[74:77], v[166:169], v[236:239], v[74:77]
	v_mfma_f32_16x16x32_bf16 v[70:73], v[174:177], v[236:239], v[70:73]
	s_setprio 0
	s_barrier
	ds_read_b128 v[178:181], v186 offset:49152
	ds_read_b128 v[188:191], v186 offset:50176
	ds_read_b128 v[192:195], v186 offset:51200
	ds_read_b128 v[206:209], v186 offset:52224
	s_add_i32 m0, s27, 0x17f80
	ds_read_b128 v[224:227], v186 offset:53248
	global_load_lds_dwordx4 v152, s[6:7] offset:128
	s_add_i32 m0, s27, 0x19f80
	ds_read_b128 v[228:231], v186 offset:54272
	global_load_lds_dwordx4 v156, s[6:7] offset:128
	s_add_i32 m0, s27, 0x1c000
	s_add_u32 s6, s6, 0x80080
	s_addc_u32 s7, s7, 0
	ds_read_b128 v[232:235], v186 offset:55296
	global_load_lds_dwordx4 v152, s[6:7]
	s_add_i32 m0, s27, 0x1e000
	ds_read_b128 v[236:239], v186 offset:56320
	global_load_lds_dwordx4 v156, s[6:7]
	s_waitcnt vmcnt(6) lgkmcnt(0)
	s_barrier
	s_setprio 1
	v_mfma_f32_16x16x32_bf16 v[66:69], v[134:137], v[178:181], v[66:69]
	v_mfma_f32_16x16x32_bf16 v[62:65], v[142:145], v[178:181], v[62:65]
	v_mfma_f32_16x16x32_bf16 v[58:61], v[134:137], v[192:195], v[58:61]
	v_mfma_f32_16x16x32_bf16 v[54:57], v[142:145], v[192:195], v[54:57]
	v_mfma_f32_16x16x32_bf16 v[50:53], v[134:137], v[224:227], v[50:53]
	v_mfma_f32_16x16x32_bf16 v[46:49], v[142:145], v[224:227], v[46:49]
	v_mfma_f32_16x16x32_bf16 v[42:45], v[134:137], v[232:235], v[42:45]
	v_mfma_f32_16x16x32_bf16 v[38:41], v[142:145], v[232:235], v[38:41]
	v_mfma_f32_16x16x32_bf16 v[66:69], v[138:141], v[188:191], v[66:69]
	v_mfma_f32_16x16x32_bf16 v[62:65], v[146:149], v[188:191], v[62:65]
	v_mfma_f32_16x16x32_bf16 v[58:61], v[138:141], v[206:209], v[58:61]
	v_mfma_f32_16x16x32_bf16 v[54:57], v[146:149], v[206:209], v[54:57]
	v_mfma_f32_16x16x32_bf16 v[50:53], v[138:141], v[228:231], v[50:53]
	v_mfma_f32_16x16x32_bf16 v[46:49], v[146:149], v[228:231], v[46:49]
	v_mfma_f32_16x16x32_bf16 v[42:45], v[138:141], v[236:239], v[42:45]
	v_mfma_f32_16x16x32_bf16 v[38:41], v[146:149], v[236:239], v[38:41]
	s_setprio 0
	s_setprio 1
	v_mfma_f32_16x16x32_bf16 v[34:37], v[162:165], v[178:181], v[34:37]
	v_mfma_f32_16x16x32_bf16 v[30:33], v[170:173], v[178:181], v[30:33]
	v_mfma_f32_16x16x32_bf16 v[26:29], v[162:165], v[192:195], v[26:29]
	v_mfma_f32_16x16x32_bf16 v[22:25], v[170:173], v[192:195], v[22:25]
	v_mfma_f32_16x16x32_bf16 v[18:21], v[162:165], v[224:227], v[18:21]
	v_mfma_f32_16x16x32_bf16 v[14:17], v[170:173], v[224:227], v[14:17]
	v_mfma_f32_16x16x32_bf16 v[8:11], v[162:165], v[232:235], v[10:13]
	v_mfma_f32_16x16x32_bf16 v[4:7], v[170:173], v[232:235], v[4:7]
	v_mfma_f32_16x16x32_bf16 v[34:37], v[166:169], v[188:191], v[34:37]
	v_mfma_f32_16x16x32_bf16 v[30:33], v[174:177], v[188:191], v[30:33]
	v_mfma_f32_16x16x32_bf16 v[26:29], v[166:169], v[206:209], v[26:29]
	v_mfma_f32_16x16x32_bf16 v[22:25], v[174:177], v[206:209], v[22:25]
	v_mfma_f32_16x16x32_bf16 v[18:21], v[166:169], v[228:231], v[18:21]
	v_mfma_f32_16x16x32_bf16 v[14:17], v[174:177], v[228:231], v[14:17]
	v_mfma_f32_16x16x32_bf16 v[10:13], v[166:169], v[236:239], v[8:11]
	v_mfma_f32_16x16x32_bf16 v[6:9], v[174:177], v[236:239], v[4:7]
	s_setprio 0
	s_barrier
	s_add_u32 s4, s4, 0x100
	s_addc_u32 s5, s5, 0
	s_add_u32 s20, s20, 0x100
	s_addc_u32 s21, s21, 0
	s_cmp_ge_i32 s22, s46
	s_mov_b32 s6, s22
	s_cbranch_scc0 .LBB0_500
	s_add_i32 s14, s27, 0x1c000
	s_mov_b32 s23, 0x18000
	s_mov_b32 s24, 0x1c000
	s_mov_b32 s52, 0x14000

; #define PG8_STAGE(bufoff, gbase, voff) do { _Pragma("unroll") for (int _i = 0; _i < 2; ++_i) \
;         __builtin_amdgcn_global_load_lds((const unsigned*)((const char*)(gbase) + (voff)[_i]), (LAS unsigned*)(lds + (bufoff) + ldsw + _i * 8192), 16, 0, 0); } while (0)
; #define PG8_LDA(dst, b, h) do { _Pragma("unroll") for (int m = 0; m < 4; ++m) _Pragma("unroll") for (int k = 0; k < 2; ++k) dst[m][k] = *(const LAS bf16x8*)(lds + PG8_SA(b, h) + aoff + m * 2048 + k * 1024); } while (0)
; #define PG8_LDB(dst, b, h) do { _Pragma("unroll") for (int n = 0; n < 2; ++n) _Pragma("unroll") for (int k = 0; k < 2; ++k) dst[n][k] = *(const LAS bf16x8*)(lds + PG8_SB(b, h) + boff + n * 2048 + k * 1024); } while (0)
; #define PG8_MMA(ai, bj, At, Bt) do { __builtin_amdgcn_s_setprio(1); _Pragma("unroll") for (int m = 0; m < 4; ++m) _Pragma("unroll") for (int n = 0; n < 2; ++n) _Pragma("unroll") for (int k = 0; k < 2; ++k) \
;         acc[ai][bj][m][n] = __builtin_amdgcn_mfma_f32_16x16x32_bf16(Bt[n][k], At[m][k], acc[ai][bj][m][n], 0, 0, 0); __builtin_amdgcn_s_setprio(0); } while (0)
; #define PG8_WAIT_V(n) asm volatile("s_waitcnt vmcnt(" #n ")" ::: "memory")
; #define PG8_WAIT_L(n) asm volatile("s_waitcnt lgkmcnt(" #n ")" ::: "memory")
; #define PG8_BAR __builtin_amdgcn_s_barrier()
; #define PG8_SCHED __builtin_amdgcn_sched_barrier(0)
; template <class Epi, bool ALIGN_EPI = true>
; __device__ __forceinline__ void gemm_phase(LAS unsigned char* lds, const Gemm g, const Sched& S, const Epi& E) {
;     ...
;             const int rflag = __builtin_amdgcn_readfirstlane(t | (int)(ui == 0));
;             PG8_LDB(B0, 0, 0); PG8_LDB(B1, 0, 1); PG8_SCHED; PG8_LDA(At, 0, 0); PG8_STAGE(PG8_SA(1, 1), a1 + hstepA, voffA);
;             if constexpr (Epi::NSTORES > 0) PG8_WAIT_RELAX(rflag, 8 + Epi::NSTORES); else PG8_WAIT_V(8);
;             PG8_WAIT_L(0); PG8_BAR; PG8_MMA(0, 0, At, B0); PG8_MMA(0, 1, At, B1); PG8_BAR; PG8_SCHED;
;             PG8_LDA(At, 0, 1); PG8_STAGE(PG8_SB(0, 0), b2, voffB); PG8_STAGE(PG8_SB(0, 1), b2 + hstepB, voffB); PG8_STAGE(PG8_SA(0, 0), a2, voffA);
;             if constexpr (Epi::NSTORES > 0) PG8_WAIT_RELAX(rflag, 8 + Epi::NSTORES); else PG8_WAIT_V(8);
;             PG8_WAIT_L(0); PG8_BAR; PG8_MMA(1, 0, At, B0); PG8_MMA(1, 1, At, B1); PG8_BAR; PG8_SCHED;
.LBB0_954:
	s_add_i32 s22, s6, 2
	s_add_u32 s7, s4, 0xfff80080
	s_addc_u32 s14, s5, -1
	s_cmp_eq_u32 s88, s6
	v_add_u32_e32 v182, s6, v2
	s_cselect_b32 s15, s16, s14
	s_cselect_b32 s14, s17, s7
	s_waitcnt lgkmcnt(0)
	s_cselect_b32 s7, s18, s21
	s_cselect_b32 s6, s19, s20
	v_readfirstlane_b32 s59, v182
	s_add_u32 s100, s4, 0xfff80000
	s_addc_u32 s101, s5, -1
	ds_read_b128 v[134:137], v185
	ds_read_b128 v[138:141], v185 offset:1024
	ds_read_b128 v[142:145], v185 offset:2048
	ds_read_b128 v[146:149], v185 offset:3072
	ds_read_b128 v[162:165], v185 offset:16384
	ds_read_b128 v[166:169], v185 offset:17408
	ds_read_b128 v[170:173], v185 offset:18432
	ds_read_b128 v[174:177], v185 offset:19456
	ds_read_b128 v[178:181], v186
	ds_read_b128 v[188:191], v186 offset:1024
	ds_read_b128 v[192:195], v186 offset:2048
	ds_read_b128 v[206:209], v186 offset:3072
	s_mov_b32 m0, s30
	ds_read_b128 v[224:227], v186 offset:4096
	global_load_lds_dwordx4 v158, s[100:101]
	s_mov_b32 m0, s33
	ds_read_b128 v[228:231], v186 offset:5120
	global_load_lds_dwordx4 v160, s[100:101]
	s_add_i32 m0, s48, 0xc000
	ds_read_b128 v[232:235], v186 offset:6144
	global_load_lds_dwordx4 v158, s[4:5]
	s_add_i32 m0, s48, 0xe000
	ds_read_b128 v[236:239], v186 offset:7168
	global_load_lds_dwordx4 v160, s[4:5]
	s_cmp_eq_u32 s59, 0
	s_cbranch_scc1 .Lrw12
	s_waitcnt vmcnt(8)
.Lrw12:
	s_waitcnt vmcnt(24) lgkmcnt(0)
	s_barrier
	s_setprio 1
	v_mfma_f32_16x16x32_bf16 v[130:133], v[134:137], v[178:181], v[130:133]
	v_mfma_f32_16x16x32_bf16 v[126:129], v[142:145], v[178:181], v[126:129]
	v_mfma_f32_16x16x32_bf16 v[122:125], v[134:137], v[192:195], v[122:125]
	v_mfma_f32_16x16x32_bf16 v[118:121], v[142:145], v[192:195], v[118:121]
	v_mfma_f32_16x16x32_bf16 v[114:117], v[134:137], v[224:227], v[114:117]
	v_mfma_f32_16x16x32_bf16 v[110:113], v[142:145], v[224:227], v[110:113]
	v_mfma_f32_16x16x32_bf16 v[106:109], v[134:137], v[232:235], v[106:109]
	v_mfma_f32_16x16x32_bf16 v[102:105], v[142:145], v[232:235], v[102:105]
	v_mfma_f32_16x16x32_bf16 v[130:133], v[138:141], v[188:191], v[130:133]
	v_mfma_f32_16x16x32_bf16 v[126:129], v[146:149], v[188:191], v[126:129]
	v_mfma_f32_16x16x32_bf16 v[122:125], v[138:141], v[206:209], v[122:125]
	v_mfma_f32_16x16x32_bf16 v[118:121], v[146:149], v[206:209], v[118:121]
	v_mfma_f32_16x16x32_bf16 v[114:117], v[138:141], v[228:231], v[114:117]
	v_mfma_f32_16x16x32_bf16 v[110:113], v[146:149], v[228:231], v[110:113]
	v_mfma_f32_16x16x32_bf16 v[106:109], v[138:141], v[236:239], v[106:109]
	v_mfma_f32_16x16x32_bf16 v[102:105], v[146:149], v[236:239], v[102:105]
	s_setprio 0
	s_setprio 1
	v_mfma_f32_16x16x32_bf16 v[98:101], v[162:165], v[178:181], v[98:101]
	v_mfma_f32_16x16x32_bf16 v[94:97], v[170:173], v[178:181], v[94:97]
	v_mfma_f32_16x16x32_bf16 v[90:93], v[162:165], v[192:195], v[90:93]
	v_mfma_f32_16x16x32_bf16 v[86:89], v[170:173], v[192:195], v[86:89]
	v_mfma_f32_16x16x32_bf16 v[82:85], v[162:165], v[224:227], v[82:85]
	v_mfma_f32_16x16x32_bf16 v[78:81], v[170:173], v[224:227], v[78:81]
	v_mfma_f32_16x16x32_bf16 v[74:77], v[162:165], v[232:235], v[74:77]
	v_mfma_f32_16x16x32_bf16 v[70:73], v[170:173], v[232:235], v[70:73]
	v_mfma_f32_16x16x32_bf16 v[98:101], v[166:169], v[188:191], v[98:101]
	v_mfma_f32_16x16x32_bf16 v[94:97], v[174:177], v[188:191], v[94:97]
	v_mfma_f32_16x16x32_bf16 v[90:93], v[166:169], v[206:209], v[90:93]
	v_mfma_f32_16x16x32_bf16 v[86:89], v[174:177], v[206:209], v[86:89]
	v_mfma_f32_16x16x32_bf16 v[82:85], v[166:169], v[228:231], v[82:85]
	v_mfma_f32_16x16x32_bf16 v[78:81], v[174:177], v[228:231], v[78:81]
	v_mfma_f32_16x16x32_bf16 v[74:77], v[166:169], v[236:239], v[74:77]
	v_mfma_f32_16x16x32_bf16 v[70:73], v[174:177], v[236:239], v[70:73]
	s_setprio 0
	s_barrier
	s_add_u32 s24, s6, 0x80000
	s_addc_u32 s25, s7, 0
	ds_read_b128 v[178:181], v186 offset:16384
	ds_read_b128 v[188:191], v186 offset:17408
	ds_read_b128 v[192:195], v186 offset:18432
	ds_read_b128 v[206:209], v186 offset:19456
	s_add_i32 m0, s94, 0x10000
	ds_read_b128 v[224:227], v186 offset:20480
	global_load_lds_dwordx4 v152, s[6:7]
	s_add_i32 m0, s94, 0x12000
	ds_read_b128 v[228:231], v186 offset:21504
	global_load_lds_dwordx4 v156, s[6:7]
	s_add_i32 m0, s94, 0x14000
	ds_read_b128 v[232:235], v186 offset:22528
	global_load_lds_dwordx4 v152, s[24:25]
	s_add_i32 m0, s94, 0x16000
	ds_read_b128 v[236:239], v186 offset:23552
	global_load_lds_dwordx4 v156, s[24:25]
	s_waitcnt vmcnt(6) lgkmcnt(0)
; #define PG8_STAGE(bufoff, gbase, voff) do { _Pragma("unroll") for (int _i = 0; _i < 2; ++_i) \
;         __builtin_amdgcn_global_load_lds((const unsigned*)((const char*)(gbase) + (voff)[_i]), (LAS unsigned*)(lds + (bufoff) + ldsw + _i * 8192), 16, 0, 0); } while (0)
; #define PG8_LDA(dst, b, h) do { _Pragma("unroll") for (int m = 0; m < 4; ++m) _Pragma("unroll") for (int k = 0; k < 2; ++k) dst[m][k] = *(const LAS bf16x8*)(lds + PG8_SA(b, h) + aoff + m * 2048 + k * 1024); } while (0)
; #define PG8_LDB(dst, b, h) do { _Pragma("unroll") for (int n = 0; n < 2; ++n) _Pragma("unroll") for (int k = 0; k < 2; ++k) dst[n][k] = *(const LAS bf16x8*)(lds + PG8_SB(b, h) + boff + n * 2048 + k * 1024); } while (0)
; #define PG8_MMA(ai, bj, At, Bt) do { __builtin_amdgcn_s_setprio(1); _Pragma("unroll") for (int m = 0; m < 4; ++m) _Pragma("unroll") for (int n = 0; n < 2; ++n) _Pragma("unroll") for (int k = 0; k < 2; ++k) \
;         acc[ai][bj][m][n] = __builtin_amdgcn_mfma_f32_16x16x32_bf16(Bt[n][k], At[m][k], acc[ai][bj][m][n], 0, 0, 0); __builtin_amdgcn_s_setprio(0); } while (0)
; #define PG8_WAIT_V(n) asm volatile("s_waitcnt vmcnt(" #n ")" ::: "memory")
; #define PG8_WAIT_L(n) asm volatile("s_waitcnt lgkmcnt(" #n ")" ::: "memory")
; #define PG8_BAR __builtin_amdgcn_s_barrier()
; #define PG8_SCHED __builtin_amdgcn_sched_barrier(0)
; template <class Epi, bool ALIGN_EPI = true>
; __device__ __forceinline__ void gemm_phase(LAS unsigned char* lds, const Gemm g, const Sched& S, const Epi& E) {
;     ...
;             PG8_WAIT_L(0); PG8_BAR; PG8_MMA(1, 0, At, B0); PG8_MMA(1, 1, At, B1); PG8_BAR; PG8_SCHED;
;             PG8_LDB(B0, 1, 0); PG8_LDB(B1, 1, 1); PG8_SCHED; PG8_LDA(At, 1, 0); PG8_STAGE(PG8_SA(0, 1), a2 + hstepA, voffA);
;             PG8_WAIT_V(8); PG8_WAIT_L(0); PG8_BAR; PG8_MMA(0, 0, At, B0); PG8_MMA(0, 1, At, B1); PG8_BAR; PG8_SCHED;
;             PG8_LDA(At, 1, 1); PG8_STAGE(PG8_SB(1, 0), b3, voffB); PG8_STAGE(PG8_SB(1, 1), b3 + hstepB, voffB); PG8_STAGE(PG8_SA(1, 0), a3, voffA);
.Lrw13:
	s_barrier
	s_setprio 1
	v_mfma_f32_16x16x32_bf16 v[66:69], v[134:137], v[178:181], v[66:69]
	v_mfma_f32_16x16x32_bf16 v[62:65], v[142:145], v[178:181], v[62:65]
	v_mfma_f32_16x16x32_bf16 v[58:61], v[134:137], v[192:195], v[58:61]
	v_mfma_f32_16x16x32_bf16 v[54:57], v[142:145], v[192:195], v[54:57]
	v_mfma_f32_16x16x32_bf16 v[50:53], v[134:137], v[224:227], v[50:53]
	v_mfma_f32_16x16x32_bf16 v[46:49], v[142:145], v[224:227], v[46:49]
	v_mfma_f32_16x16x32_bf16 v[42:45], v[134:137], v[232:235], v[42:45]
	v_mfma_f32_16x16x32_bf16 v[38:41], v[142:145], v[232:235], v[38:41]
	v_mfma_f32_16x16x32_bf16 v[66:69], v[138:141], v[188:191], v[66:69]
	v_mfma_f32_16x16x32_bf16 v[62:65], v[146:149], v[188:191], v[62:65]
	v_mfma_f32_16x16x32_bf16 v[58:61], v[138:141], v[206:209], v[58:61]
	v_mfma_f32_16x16x32_bf16 v[54:57], v[146:149], v[206:209], v[54:57]
	v_mfma_f32_16x16x32_bf16 v[50:53], v[138:141], v[228:231], v[50:53]
	v_mfma_f32_16x16x32_bf16 v[46:49], v[146:149], v[228:231], v[46:49]
	v_mfma_f32_16x16x32_bf16 v[42:45], v[138:141], v[236:239], v[42:45]
	v_mfma_f32_16x16x32_bf16 v[38:41], v[146:149], v[236:239], v[38:41]
	s_setprio 0
	s_setprio 1
	v_mfma_f32_16x16x32_bf16 v[34:37], v[162:165], v[178:181], v[34:37]
	v_mfma_f32_16x16x32_bf16 v[30:33], v[170:173], v[178:181], v[30:33]
	v_mfma_f32_16x16x32_bf16 v[26:29], v[162:165], v[192:195], v[26:29]
	v_mfma_f32_16x16x32_bf16 v[22:25], v[170:173], v[192:195], v[22:25]
	v_mfma_f32_16x16x32_bf16 v[18:21], v[162:165], v[224:227], v[18:21]
	v_mfma_f32_16x16x32_bf16 v[14:17], v[170:173], v[224:227], v[14:17]
	v_mfma_f32_16x16x32_bf16 v[10:13], v[162:165], v[232:235], v[10:13]
	v_mfma_f32_16x16x32_bf16 v[4:7], v[170:173], v[232:235], v[6:9]
	v_mfma_f32_16x16x32_bf16 v[34:37], v[166:169], v[188:191], v[34:37]
	v_mfma_f32_16x16x32_bf16 v[30:33], v[174:177], v[188:191], v[30:33]
	v_mfma_f32_16x16x32_bf16 v[26:29], v[166:169], v[206:209], v[26:29]
	v_mfma_f32_16x16x32_bf16 v[22:25], v[174:177], v[206:209], v[22:25]
	v_mfma_f32_16x16x32_bf16 v[18:21], v[166:169], v[228:231], v[18:21]
	v_mfma_f32_16x16x32_bf16 v[14:17], v[174:177], v[228:231], v[14:17]
	v_mfma_f32_16x16x32_bf16 v[10:13], v[166:169], v[236:239], v[10:13]
	v_mfma_f32_16x16x32_bf16 v[4:7], v[174:177], v[236:239], v[4:7]
	s_setprio 0
	s_barrier
	s_mov_b64 s[100:101], s[14:15]
	s_add_u32 s14, s14, 0x80000
	s_addc_u32 s15, s15, 0
	ds_read_b128 v[134:137], v185 offset:32768
	ds_read_b128 v[138:141], v185 offset:33792
	ds_read_b128 v[142:145], v185 offset:34816
	ds_read_b128 v[146:149], v185 offset:35840
	ds_read_b128 v[162:165], v185 offset:49152
	ds_read_b128 v[166:169], v185 offset:50176
	ds_read_b128 v[170:173], v185 offset:51200
	ds_read_b128 v[174:177], v185 offset:52224
	ds_read_b128 v[178:181], v186 offset:32768
	ds_read_b128 v[188:191], v186 offset:33792
	ds_read_b128 v[192:195], v186 offset:34816
	ds_read_b128 v[206:209], v186 offset:35840
	s_mov_b32 m0, s48
	ds_read_b128 v[224:227], v186 offset:36864
	global_load_lds_dwordx4 v150, s[100:101]
	s_mov_b32 m0, s49
	ds_read_b128 v[228:231], v186 offset:37888
	global_load_lds_dwordx4 v154, s[100:101]
	s_mov_b32 m0, s46
	ds_read_b128 v[232:235], v186 offset:38912
	global_load_lds_dwordx4 v150, s[14:15]
	s_mov_b32 m0, s47
	ds_read_b128 v[236:239], v186 offset:39936
	global_load_lds_dwordx4 v154, s[14:15]
	s_waitcnt vmcnt(8) lgkmcnt(0)
	s_barrier
; #define PG8_STAGE(bufoff, gbase, voff) do { _Pragma("unroll") for (int _i = 0; _i < 2; ++_i) \
;         __builtin_amdgcn_global_load_lds((const unsigned*)((const char*)(gbase) + (voff)[_i]), (LAS unsigned*)(lds + (bufoff) + ldsw + _i * 8192), 16, 0, 0); } while (0)
; #define PG8_LDA(dst, b, h) do { _Pragma("unroll") for (int m = 0; m < 4; ++m) _Pragma("unroll") for (int k = 0; k < 2; ++k) dst[m][k] = *(const LAS bf16x8*)(lds + PG8_SA(b, h) + aoff + m * 2048 + k * 1024); } while (0)
; #define PG8_MMA(ai, bj, At, Bt) do { __builtin_amdgcn_s_setprio(1); _Pragma("unroll") for (int m = 0; m < 4; ++m) _Pragma("unroll") for (int n = 0; n < 2; ++n) _Pragma("unroll") for (int k = 0; k < 2; ++k) \
;         acc[ai][bj][m][n] = __builtin_amdgcn_mfma_f32_16x16x32_bf16(Bt[n][k], At[m][k], acc[ai][bj][m][n], 0, 0, 0); __builtin_amdgcn_s_setprio(0); } while (0)
; #define PG8_WAIT_V(n) asm volatile("s_waitcnt vmcnt(" #n ")" ::: "memory")
; #define PG8_WAIT_L(n) asm volatile("s_waitcnt lgkmcnt(" #n ")" ::: "memory")
; #define PG8_BAR __builtin_amdgcn_s_barrier()
; #define PG8_SCHED __builtin_amdgcn_sched_barrier(0)
; template <class Epi, bool ALIGN_EPI = true>
; __device__ __forceinline__ void gemm_phase(LAS unsigned char* lds, const Gemm g, const Sched& S, const Epi& E) {
;     ...
;             PG8_LDA(At, 1, 1); PG8_STAGE(PG8_SB(1, 0), b3, voffB); PG8_STAGE(PG8_SB(1, 1), b3 + hstepB, voffB); PG8_STAGE(PG8_SA(1, 0), a3, voffA);
;             PG8_WAIT_V(8); PG8_WAIT_L(0); PG8_BAR; PG8_MMA(1, 0, At, B0); PG8_MMA(1, 1, At, B1); PG8_BAR; PG8_SCHED;
;         }
	s_setprio 1
	v_mfma_f32_16x16x32_bf16 v[130:133], v[134:137], v[178:181], v[130:133]
	v_mfma_f32_16x16x32_bf16 v[126:129], v[142:145], v[178:181], v[126:129]
	v_mfma_f32_16x16x32_bf16 v[122:125], v[134:137], v[192:195], v[122:125]
	v_mfma_f32_16x16x32_bf16 v[118:121], v[142:145], v[192:195], v[118:121]
	v_mfma_f32_16x16x32_bf16 v[114:117], v[134:137], v[224:227], v[114:117]
	v_mfma_f32_16x16x32_bf16 v[110:113], v[142:145], v[224:227], v[110:113]
	v_mfma_f32_16x16x32_bf16 v[106:109], v[134:137], v[232:235], v[106:109]
	v_mfma_f32_16x16x32_bf16 v[102:105], v[142:145], v[232:235], v[102:105]
	v_mfma_f32_16x16x32_bf16 v[130:133], v[138:141], v[188:191], v[130:133]
	v_mfma_f32_16x16x32_bf16 v[126:129], v[146:149], v[188:191], v[126:129]
	v_mfma_f32_16x16x32_bf16 v[122:125], v[138:141], v[206:209], v[122:125]
	v_mfma_f32_16x16x32_bf16 v[118:121], v[146:149], v[206:209], v[118:121]
	v_mfma_f32_16x16x32_bf16 v[114:117], v[138:141], v[228:231], v[114:117]
	v_mfma_f32_16x16x32_bf16 v[110:113], v[146:149], v[228:231], v[110:113]
	v_mfma_f32_16x16x32_bf16 v[106:109], v[138:141], v[236:239], v[106:109]
	v_mfma_f32_16x16x32_bf16 v[102:105], v[146:149], v[236:239], v[102:105]
	s_setprio 0
	s_setprio 1
	v_mfma_f32_16x16x32_bf16 v[98:101], v[162:165], v[178:181], v[98:101]
	v_mfma_f32_16x16x32_bf16 v[94:97], v[170:173], v[178:181], v[94:97]
	v_mfma_f32_16x16x32_bf16 v[90:93], v[162:165], v[192:195], v[90:93]
	v_mfma_f32_16x16x32_bf16 v[86:89], v[170:173], v[192:195], v[86:89]
	v_mfma_f32_16x16x32_bf16 v[82:85], v[162:165], v[224:227], v[82:85]
	v_mfma_f32_16x16x32_bf16 v[78:81], v[170:173], v[224:227], v[78:81]
	v_mfma_f32_16x16x32_bf16 v[74:77], v[162:165], v[232:235], v[74:77]
	v_mfma_f32_16x16x32_bf16 v[70:73], v[170:173], v[232:235], v[70:73]
	v_mfma_f32_16x16x32_bf16 v[98:101], v[166:169], v[188:191], v[98:101]
	v_mfma_f32_16x16x32_bf16 v[94:97], v[174:177], v[188:191], v[94:97]
	v_mfma_f32_16x16x32_bf16 v[90:93], v[166:169], v[206:209], v[90:93]
	v_mfma_f32_16x16x32_bf16 v[86:89], v[174:177], v[206:209], v[86:89]
	v_mfma_f32_16x16x32_bf16 v[82:85], v[166:169], v[228:231], v[82:85]
	v_mfma_f32_16x16x32_bf16 v[78:81], v[174:177], v[228:231], v[78:81]
	v_mfma_f32_16x16x32_bf16 v[74:77], v[166:169], v[236:239], v[74:77]
	v_mfma_f32_16x16x32_bf16 v[70:73], v[174:177], v[236:239], v[70:73]
	s_setprio 0
	s_barrier
	ds_read_b128 v[178:181], v186 offset:49152
	ds_read_b128 v[188:191], v186 offset:50176
	ds_read_b128 v[192:195], v186 offset:51200
	ds_read_b128 v[206:209], v186 offset:52224
	s_add_i32 m0, s94, 0x17f80
	ds_read_b128 v[224:227], v186 offset:53248
	global_load_lds_dwordx4 v152, s[6:7] offset:128
	s_add_i32 m0, s94, 0x19f80
	ds_read_b128 v[228:231], v186 offset:54272
	global_load_lds_dwordx4 v156, s[6:7] offset:128
	s_add_i32 m0, s94, 0x1c000
	s_add_u32 s6, s6, 0x80080
	s_addc_u32 s7, s7, 0
	ds_read_b128 v[232:235], v186 offset:55296
	global_load_lds_dwordx4 v152, s[6:7]
	s_add_i32 m0, s94, 0x1e000
	ds_read_b128 v[236:239], v186 offset:56320
	global_load_lds_dwordx4 v156, s[6:7]
	s_waitcnt vmcnt(6) lgkmcnt(0)
	s_barrier
	s_setprio 1
	v_mfma_f32_16x16x32_bf16 v[66:69], v[134:137], v[178:181], v[66:69]
	v_mfma_f32_16x16x32_bf16 v[62:65], v[142:145], v[178:181], v[62:65]
	v_mfma_f32_16x16x32_bf16 v[58:61], v[134:137], v[192:195], v[58:61]
	v_mfma_f32_16x16x32_bf16 v[54:57], v[142:145], v[192:195], v[54:57]
	v_mfma_f32_16x16x32_bf16 v[50:53], v[134:137], v[224:227], v[50:53]
	v_mfma_f32_16x16x32_bf16 v[46:49], v[142:145], v[224:227], v[46:49]
	v_mfma_f32_16x16x32_bf16 v[42:45], v[134:137], v[232:235], v[42:45]
	v_mfma_f32_16x16x32_bf16 v[38:41], v[142:145], v[232:235], v[38:41]
	v_mfma_f32_16x16x32_bf16 v[66:69], v[138:141], v[188:191], v[66:69]
	v_mfma_f32_16x16x32_bf16 v[62:65], v[146:149], v[188:191], v[62:65]
	v_mfma_f32_16x16x32_bf16 v[58:61], v[138:141], v[206:209], v[58:61]
	v_mfma_f32_16x16x32_bf16 v[54:57], v[146:149], v[206:209], v[54:57]
	v_mfma_f32_16x16x32_bf16 v[50:53], v[138:141], v[228:231], v[50:53]
	v_mfma_f32_16x16x32_bf16 v[46:49], v[146:149], v[228:231], v[46:49]
	v_mfma_f32_16x16x32_bf16 v[42:45], v[138:141], v[236:239], v[42:45]
	v_mfma_f32_16x16x32_bf16 v[38:41], v[146:149], v[236:239], v[38:41]
	s_setprio 0
	s_setprio 1
	v_mfma_f32_16x16x32_bf16 v[34:37], v[162:165], v[178:181], v[34:37]
	v_mfma_f32_16x16x32_bf16 v[30:33], v[170:173], v[178:181], v[30:33]
	v_mfma_f32_16x16x32_bf16 v[26:29], v[162:165], v[192:195], v[26:29]
	v_mfma_f32_16x16x32_bf16 v[22:25], v[170:173], v[192:195], v[22:25]
	v_mfma_f32_16x16x32_bf16 v[18:21], v[162:165], v[224:227], v[18:21]
	v_mfma_f32_16x16x32_bf16 v[14:17], v[170:173], v[224:227], v[14:17]
	v_mfma_f32_16x16x32_bf16 v[8:11], v[162:165], v[232:235], v[10:13]
	v_mfma_f32_16x16x32_bf16 v[4:7], v[170:173], v[232:235], v[4:7]
	v_mfma_f32_16x16x32_bf16 v[34:37], v[166:169], v[188:191], v[34:37]
	v_mfma_f32_16x16x32_bf16 v[30:33], v[174:177], v[188:191], v[30:33]
	v_mfma_f32_16x16x32_bf16 v[26:29], v[166:169], v[206:209], v[26:29]
	v_mfma_f32_16x16x32_bf16 v[22:25], v[174:177], v[206:209], v[22:25]
	v_mfma_f32_16x16x32_bf16 v[18:21], v[166:169], v[228:231], v[18:21]
	v_mfma_f32_16x16x32_bf16 v[14:17], v[174:177], v[228:231], v[14:17]
	v_mfma_f32_16x16x32_bf16 v[10:13], v[166:169], v[236:239], v[8:11]
	v_mfma_f32_16x16x32_bf16 v[6:9], v[174:177], v[236:239], v[4:7]
	s_setprio 0
	s_barrier
	s_add_u32 s4, s4, 0x100
	s_addc_u32 s5, s5, 0
	s_add_u32 s20, s20, 0x100
	s_addc_u32 s21, s21, 0
	s_cmp_ge_i32 s22, s31
	s_mov_b32 s6, s22
	s_cbranch_scc0 .LBB0_954
	s_add_i32 s14, s94, 0x1c000
	s_mov_b32 s23, 0x18000
	s_mov_b32 s24, 0x1c000
	s_mov_b32 s58, 0x14000

; #define PG8_STAGE(bufoff, gbase, voff) do { _Pragma("unroll") for (int _i = 0; _i < 2; ++_i) \
;         __builtin_amdgcn_global_load_lds((const unsigned*)((const char*)(gbase) + (voff)[_i]), (LAS unsigned*)(lds + (bufoff) + ldsw + _i * 8192), 16, 0, 0); } while (0)
; #define PG8_LDA(dst, b, h) do { _Pragma("unroll") for (int m = 0; m < 4; ++m) _Pragma("unroll") for (int k = 0; k < 2; ++k) dst[m][k] = *(const LAS bf16x8*)(lds + PG8_SA(b, h) + aoff + m * 2048 + k * 1024); } while (0)
; #define PG8_LDB(dst, b, h) do { _Pragma("unroll") for (int n = 0; n < 2; ++n) _Pragma("unroll") for (int k = 0; k < 2; ++k) dst[n][k] = *(const LAS bf16x8*)(lds + PG8_SB(b, h) + boff + n * 2048 + k * 1024); } while (0)
; #define PG8_MMA(ai, bj, At, Bt) do { __builtin_amdgcn_s_setprio(1); _Pragma("unroll") for (int m = 0; m < 4; ++m) _Pragma("unroll") for (int n = 0; n < 2; ++n) _Pragma("unroll") for (int k = 0; k < 2; ++k) \
;         acc[ai][bj][m][n] = __builtin_amdgcn_mfma_f32_16x16x32_bf16(Bt[n][k], At[m][k], acc[ai][bj][m][n], 0, 0, 0); __builtin_amdgcn_s_setprio(0); } while (0)
; #define PG8_WAIT_V(n) asm volatile("s_waitcnt vmcnt(" #n ")" ::: "memory")
; #define PG8_WAIT_L(n) asm volatile("s_waitcnt lgkmcnt(" #n ")" ::: "memory")
; #define PG8_BAR __builtin_amdgcn_s_barrier()
; #define PG8_WAIT_RELAX(flag, n) asm volatile("s_cmp_eq_u32 %0, 0\n\ts_cbranch_scc1 .Lrw%=\n\ts_waitcnt vmcnt(8)\n.Lrw%=:\n\ts_waitcnt vmcnt(%1)" :: "s"(flag), "n"(n) : "scc", "memory")
; #define PG8_SCHED __builtin_amdgcn_sched_barrier(0)
; template <class Epi, bool ALIGN_EPI = true>
; __device__ __forceinline__ void gemm_phase(LAS unsigned char* lds, const Gemm g, const Sched& S, const Epi& E) {
;     ...
;             PG8_LDB(B0, 0, 0); PG8_LDB(B1, 0, 1); PG8_SCHED; PG8_LDA(At, 0, 0); PG8_STAGE(PG8_SA(1, 1), a1 + hstepA, voffA);
;             if constexpr (Epi::NSTORES > 0) PG8_WAIT_RELAX(rflag, 8 + Epi::NSTORES); else PG8_WAIT_V(8);
;             PG8_WAIT_L(0); PG8_BAR; PG8_MMA(0, 0, At, B0); PG8_MMA(0, 1, At, B1); PG8_BAR; PG8_SCHED;
;             PG8_LDA(At, 0, 1); PG8_STAGE(PG8_SB(0, 0), b2, voffB); PG8_STAGE(PG8_SB(0, 1), b2 + hstepB, voffB); PG8_STAGE(PG8_SA(0, 0), a2, voffA);
;             if constexpr (Epi::NSTORES > 0) PG8_WAIT_RELAX(rflag, 8 + Epi::NSTORES); else PG8_WAIT_V(8);
;             PG8_WAIT_L(0); PG8_BAR; PG8_MMA(1, 0, At, B0); PG8_MMA(1, 1, At, B1); PG8_BAR; PG8_SCHED;
.LBB0_1237:
	s_add_i32 s94, s24, 1
	s_lshl_b64 s[92:93], s[94:95], 7
	s_add_i32 s94, s24, 2
	s_lshl_b64 s[26:27], s[94:95], 7
	s_add_u32 s25, s56, s26
	s_addc_u32 s91, s57, s27
	s_add_u32 s96, s54, s26
	s_addc_u32 s97, s55, s27
	s_cmp_eq_u32 s85, s24
	s_cselect_b32 s27, s19, s91
	s_cselect_b32 s26, s87, s25
	s_cselect_b32 s25, s88, s97
	s_cselect_b32 s24, s89, s96
	s_add_u32 s92, s56, s92
	s_addc_u32 s93, s57, s93
	s_add_u32 s92, s92, 0x80000
	s_addc_u32 s93, s93, 0
	s_add_u32 s100, s92, 0xfff80000
	s_addc_u32 s101, s93, -1
	ds_read_b128 v[134:137], v224
	ds_read_b128 v[138:141], v224 offset:1024
	ds_read_b128 v[142:145], v224 offset:2048
	ds_read_b128 v[146:149], v224 offset:3072
	ds_read_b128 v[150:153], v224 offset:16384
	ds_read_b128 v[154:157], v224 offset:17408
	ds_read_b128 v[158:161], v224 offset:18432
	ds_read_b128 v[162:165], v224 offset:19456
	ds_read_b128 v[166:169], v225
	ds_read_b128 v[170:173], v225 offset:1024
	ds_read_b128 v[174:177], v225 offset:2048
	ds_read_b128 v[178:181], v225 offset:3072
	s_mov_b32 m0, s81
	ds_read_b128 v[182:185], v225 offset:4096
	global_load_lds_dwordx4 v208, s[100:101]
	s_mov_b32 m0, s82
	ds_read_b128 v[186:189], v225 offset:5120
	global_load_lds_dwordx4 v196, s[100:101]
	s_add_i32 m0, s36, 0xc000
	ds_read_b128 v[190:193], v225 offset:6144
	global_load_lds_dwordx4 v208, s[92:93]
	s_add_i32 m0, s36, 0xe000
	ds_read_b128 v[226:229], v225 offset:7168
	global_load_lds_dwordx4 v196, s[92:93]
	s_waitcnt vmcnt(8) lgkmcnt(0)
	s_barrier
	s_setprio 1
	v_mfma_f32_16x16x32_bf16 v[130:133], v[134:137], v[166:169], v[130:133]
	v_mfma_f32_16x16x32_bf16 v[126:129], v[142:145], v[166:169], v[126:129]
	v_mfma_f32_16x16x32_bf16 v[114:117], v[134:137], v[174:177], v[114:117]
	v_mfma_f32_16x16x32_bf16 v[110:113], v[142:145], v[174:177], v[110:113]
	v_mfma_f32_16x16x32_bf16 v[98:101], v[134:137], v[182:185], v[98:101]
	v_mfma_f32_16x16x32_bf16 v[94:97], v[142:145], v[182:185], v[94:97]
	v_mfma_f32_16x16x32_bf16 v[82:85], v[134:137], v[190:193], v[82:85]
	v_mfma_f32_16x16x32_bf16 v[78:81], v[142:145], v[190:193], v[78:81]
	v_mfma_f32_16x16x32_bf16 v[130:133], v[138:141], v[170:173], v[130:133]
	v_mfma_f32_16x16x32_bf16 v[126:129], v[146:149], v[170:173], v[126:129]
	v_mfma_f32_16x16x32_bf16 v[114:117], v[138:141], v[178:181], v[114:117]
	v_mfma_f32_16x16x32_bf16 v[110:113], v[146:149], v[178:181], v[110:113]
	v_mfma_f32_16x16x32_bf16 v[98:101], v[138:141], v[186:189], v[98:101]
	v_mfma_f32_16x16x32_bf16 v[94:97], v[146:149], v[186:189], v[94:97]
	v_mfma_f32_16x16x32_bf16 v[82:85], v[138:141], v[226:229], v[82:85]
	v_mfma_f32_16x16x32_bf16 v[78:81], v[146:149], v[226:229], v[78:81]
	s_setprio 0
	s_setprio 1
	v_mfma_f32_16x16x32_bf16 v[122:125], v[150:153], v[166:169], v[122:125]
	v_mfma_f32_16x16x32_bf16 v[118:121], v[158:161], v[166:169], v[118:121]
	v_mfma_f32_16x16x32_bf16 v[106:109], v[150:153], v[174:177], v[106:109]
	v_mfma_f32_16x16x32_bf16 v[102:105], v[158:161], v[174:177], v[102:105]
	v_mfma_f32_16x16x32_bf16 v[90:93], v[150:153], v[182:185], v[90:93]
	v_mfma_f32_16x16x32_bf16 v[86:89], v[158:161], v[182:185], v[86:89]
	v_mfma_f32_16x16x32_bf16 v[74:77], v[150:153], v[190:193], v[74:77]
	v_mfma_f32_16x16x32_bf16 v[70:73], v[158:161], v[190:193], v[70:73]
	v_mfma_f32_16x16x32_bf16 v[122:125], v[154:157], v[170:173], v[122:125]
	v_mfma_f32_16x16x32_bf16 v[118:121], v[162:165], v[170:173], v[118:121]
	v_mfma_f32_16x16x32_bf16 v[106:109], v[154:157], v[178:181], v[106:109]
	v_mfma_f32_16x16x32_bf16 v[102:105], v[162:165], v[178:181], v[102:105]
	v_mfma_f32_16x16x32_bf16 v[90:93], v[154:157], v[186:189], v[90:93]
	v_mfma_f32_16x16x32_bf16 v[86:89], v[162:165], v[186:189], v[86:89]
	v_mfma_f32_16x16x32_bf16 v[74:77], v[154:157], v[226:229], v[74:77]
	v_mfma_f32_16x16x32_bf16 v[70:73], v[162:165], v[226:229], v[70:73]
	s_setprio 0
	s_barrier
	s_add_u32 s92, s24, 0x80000
	s_addc_u32 s93, s25, 0
	ds_read_b128 v[166:169], v225 offset:16384
	ds_read_b128 v[170:173], v225 offset:17408
	ds_read_b128 v[174:177], v225 offset:18432
	ds_read_b128 v[178:181], v225 offset:19456
	s_add_i32 m0, s35, 0x10000
	ds_read_b128 v[182:185], v225 offset:20480
	global_load_lds_dwordx4 v206, s[24:25]
	s_add_i32 m0, s35, 0x12000
	ds_read_b128 v[186:189], v225 offset:21504
	global_load_lds_dwordx4 v194, s[24:25]
	s_add_i32 m0, s35, 0x14000
	ds_read_b128 v[190:193], v225 offset:22528
	global_load_lds_dwordx4 v206, s[92:93]
	s_add_i32 m0, s35, 0x16000
	ds_read_b128 v[226:229], v225 offset:23552
	global_load_lds_dwordx4 v194, s[92:93]
	s_waitcnt vmcnt(6) lgkmcnt(0)
	s_barrier
; #define PG8_STAGE(bufoff, gbase, voff) do { _Pragma("unroll") for (int _i = 0; _i < 2; ++_i) \
;         __builtin_amdgcn_global_load_lds((const unsigned*)((const char*)(gbase) + (voff)[_i]), (LAS unsigned*)(lds + (bufoff) + ldsw + _i * 8192), 16, 0, 0); } while (0)
; #define PG8_LDA(dst, b, h) do { _Pragma("unroll") for (int m = 0; m < 4; ++m) _Pragma("unroll") for (int k = 0; k < 2; ++k) dst[m][k] = *(const LAS bf16x8*)(lds + PG8_SA(b, h) + aoff + m * 2048 + k * 1024); } while (0)
; #define PG8_LDB(dst, b, h) do { _Pragma("unroll") for (int n = 0; n < 2; ++n) _Pragma("unroll") for (int k = 0; k < 2; ++k) dst[n][k] = *(const LAS bf16x8*)(lds + PG8_SB(b, h) + boff + n * 2048 + k * 1024); } while (0)
; #define PG8_MMA(ai, bj, At, Bt) do { __builtin_amdgcn_s_setprio(1); _Pragma("unroll") for (int m = 0; m < 4; ++m) _Pragma("unroll") for (int n = 0; n < 2; ++n) _Pragma("unroll") for (int k = 0; k < 2; ++k) \
;         acc[ai][bj][m][n] = __builtin_amdgcn_mfma_f32_16x16x32_bf16(Bt[n][k], At[m][k], acc[ai][bj][m][n], 0, 0, 0); __builtin_amdgcn_s_setprio(0); } while (0)
; #define PG8_WAIT_V(n) asm volatile("s_waitcnt vmcnt(" #n ")" ::: "memory")
; #define PG8_WAIT_L(n) asm volatile("s_waitcnt lgkmcnt(" #n ")" ::: "memory")
; #define PG8_BAR __builtin_amdgcn_s_barrier()
; #define PG8_SCHED __builtin_amdgcn_sched_barrier(0)
; template <class Epi, bool ALIGN_EPI = true>
; __device__ __forceinline__ void gemm_phase(LAS unsigned char* lds, const Gemm g, const Sched& S, const Epi& E) {
;     ...
;             PG8_WAIT_L(0); PG8_BAR; PG8_MMA(1, 0, At, B0); PG8_MMA(1, 1, At, B1); PG8_BAR; PG8_SCHED;
;             PG8_LDB(B0, 1, 0); PG8_LDB(B1, 1, 1); PG8_SCHED; PG8_LDA(At, 1, 0); PG8_STAGE(PG8_SA(0, 1), a2 + hstepA, voffA);
;             PG8_WAIT_V(8); PG8_WAIT_L(0); PG8_BAR; PG8_MMA(0, 0, At, B0); PG8_MMA(0, 1, At, B1); PG8_BAR; PG8_SCHED;
;             PG8_LDA(At, 1, 1); PG8_STAGE(PG8_SB(1, 0), b3, voffB); PG8_STAGE(PG8_SB(1, 1), b3 + hstepB, voffB); PG8_STAGE(PG8_SA(1, 0), a3, voffA);
	s_setprio 1
	v_mfma_f32_16x16x32_bf16 v[66:69], v[134:137], v[166:169], v[66:69]
	v_mfma_f32_16x16x32_bf16 v[62:65], v[142:145], v[166:169], v[62:65]
	v_mfma_f32_16x16x32_bf16 v[50:53], v[134:137], v[174:177], v[50:53]
	v_mfma_f32_16x16x32_bf16 v[46:49], v[142:145], v[174:177], v[46:49]
	v_mfma_f32_16x16x32_bf16 v[34:37], v[134:137], v[182:185], v[34:37]
	v_mfma_f32_16x16x32_bf16 v[30:33], v[142:145], v[182:185], v[30:33]
	v_mfma_f32_16x16x32_bf16 v[18:21], v[134:137], v[190:193], v[18:21]
	v_mfma_f32_16x16x32_bf16 v[14:17], v[142:145], v[190:193], v[14:17]
	v_mfma_f32_16x16x32_bf16 v[66:69], v[138:141], v[170:173], v[66:69]
	v_mfma_f32_16x16x32_bf16 v[62:65], v[146:149], v[170:173], v[62:65]
	v_mfma_f32_16x16x32_bf16 v[50:53], v[138:141], v[178:181], v[50:53]
	v_mfma_f32_16x16x32_bf16 v[46:49], v[146:149], v[178:181], v[46:49]
	v_mfma_f32_16x16x32_bf16 v[34:37], v[138:141], v[186:189], v[34:37]
	v_mfma_f32_16x16x32_bf16 v[30:33], v[146:149], v[186:189], v[30:33]
	v_mfma_f32_16x16x32_bf16 v[18:21], v[138:141], v[226:229], v[18:21]
	v_mfma_f32_16x16x32_bf16 v[14:17], v[146:149], v[226:229], v[14:17]
	s_setprio 0
	s_setprio 1
	v_mfma_f32_16x16x32_bf16 v[58:61], v[150:153], v[166:169], v[58:61]
	v_mfma_f32_16x16x32_bf16 v[54:57], v[158:161], v[166:169], v[54:57]
	v_mfma_f32_16x16x32_bf16 v[42:45], v[150:153], v[174:177], v[42:45]
	v_mfma_f32_16x16x32_bf16 v[38:41], v[158:161], v[174:177], v[38:41]
	v_mfma_f32_16x16x32_bf16 v[26:29], v[150:153], v[182:185], v[26:29]
	v_mfma_f32_16x16x32_bf16 v[22:25], v[158:161], v[182:185], v[22:25]
	v_mfma_f32_16x16x32_bf16 v[10:13], v[150:153], v[190:193], v[10:13]
	v_mfma_f32_16x16x32_bf16 v[4:7], v[158:161], v[190:193], v[6:9]
	v_mfma_f32_16x16x32_bf16 v[58:61], v[154:157], v[170:173], v[58:61]
	v_mfma_f32_16x16x32_bf16 v[54:57], v[162:165], v[170:173], v[54:57]
	v_mfma_f32_16x16x32_bf16 v[42:45], v[154:157], v[178:181], v[42:45]
	v_mfma_f32_16x16x32_bf16 v[38:41], v[162:165], v[178:181], v[38:41]
	v_mfma_f32_16x16x32_bf16 v[26:29], v[154:157], v[186:189], v[26:29]
	v_mfma_f32_16x16x32_bf16 v[22:25], v[162:165], v[186:189], v[22:25]
	v_mfma_f32_16x16x32_bf16 v[10:13], v[154:157], v[226:229], v[10:13]
	v_mfma_f32_16x16x32_bf16 v[4:7], v[162:165], v[226:229], v[4:7]
	s_setprio 0
	s_barrier
	s_mov_b64 s[100:101], s[26:27]
	s_add_u32 s26, s26, 0x80000
	s_addc_u32 s27, s27, 0
	ds_read_b128 v[134:137], v224 offset:32768
	ds_read_b128 v[138:141], v224 offset:33792
	ds_read_b128 v[142:145], v224 offset:34816
	ds_read_b128 v[146:149], v224 offset:35840
	ds_read_b128 v[150:153], v224 offset:49152
	ds_read_b128 v[154:157], v224 offset:50176
	ds_read_b128 v[158:161], v224 offset:51200
	ds_read_b128 v[162:165], v224 offset:52224
	ds_read_b128 v[166:169], v225 offset:32768
	ds_read_b128 v[170:173], v225 offset:33792
	ds_read_b128 v[174:177], v225 offset:34816
	ds_read_b128 v[178:181], v225 offset:35840
	s_mov_b32 m0, s36
	ds_read_b128 v[182:185], v225 offset:36864
	global_load_lds_dwordx4 v208, s[100:101]
	s_mov_b32 m0, s37
	ds_read_b128 v[186:189], v225 offset:37888
	global_load_lds_dwordx4 v196, s[100:101]
	s_mov_b32 m0, s76
	ds_read_b128 v[190:193], v225 offset:38912
	global_load_lds_dwordx4 v208, s[26:27]
	s_mov_b32 m0, s77
	ds_read_b128 v[226:229], v225 offset:39936
	global_load_lds_dwordx4 v196, s[26:27]
	s_waitcnt vmcnt(8) lgkmcnt(0)
	s_barrier
; #define PG8_STAGE(bufoff, gbase, voff) do { _Pragma("unroll") for (int _i = 0; _i < 2; ++_i) \
;         __builtin_amdgcn_global_load_lds((const unsigned*)((const char*)(gbase) + (voff)[_i]), (LAS unsigned*)(lds + (bufoff) + ldsw + _i * 8192), 16, 0, 0); } while (0)
; #define PG8_LDA(dst, b, h) do { _Pragma("unroll") for (int m = 0; m < 4; ++m) _Pragma("unroll") for (int k = 0; k < 2; ++k) dst[m][k] = *(const LAS bf16x8*)(lds + PG8_SA(b, h) + aoff + m * 2048 + k * 1024); } while (0)
; #define PG8_MMA(ai, bj, At, Bt) do { __builtin_amdgcn_s_setprio(1); _Pragma("unroll") for (int m = 0; m < 4; ++m) _Pragma("unroll") for (int n = 0; n < 2; ++n) _Pragma("unroll") for (int k = 0; k < 2; ++k) \
;         acc[ai][bj][m][n] = __builtin_amdgcn_mfma_f32_16x16x32_bf16(Bt[n][k], At[m][k], acc[ai][bj][m][n], 0, 0, 0); __builtin_amdgcn_s_setprio(0); } while (0)
; #define PG8_WAIT_V(n) asm volatile("s_waitcnt vmcnt(" #n ")" ::: "memory")
; #define PG8_WAIT_L(n) asm volatile("s_waitcnt lgkmcnt(" #n ")" ::: "memory")
; #define PG8_BAR __builtin_amdgcn_s_barrier()
; #define PG8_SCHED __builtin_amdgcn_sched_barrier(0)
; template <class Epi, bool ALIGN_EPI = true>
; __device__ __forceinline__ void gemm_phase(LAS unsigned char* lds, const Gemm g, const Sched& S, const Epi& E) {
;     ...
;             PG8_LDA(At, 1, 1); PG8_STAGE(PG8_SB(1, 0), b3, voffB); PG8_STAGE(PG8_SB(1, 1), b3 + hstepB, voffB); PG8_STAGE(PG8_SA(1, 0), a3, voffA);
;             PG8_WAIT_V(8); PG8_WAIT_L(0); PG8_BAR; PG8_MMA(1, 0, At, B0); PG8_MMA(1, 1, At, B1); PG8_BAR; PG8_SCHED;
;         }
	s_setprio 1
	v_mfma_f32_16x16x32_bf16 v[130:133], v[134:137], v[166:169], v[130:133]
	v_mfma_f32_16x16x32_bf16 v[126:129], v[142:145], v[166:169], v[126:129]
	v_mfma_f32_16x16x32_bf16 v[114:117], v[134:137], v[174:177], v[114:117]
	v_mfma_f32_16x16x32_bf16 v[110:113], v[142:145], v[174:177], v[110:113]
	v_mfma_f32_16x16x32_bf16 v[98:101], v[134:137], v[182:185], v[98:101]
	v_mfma_f32_16x16x32_bf16 v[94:97], v[142:145], v[182:185], v[94:97]
	v_mfma_f32_16x16x32_bf16 v[82:85], v[134:137], v[190:193], v[82:85]
	v_mfma_f32_16x16x32_bf16 v[78:81], v[142:145], v[190:193], v[78:81]
	v_mfma_f32_16x16x32_bf16 v[130:133], v[138:141], v[170:173], v[130:133]
	v_mfma_f32_16x16x32_bf16 v[126:129], v[146:149], v[170:173], v[126:129]
	v_mfma_f32_16x16x32_bf16 v[114:117], v[138:141], v[178:181], v[114:117]
	v_mfma_f32_16x16x32_bf16 v[110:113], v[146:149], v[178:181], v[110:113]
	v_mfma_f32_16x16x32_bf16 v[98:101], v[138:141], v[186:189], v[98:101]
	v_mfma_f32_16x16x32_bf16 v[94:97], v[146:149], v[186:189], v[94:97]
	v_mfma_f32_16x16x32_bf16 v[82:85], v[138:141], v[226:229], v[82:85]
	v_mfma_f32_16x16x32_bf16 v[78:81], v[146:149], v[226:229], v[78:81]
	s_setprio 0
	s_setprio 1
	v_mfma_f32_16x16x32_bf16 v[122:125], v[150:153], v[166:169], v[122:125]
	v_mfma_f32_16x16x32_bf16 v[118:121], v[158:161], v[166:169], v[118:121]
	v_mfma_f32_16x16x32_bf16 v[106:109], v[150:153], v[174:177], v[106:109]
	v_mfma_f32_16x16x32_bf16 v[102:105], v[158:161], v[174:177], v[102:105]
	v_mfma_f32_16x16x32_bf16 v[90:93], v[150:153], v[182:185], v[90:93]
	v_mfma_f32_16x16x32_bf16 v[86:89], v[158:161], v[182:185], v[86:89]
	v_mfma_f32_16x16x32_bf16 v[74:77], v[150:153], v[190:193], v[74:77]
	v_mfma_f32_16x16x32_bf16 v[70:73], v[158:161], v[190:193], v[70:73]
	v_mfma_f32_16x16x32_bf16 v[122:125], v[154:157], v[170:173], v[122:125]
	v_mfma_f32_16x16x32_bf16 v[118:121], v[162:165], v[170:173], v[118:121]
	v_mfma_f32_16x16x32_bf16 v[106:109], v[154:157], v[178:181], v[106:109]
	v_mfma_f32_16x16x32_bf16 v[102:105], v[162:165], v[178:181], v[102:105]
	v_mfma_f32_16x16x32_bf16 v[90:93], v[154:157], v[186:189], v[90:93]
	v_mfma_f32_16x16x32_bf16 v[86:89], v[162:165], v[186:189], v[86:89]
	v_mfma_f32_16x16x32_bf16 v[74:77], v[154:157], v[226:229], v[74:77]
	v_mfma_f32_16x16x32_bf16 v[70:73], v[162:165], v[226:229], v[70:73]
	s_setprio 0
	s_barrier
	ds_read_b128 v[166:169], v225 offset:49152
	ds_read_b128 v[170:173], v225 offset:50176
	ds_read_b128 v[174:177], v225 offset:51200
	ds_read_b128 v[178:181], v225 offset:52224
	s_add_i32 m0, s35, 0x17f80
	ds_read_b128 v[182:185], v225 offset:53248
	global_load_lds_dwordx4 v206, s[24:25] offset:128
	s_add_i32 m0, s35, 0x19f80
	ds_read_b128 v[186:189], v225 offset:54272
	global_load_lds_dwordx4 v194, s[24:25] offset:128
	s_add_i32 m0, s35, 0x1c000
	s_add_u32 s24, s24, 0x80080
	s_addc_u32 s25, s25, 0
	ds_read_b128 v[190:193], v225 offset:55296
	global_load_lds_dwordx4 v206, s[24:25]
	s_add_i32 m0, s35, 0x1e000
	ds_read_b128 v[226:229], v225 offset:56320
	global_load_lds_dwordx4 v194, s[24:25]
	s_waitcnt vmcnt(6) lgkmcnt(0)
	s_barrier
	s_setprio 1
	v_mfma_f32_16x16x32_bf16 v[66:69], v[134:137], v[166:169], v[66:69]
	v_mfma_f32_16x16x32_bf16 v[62:65], v[142:145], v[166:169], v[62:65]
	v_mfma_f32_16x16x32_bf16 v[50:53], v[134:137], v[174:177], v[50:53]
	v_mfma_f32_16x16x32_bf16 v[46:49], v[142:145], v[174:177], v[46:49]
	v_mfma_f32_16x16x32_bf16 v[34:37], v[134:137], v[182:185], v[34:37]
	v_mfma_f32_16x16x32_bf16 v[30:33], v[142:145], v[182:185], v[30:33]
	v_mfma_f32_16x16x32_bf16 v[18:21], v[134:137], v[190:193], v[18:21]
	v_mfma_f32_16x16x32_bf16 v[14:17], v[142:145], v[190:193], v[14:17]
	v_mfma_f32_16x16x32_bf16 v[66:69], v[138:141], v[170:173], v[66:69]
	v_mfma_f32_16x16x32_bf16 v[62:65], v[146:149], v[170:173], v[62:65]
	v_mfma_f32_16x16x32_bf16 v[50:53], v[138:141], v[178:181], v[50:53]
	v_mfma_f32_16x16x32_bf16 v[46:49], v[146:149], v[178:181], v[46:49]
	v_mfma_f32_16x16x32_bf16 v[34:37], v[138:141], v[186:189], v[34:37]
	v_mfma_f32_16x16x32_bf16 v[30:33], v[146:149], v[186:189], v[30:33]
	v_mfma_f32_16x16x32_bf16 v[18:21], v[138:141], v[226:229], v[18:21]
	v_mfma_f32_16x16x32_bf16 v[14:17], v[146:149], v[226:229], v[14:17]
	s_setprio 0
	s_setprio 1
	v_mfma_f32_16x16x32_bf16 v[58:61], v[150:153], v[166:169], v[58:61]
	v_mfma_f32_16x16x32_bf16 v[54:57], v[158:161], v[166:169], v[54:57]
	v_mfma_f32_16x16x32_bf16 v[42:45], v[150:153], v[174:177], v[42:45]
	v_mfma_f32_16x16x32_bf16 v[38:41], v[158:161], v[174:177], v[38:41]
	v_mfma_f32_16x16x32_bf16 v[26:29], v[150:153], v[182:185], v[26:29]
	v_mfma_f32_16x16x32_bf16 v[22:25], v[158:161], v[182:185], v[22:25]
	v_mfma_f32_16x16x32_bf16 v[8:11], v[150:153], v[190:193], v[10:13]
	v_mfma_f32_16x16x32_bf16 v[4:7], v[158:161], v[190:193], v[4:7]
	v_mfma_f32_16x16x32_bf16 v[58:61], v[154:157], v[170:173], v[58:61]
	v_mfma_f32_16x16x32_bf16 v[54:57], v[162:165], v[170:173], v[54:57]
	v_mfma_f32_16x16x32_bf16 v[42:45], v[154:157], v[178:181], v[42:45]
	v_mfma_f32_16x16x32_bf16 v[38:41], v[162:165], v[178:181], v[38:41]
	v_mfma_f32_16x16x32_bf16 v[26:29], v[154:157], v[186:189], v[26:29]
	v_mfma_f32_16x16x32_bf16 v[22:25], v[162:165], v[186:189], v[22:25]
	v_mfma_f32_16x16x32_bf16 v[10:13], v[154:157], v[226:229], v[8:11]
	v_mfma_f32_16x16x32_bf16 v[6:9], v[162:165], v[226:229], v[4:7]
	s_setprio 0
	s_barrier
	s_cmp_ge_i32 s94, s90
	s_mov_b32 s24, s94
	s_cbranch_scc0 .LBB0_1237
	s_add_i32 s26, s35, 0x1c000
	s_mov_b32 s91, 0x18000
	s_mov_b32 s92, 0x1c000
	s_mov_b32 vcc_lo, 0x10000
	s_branch .LBB0_1232

; #define PG8_STAGE(bufoff, gbase, voff) do { _Pragma("unroll") for (int _i = 0; _i < 2; ++_i) \
;         __builtin_amdgcn_global_load_lds((const unsigned*)((const char*)(gbase) + (voff)[_i]), (LAS unsigned*)(lds + (bufoff) + ldsw + _i * 8192), 16, 0, 0); } while (0)
; #define PG8_LDA(dst, b, h) do { _Pragma("unroll") for (int m = 0; m < 4; ++m) _Pragma("unroll") for (int k = 0; k < 2; ++k) dst[m][k] = *(const LAS bf16x8*)(lds + PG8_SA(b, h) + aoff + m * 2048 + k * 1024); } while (0)
; #define PG8_LDB(dst, b, h) do { _Pragma("unroll") for (int n = 0; n < 2; ++n) _Pragma("unroll") for (int k = 0; k < 2; ++k) dst[n][k] = *(const LAS bf16x8*)(lds + PG8_SB(b, h) + boff + n * 2048 + k * 1024); } while (0)
; #define PG8_MMA(ai, bj, At, Bt) do { __builtin_amdgcn_s_setprio(1); _Pragma("unroll") for (int m = 0; m < 4; ++m) _Pragma("unroll") for (int n = 0; n < 2; ++n) _Pragma("unroll") for (int k = 0; k < 2; ++k) \
;         acc[ai][bj][m][n] = __builtin_amdgcn_mfma_f32_16x16x32_bf16(Bt[n][k], At[m][k], acc[ai][bj][m][n], 0, 0, 0); __builtin_amdgcn_s_setprio(0); } while (0)
; #define PG8_WAIT_V(n) asm volatile("s_waitcnt vmcnt(" #n ")" ::: "memory")
; #define PG8_WAIT_L(n) asm volatile("s_waitcnt lgkmcnt(" #n ")" ::: "memory")
; #define PG8_BAR __builtin_amdgcn_s_barrier()
; #define PG8_WAIT_RELAX(flag, n) asm volatile("s_cmp_eq_u32 %0, 0\n\ts_cbranch_scc1 .Lrw%=\n\ts_waitcnt vmcnt(8)\n.Lrw%=:\n\ts_waitcnt vmcnt(%1)" :: "s"(flag), "n"(n) : "scc", "memory")
; #define PG8_SCHED __builtin_amdgcn_sched_barrier(0)
; template <class Epi, bool ALIGN_EPI = true>
; __device__ __forceinline__ void gemm_phase(LAS unsigned char* lds, const Gemm g, const Sched& S, const Epi& E) {
;     ...
;             PG8_LDB(B0, 0, 0); PG8_LDB(B1, 0, 1); PG8_SCHED; PG8_LDA(At, 0, 0); PG8_STAGE(PG8_SA(1, 1), a1 + hstepA, voffA);
;             if constexpr (Epi::NSTORES > 0) PG8_WAIT_RELAX(rflag, 8 + Epi::NSTORES); else PG8_WAIT_V(8);
;             PG8_WAIT_L(0); PG8_BAR; PG8_MMA(0, 0, At, B0); PG8_MMA(0, 1, At, B1); PG8_BAR; PG8_SCHED;
;             PG8_LDA(At, 0, 1); PG8_STAGE(PG8_SB(0, 0), b2, voffB); PG8_STAGE(PG8_SB(0, 1), b2 + hstepB, voffB); PG8_STAGE(PG8_SA(0, 0), a2, voffA);
;             if constexpr (Epi::NSTORES > 0) PG8_WAIT_RELAX(rflag, 8 + Epi::NSTORES); else PG8_WAIT_V(8);
;             PG8_WAIT_L(0); PG8_BAR; PG8_MMA(1, 0, At, B0); PG8_MMA(1, 1, At, B1); PG8_BAR; PG8_SCHED;
.LBB0_1311:
	s_add_i32 s67, s48, 2
	s_add_u32 s49, s46, 0xfff80080
	s_addc_u32 s50, s47, -1
	s_cmp_eq_u32 s59, s48
	s_cselect_b32 s51, s21, s50
	s_cselect_b32 s50, s23, s49
	s_cselect_b32 s49, s63, s66
	s_cselect_b32 s48, s64, s65
	s_add_u32 s100, s46, 0xfff80000
	s_addc_u32 s101, s47, -1
	ds_read_b128 v[150:153], v147
	ds_read_b128 v[154:157], v147 offset:1024
	ds_read_b128 v[158:161], v147 offset:2048
	ds_read_b128 v[162:165], v147 offset:3072
	ds_read_b128 v[166:169], v147 offset:16384
	ds_read_b128 v[170:173], v147 offset:17408
	ds_read_b128 v[174:177], v147 offset:18432
	ds_read_b128 v[178:181], v147 offset:19456
	ds_read_b128 v[182:185], v148
	ds_read_b128 v[186:189], v148 offset:1024
	ds_read_b128 v[190:193], v148 offset:2048
	ds_read_b128 v[194:197], v148 offset:3072
	s_mov_b32 m0, s57
	ds_read_b128 v[206:209], v148 offset:4096
	global_load_lds_dwordx4 v142, s[100:101]
	s_mov_b32 m0, s58
	ds_read_b128 v[224:227], v148 offset:5120
	global_load_lds_dwordx4 v144, s[100:101]
	s_add_i32 m0, s52, 0xc000
	ds_read_b128 v[228:231], v148 offset:6144
	global_load_lds_dwordx4 v142, s[46:47]
	s_add_i32 m0, s52, 0xe000
	ds_read_b128 v[232:235], v148 offset:7168
	global_load_lds_dwordx4 v144, s[46:47]
	s_waitcnt vmcnt(8) lgkmcnt(0)
	s_barrier
	s_setprio 1
	v_mfma_f32_16x16x32_bf16 v[130:133], v[150:153], v[182:185], v[130:133]
	v_mfma_f32_16x16x32_bf16 v[126:129], v[158:161], v[182:185], v[126:129]
	v_mfma_f32_16x16x32_bf16 v[114:117], v[150:153], v[190:193], v[114:117]
	v_mfma_f32_16x16x32_bf16 v[110:113], v[158:161], v[190:193], v[110:113]
	v_mfma_f32_16x16x32_bf16 v[98:101], v[150:153], v[206:209], v[98:101]
	v_mfma_f32_16x16x32_bf16 v[94:97], v[158:161], v[206:209], v[94:97]
	v_mfma_f32_16x16x32_bf16 v[82:85], v[150:153], v[228:231], v[82:85]
	v_mfma_f32_16x16x32_bf16 v[78:81], v[158:161], v[228:231], v[78:81]
	v_mfma_f32_16x16x32_bf16 v[130:133], v[154:157], v[186:189], v[130:133]
	v_mfma_f32_16x16x32_bf16 v[126:129], v[162:165], v[186:189], v[126:129]
	v_mfma_f32_16x16x32_bf16 v[114:117], v[154:157], v[194:197], v[114:117]
	v_mfma_f32_16x16x32_bf16 v[110:113], v[162:165], v[194:197], v[110:113]
	v_mfma_f32_16x16x32_bf16 v[98:101], v[154:157], v[224:227], v[98:101]
	v_mfma_f32_16x16x32_bf16 v[94:97], v[162:165], v[224:227], v[94:97]
	v_mfma_f32_16x16x32_bf16 v[82:85], v[154:157], v[232:235], v[82:85]
	v_mfma_f32_16x16x32_bf16 v[78:81], v[162:165], v[232:235], v[78:81]
	s_setprio 0
	s_setprio 1
	v_mfma_f32_16x16x32_bf16 v[122:125], v[166:169], v[182:185], v[122:125]
	v_mfma_f32_16x16x32_bf16 v[118:121], v[174:177], v[182:185], v[118:121]
	v_mfma_f32_16x16x32_bf16 v[106:109], v[166:169], v[190:193], v[106:109]
	v_mfma_f32_16x16x32_bf16 v[102:105], v[174:177], v[190:193], v[102:105]
	v_mfma_f32_16x16x32_bf16 v[90:93], v[166:169], v[206:209], v[90:93]
	v_mfma_f32_16x16x32_bf16 v[86:89], v[174:177], v[206:209], v[86:89]
	v_mfma_f32_16x16x32_bf16 v[74:77], v[166:169], v[228:231], v[74:77]
	v_mfma_f32_16x16x32_bf16 v[70:73], v[174:177], v[228:231], v[70:73]
	v_mfma_f32_16x16x32_bf16 v[122:125], v[170:173], v[186:189], v[122:125]
	v_mfma_f32_16x16x32_bf16 v[118:121], v[178:181], v[186:189], v[118:121]
	v_mfma_f32_16x16x32_bf16 v[106:109], v[170:173], v[194:197], v[106:109]
	v_mfma_f32_16x16x32_bf16 v[102:105], v[178:181], v[194:197], v[102:105]
	v_mfma_f32_16x16x32_bf16 v[90:93], v[170:173], v[224:227], v[90:93]
	v_mfma_f32_16x16x32_bf16 v[86:89], v[178:181], v[224:227], v[86:89]
	v_mfma_f32_16x16x32_bf16 v[74:77], v[170:173], v[232:235], v[74:77]
	v_mfma_f32_16x16x32_bf16 v[70:73], v[178:181], v[232:235], v[70:73]
	s_setprio 0
	s_barrier
	s_add_u32 s68, s48, 0x80000
	s_addc_u32 s69, s49, 0
	ds_read_b128 v[182:185], v148 offset:16384
	ds_read_b128 v[186:189], v148 offset:17408
	ds_read_b128 v[190:193], v148 offset:18432
	ds_read_b128 v[194:197], v148 offset:19456
	s_add_i32 m0, s37, 0x10000
	ds_read_b128 v[206:209], v148 offset:20480
	global_load_lds_dwordx4 v138, s[48:49]
	s_add_i32 m0, s37, 0x12000
	ds_read_b128 v[224:227], v148 offset:21504
	global_load_lds_dwordx4 v134, s[48:49]
	s_add_i32 m0, s37, 0x14000
	ds_read_b128 v[228:231], v148 offset:22528
	global_load_lds_dwordx4 v138, s[68:69]
	s_add_i32 m0, s37, 0x16000
	ds_read_b128 v[232:235], v148 offset:23552
	global_load_lds_dwordx4 v134, s[68:69]
	s_waitcnt vmcnt(6) lgkmcnt(0)
	s_barrier
	s_setprio 1
	v_mfma_f32_16x16x32_bf16 v[66:69], v[150:153], v[182:185], v[66:69]
	v_mfma_f32_16x16x32_bf16 v[62:65], v[158:161], v[182:185], v[62:65]
	v_mfma_f32_16x16x32_bf16 v[50:53], v[150:153], v[190:193], v[50:53]
	v_mfma_f32_16x16x32_bf16 v[46:49], v[158:161], v[190:193], v[46:49]
	v_mfma_f32_16x16x32_bf16 v[34:37], v[150:153], v[206:209], v[34:37]
	v_mfma_f32_16x16x32_bf16 v[30:33], v[158:161], v[206:209], v[30:33]
	v_mfma_f32_16x16x32_bf16 v[18:21], v[150:153], v[228:231], v[18:21]
	v_mfma_f32_16x16x32_bf16 v[14:17], v[158:161], v[228:231], v[14:17]
	v_mfma_f32_16x16x32_bf16 v[66:69], v[154:157], v[186:189], v[66:69]
	v_mfma_f32_16x16x32_bf16 v[62:65], v[162:165], v[186:189], v[62:65]
	v_mfma_f32_16x16x32_bf16 v[50:53], v[154:157], v[194:197], v[50:53]
	v_mfma_f32_16x16x32_bf16 v[46:49], v[162:165], v[194:197], v[46:49]
	v_mfma_f32_16x16x32_bf16 v[34:37], v[154:157], v[224:227], v[34:37]
	v_mfma_f32_16x16x32_bf16 v[30:33], v[162:165], v[224:227], v[30:33]
	v_mfma_f32_16x16x32_bf16 v[18:21], v[154:157], v[232:235], v[18:21]
	v_mfma_f32_16x16x32_bf16 v[14:17], v[162:165], v[232:235], v[14:17]
	s_setprio 0
	s_setprio 1
	v_mfma_f32_16x16x32_bf16 v[58:61], v[166:169], v[182:185], v[58:61]
	v_mfma_f32_16x16x32_bf16 v[54:57], v[174:177], v[182:185], v[54:57]
	v_mfma_f32_16x16x32_bf16 v[42:45], v[166:169], v[190:193], v[42:45]
	v_mfma_f32_16x16x32_bf16 v[38:41], v[174:177], v[190:193], v[38:41]
	v_mfma_f32_16x16x32_bf16 v[26:29], v[166:169], v[206:209], v[26:29]
	v_mfma_f32_16x16x32_bf16 v[22:25], v[174:177], v[206:209], v[22:25]
	v_mfma_f32_16x16x32_bf16 v[10:13], v[166:169], v[228:231], v[10:13]
	v_mfma_f32_16x16x32_bf16 v[4:7], v[174:177], v[228:231], v[6:9]
	v_mfma_f32_16x16x32_bf16 v[58:61], v[170:173], v[186:189], v[58:61]
	v_mfma_f32_16x16x32_bf16 v[54:57], v[178:181], v[186:189], v[54:57]
	v_mfma_f32_16x16x32_bf16 v[42:45], v[170:173], v[194:197], v[42:45]
	v_mfma_f32_16x16x32_bf16 v[38:41], v[178:181], v[194:197], v[38:41]
	v_mfma_f32_16x16x32_bf16 v[26:29], v[170:173], v[224:227], v[26:29]
	v_mfma_f32_16x16x32_bf16 v[22:25], v[178:181], v[224:227], v[22:25]
	v_mfma_f32_16x16x32_bf16 v[10:13], v[170:173], v[232:235], v[10:13]
	v_mfma_f32_16x16x32_bf16 v[4:7], v[178:181], v[232:235], v[4:7]
	s_setprio 0
	s_barrier
; #define PG8_STAGE(bufoff, gbase, voff) do { _Pragma("unroll") for (int _i = 0; _i < 2; ++_i) \
;         __builtin_amdgcn_global_load_lds((const unsigned*)((const char*)(gbase) + (voff)[_i]), (LAS unsigned*)(lds + (bufoff) + ldsw + _i * 8192), 16, 0, 0); } while (0)
; #define PG8_LDA(dst, b, h) do { _Pragma("unroll") for (int m = 0; m < 4; ++m) _Pragma("unroll") for (int k = 0; k < 2; ++k) dst[m][k] = *(const LAS bf16x8*)(lds + PG8_SA(b, h) + aoff + m * 2048 + k * 1024); } while (0)
; #define PG8_LDB(dst, b, h) do { _Pragma("unroll") for (int n = 0; n < 2; ++n) _Pragma("unroll") for (int k = 0; k < 2; ++k) dst[n][k] = *(const LAS bf16x8*)(lds + PG8_SB(b, h) + boff + n * 2048 + k * 1024); } while (0)
; #define PG8_MMA(ai, bj, At, Bt) do { __builtin_amdgcn_s_setprio(1); _Pragma("unroll") for (int m = 0; m < 4; ++m) _Pragma("unroll") for (int n = 0; n < 2; ++n) _Pragma("unroll") for (int k = 0; k < 2; ++k) \
;         acc[ai][bj][m][n] = __builtin_amdgcn_mfma_f32_16x16x32_bf16(Bt[n][k], At[m][k], acc[ai][bj][m][n], 0, 0, 0); __builtin_amdgcn_s_setprio(0); } while (0)
; #define PG8_WAIT_V(n) asm volatile("s_waitcnt vmcnt(" #n ")" ::: "memory")
; #define PG8_WAIT_L(n) asm volatile("s_waitcnt lgkmcnt(" #n ")" ::: "memory")
; #define PG8_BAR __builtin_amdgcn_s_barrier()
; #define PG8_SCHED __builtin_amdgcn_sched_barrier(0)
; template <class Epi, bool ALIGN_EPI = true>
; __device__ __forceinline__ void gemm_phase(LAS unsigned char* lds, const Gemm g, const Sched& S, const Epi& E) {
;     ...
;         for (int t = t_lo; t < t_hi; t += 2) {
;             const bool last = (t == nt - 2);
;     ...
;             PG8_LDB(B0, 1, 0); PG8_LDB(B1, 1, 1); PG8_SCHED; PG8_LDA(At, 1, 0); PG8_STAGE(PG8_SA(0, 1), a2 + hstepA, voffA);
;             PG8_WAIT_V(8); PG8_WAIT_L(0); PG8_BAR; PG8_MMA(0, 0, At, B0); PG8_MMA(0, 1, At, B1); PG8_BAR; PG8_SCHED;
;             PG8_LDA(At, 1, 1); PG8_STAGE(PG8_SB(1, 0), b3, voffB); PG8_STAGE(PG8_SB(1, 1), b3 + hstepB, voffB); PG8_STAGE(PG8_SA(1, 0), a3, voffA);
;             PG8_WAIT_V(8); PG8_WAIT_L(0); PG8_BAR; PG8_MMA(1, 0, At, B0); PG8_MMA(1, 1, At, B1); PG8_BAR; PG8_SCHED;
	s_mov_b64 s[100:101], s[50:51]
	s_add_u32 s50, s50, 0x80000
	s_addc_u32 s51, s51, 0
	ds_read_b128 v[150:153], v147 offset:32768
	ds_read_b128 v[154:157], v147 offset:33792
	ds_read_b128 v[158:161], v147 offset:34816
	ds_read_b128 v[162:165], v147 offset:35840
	ds_read_b128 v[166:169], v147 offset:49152
	ds_read_b128 v[170:173], v147 offset:50176
	ds_read_b128 v[174:177], v147 offset:51200
	ds_read_b128 v[178:181], v147 offset:52224
	ds_read_b128 v[182:185], v148 offset:32768
	ds_read_b128 v[186:189], v148 offset:33792
	ds_read_b128 v[190:193], v148 offset:34816
	ds_read_b128 v[194:197], v148 offset:35840
	s_mov_b32 m0, s52
	ds_read_b128 v[206:209], v148 offset:36864
	global_load_lds_dwordx4 v140, s[100:101]
	s_mov_b32 m0, s53
	ds_read_b128 v[224:227], v148 offset:37888
	global_load_lds_dwordx4 v136, s[100:101]
	s_mov_b32 m0, s54
	ds_read_b128 v[228:231], v148 offset:38912
	global_load_lds_dwordx4 v140, s[50:51]
	s_mov_b32 m0, s55
	ds_read_b128 v[232:235], v148 offset:39936
	global_load_lds_dwordx4 v136, s[50:51]
	s_waitcnt vmcnt(8) lgkmcnt(0)
	s_barrier
	s_setprio 1
	v_mfma_f32_16x16x32_bf16 v[130:133], v[150:153], v[182:185], v[130:133]
	v_mfma_f32_16x16x32_bf16 v[126:129], v[158:161], v[182:185], v[126:129]
	v_mfma_f32_16x16x32_bf16 v[114:117], v[150:153], v[190:193], v[114:117]
	v_mfma_f32_16x16x32_bf16 v[110:113], v[158:161], v[190:193], v[110:113]
	v_mfma_f32_16x16x32_bf16 v[98:101], v[150:153], v[206:209], v[98:101]
	v_mfma_f32_16x16x32_bf16 v[94:97], v[158:161], v[206:209], v[94:97]
	v_mfma_f32_16x16x32_bf16 v[82:85], v[150:153], v[228:231], v[82:85]
	v_mfma_f32_16x16x32_bf16 v[78:81], v[158:161], v[228:231], v[78:81]
	v_mfma_f32_16x16x32_bf16 v[130:133], v[154:157], v[186:189], v[130:133]
	v_mfma_f32_16x16x32_bf16 v[126:129], v[162:165], v[186:189], v[126:129]
	v_mfma_f32_16x16x32_bf16 v[114:117], v[154:157], v[194:197], v[114:117]
	v_mfma_f32_16x16x32_bf16 v[110:113], v[162:165], v[194:197], v[110:113]
	v_mfma_f32_16x16x32_bf16 v[98:101], v[154:157], v[224:227], v[98:101]
	v_mfma_f32_16x16x32_bf16 v[94:97], v[162:165], v[224:227], v[94:97]
	v_mfma_f32_16x16x32_bf16 v[82:85], v[154:157], v[232:235], v[82:85]
	v_mfma_f32_16x16x32_bf16 v[78:81], v[162:165], v[232:235], v[78:81]
	s_setprio 0
	s_setprio 1
	v_mfma_f32_16x16x32_bf16 v[122:125], v[166:169], v[182:185], v[122:125]
	v_mfma_f32_16x16x32_bf16 v[118:121], v[174:177], v[182:185], v[118:121]
	v_mfma_f32_16x16x32_bf16 v[106:109], v[166:169], v[190:193], v[106:109]
	v_mfma_f32_16x16x32_bf16 v[102:105], v[174:177], v[190:193], v[102:105]
	v_mfma_f32_16x16x32_bf16 v[90:93], v[166:169], v[206:209], v[90:93]
	v_mfma_f32_16x16x32_bf16 v[86:89], v[174:177], v[206:209], v[86:89]
	v_mfma_f32_16x16x32_bf16 v[74:77], v[166:169], v[228:231], v[74:77]
	v_mfma_f32_16x16x32_bf16 v[70:73], v[174:177], v[228:231], v[70:73]
	v_mfma_f32_16x16x32_bf16 v[122:125], v[170:173], v[186:189], v[122:125]
	v_mfma_f32_16x16x32_bf16 v[118:121], v[178:181], v[186:189], v[118:121]
	v_mfma_f32_16x16x32_bf16 v[106:109], v[170:173], v[194:197], v[106:109]
	v_mfma_f32_16x16x32_bf16 v[102:105], v[178:181], v[194:197], v[102:105]
	v_mfma_f32_16x16x32_bf16 v[90:93], v[170:173], v[224:227], v[90:93]
	v_mfma_f32_16x16x32_bf16 v[86:89], v[178:181], v[224:227], v[86:89]
	v_mfma_f32_16x16x32_bf16 v[74:77], v[170:173], v[232:235], v[74:77]
	v_mfma_f32_16x16x32_bf16 v[70:73], v[178:181], v[232:235], v[70:73]
	s_setprio 0
	s_barrier
	ds_read_b128 v[182:185], v148 offset:49152
	ds_read_b128 v[186:189], v148 offset:50176
	ds_read_b128 v[190:193], v148 offset:51200
	ds_read_b128 v[194:197], v148 offset:52224
	s_add_i32 m0, s37, 0x17f80
	ds_read_b128 v[206:209], v148 offset:53248
	global_load_lds_dwordx4 v138, s[48:49] offset:128
	s_add_i32 m0, s37, 0x19f80
	ds_read_b128 v[224:227], v148 offset:54272
	global_load_lds_dwordx4 v134, s[48:49] offset:128
	s_add_i32 m0, s37, 0x1c000
	s_add_u32 s48, s48, 0x80080
	s_addc_u32 s49, s49, 0
	ds_read_b128 v[228:231], v148 offset:55296
	global_load_lds_dwordx4 v138, s[48:49]
	s_add_i32 m0, s37, 0x1e000
	ds_read_b128 v[232:235], v148 offset:56320
	global_load_lds_dwordx4 v134, s[48:49]
	s_waitcnt vmcnt(6) lgkmcnt(0)
	s_barrier
	s_setprio 1
	v_mfma_f32_16x16x32_bf16 v[66:69], v[150:153], v[182:185], v[66:69]
	v_mfma_f32_16x16x32_bf16 v[62:65], v[158:161], v[182:185], v[62:65]
	v_mfma_f32_16x16x32_bf16 v[50:53], v[150:153], v[190:193], v[50:53]
	v_mfma_f32_16x16x32_bf16 v[46:49], v[158:161], v[190:193], v[46:49]
	v_mfma_f32_16x16x32_bf16 v[34:37], v[150:153], v[206:209], v[34:37]
	v_mfma_f32_16x16x32_bf16 v[30:33], v[158:161], v[206:209], v[30:33]
	v_mfma_f32_16x16x32_bf16 v[18:21], v[150:153], v[228:231], v[18:21]
	v_mfma_f32_16x16x32_bf16 v[14:17], v[158:161], v[228:231], v[14:17]
	v_mfma_f32_16x16x32_bf16 v[66:69], v[154:157], v[186:189], v[66:69]
	v_mfma_f32_16x16x32_bf16 v[62:65], v[162:165], v[186:189], v[62:65]
	v_mfma_f32_16x16x32_bf16 v[50:53], v[154:157], v[194:197], v[50:53]
	v_mfma_f32_16x16x32_bf16 v[46:49], v[162:165], v[194:197], v[46:49]
	v_mfma_f32_16x16x32_bf16 v[34:37], v[154:157], v[224:227], v[34:37]
	v_mfma_f32_16x16x32_bf16 v[30:33], v[162:165], v[224:227], v[30:33]
	v_mfma_f32_16x16x32_bf16 v[18:21], v[154:157], v[232:235], v[18:21]
	v_mfma_f32_16x16x32_bf16 v[14:17], v[162:165], v[232:235], v[14:17]
	s_setprio 0
	s_setprio 1
	v_mfma_f32_16x16x32_bf16 v[58:61], v[166:169], v[182:185], v[58:61]
	v_mfma_f32_16x16x32_bf16 v[54:57], v[174:177], v[182:185], v[54:57]
	v_mfma_f32_16x16x32_bf16 v[42:45], v[166:169], v[190:193], v[42:45]
	v_mfma_f32_16x16x32_bf16 v[38:41], v[174:177], v[190:193], v[38:41]
	v_mfma_f32_16x16x32_bf16 v[26:29], v[166:169], v[206:209], v[26:29]
	v_mfma_f32_16x16x32_bf16 v[22:25], v[174:177], v[206:209], v[22:25]
	v_mfma_f32_16x16x32_bf16 v[8:11], v[166:169], v[228:231], v[10:13]
	v_mfma_f32_16x16x32_bf16 v[4:7], v[174:177], v[228:231], v[4:7]
	v_mfma_f32_16x16x32_bf16 v[58:61], v[170:173], v[186:189], v[58:61]
	v_mfma_f32_16x16x32_bf16 v[54:57], v[178:181], v[186:189], v[54:57]
	v_mfma_f32_16x16x32_bf16 v[42:45], v[170:173], v[194:197], v[42:45]
	v_mfma_f32_16x16x32_bf16 v[38:41], v[178:181], v[194:197], v[38:41]
	v_mfma_f32_16x16x32_bf16 v[26:29], v[170:173], v[224:227], v[26:29]
	v_mfma_f32_16x16x32_bf16 v[22:25], v[178:181], v[224:227], v[22:25]
	v_mfma_f32_16x16x32_bf16 v[10:13], v[170:173], v[232:235], v[8:11]
	v_mfma_f32_16x16x32_bf16 v[6:9], v[178:181], v[232:235], v[4:7]
	s_setprio 0
	s_barrier
	s_add_u32 s46, s46, 0x100
	s_addc_u32 s47, s47, 0
	s_add_u32 s65, s65, 0x100
	s_addc_u32 s66, s66, 0
	s_cmp_ge_i32 s67, s56
	s_mov_b32 s48, s67
	s_cbranch_scc0 .LBB0_1311
	s_add_i32 s50, s37, 0x1c000
	s_mov_b32 s68, 0x18000
	s_mov_b32 s69, 0x1c000
	s_add_i32 s70, s37, 0x14000

; #define PG8_STAGE(bufoff, gbase, voff) do { _Pragma("unroll") for (int _i = 0; _i < 2; ++_i) \
;         __builtin_amdgcn_global_load_lds((const unsigned*)((const char*)(gbase) + (voff)[_i]), (LAS unsigned*)(lds + (bufoff) + ldsw + _i * 8192), 16, 0, 0); } while (0)
; #define PG8_LDA(dst, b, h) do { _Pragma("unroll") for (int m = 0; m < 4; ++m) _Pragma("unroll") for (int k = 0; k < 2; ++k) dst[m][k] = *(const LAS bf16x8*)(lds + PG8_SA(b, h) + aoff + m * 2048 + k * 1024); } while (0)
; #define PG8_LDB(dst, b, h) do { _Pragma("unroll") for (int n = 0; n < 2; ++n) _Pragma("unroll") for (int k = 0; k < 2; ++k) dst[n][k] = *(const LAS bf16x8*)(lds + PG8_SB(b, h) + boff + n * 2048 + k * 1024); } while (0)
; #define PG8_MMA(ai, bj, At, Bt) do { __builtin_amdgcn_s_setprio(1); _Pragma("unroll") for (int m = 0; m < 4; ++m) _Pragma("unroll") for (int n = 0; n < 2; ++n) _Pragma("unroll") for (int k = 0; k < 2; ++k) \
;         acc[ai][bj][m][n] = __builtin_amdgcn_mfma_f32_16x16x32_bf16(Bt[n][k], At[m][k], acc[ai][bj][m][n], 0, 0, 0); __builtin_amdgcn_s_setprio(0); } while (0)
; template <class Epi, bool ALIGN_EPI = true>
; __device__ __forceinline__ void gemm_phase(LAS unsigned char* lds, const Gemm g, const Sched& S, const Epi& E) {
;     ...
;         for (int t = t_lo; t < t_hi; t += 2) {
;             const bool last = (t == nt - 2);
;             const char* a1 = cA + (size_t)(t + 1) * kstep;
;             const char* a2 = last ? nA : cA + (size_t)(t + 2) * kstep; const char* b2 = last ? nB : cB + (size_t)(t + 2) * kstep;
;             const char* a3 = a2 + kstep; const char* b3 = b2 + kstep;
;             const int rflag = __builtin_amdgcn_readfirstlane(t | (int)(ui == 0));
;             PG8_LDB(B0, 0, 0); PG8_LDB(B1, 0, 1); PG8_SCHED; PG8_LDA(At, 0, 0); PG8_STAGE(PG8_SA(1, 1), a1 + hstepA, voffA);
;             if constexpr (Epi::NSTORES > 0) PG8_WAIT_RELAX(rflag, 8 + Epi::NSTORES); else PG8_WAIT_V(8);
;             PG8_WAIT_L(0); PG8_BAR; PG8_MMA(0, 0, At, B0); PG8_MMA(0, 1, At, B1); PG8_BAR; PG8_SCHED;
;             PG8_LDA(At, 0, 1); PG8_STAGE(PG8_SB(0, 0), b2, voffB); PG8_STAGE(PG8_SB(0, 1), b2 + hstepB, voffB); PG8_STAGE(PG8_SA(0, 0), a2, voffA);
;             if constexpr (Epi::NSTORES > 0) PG8_WAIT_RELAX(rflag, 8 + Epi::NSTORES); else PG8_WAIT_V(8);
;             PG8_WAIT_L(0); PG8_BAR; PG8_MMA(1, 0, At, B0); PG8_MMA(1, 1, At, B1); PG8_BAR; PG8_SCHED;
.LBB0_1402:
	s_add_i32 s67, s46, 2
	s_add_u32 s47, s44, 0xfff80080
	s_addc_u32 s48, s45, -1
	s_cmp_eq_u32 s59, s46
	s_cselect_b32 s49, s19, s48
	s_cselect_b32 s48, s21, s47
	s_cselect_b32 s47, s63, s66
	s_cselect_b32 s46, s64, s65
	s_add_u32 s100, s44, 0xfff80000
	s_addc_u32 s101, s45, -1
	ds_read_b128 v[150:153], v147
	ds_read_b128 v[154:157], v147 offset:1024
	ds_read_b128 v[158:161], v147 offset:2048
	ds_read_b128 v[162:165], v147 offset:3072
	ds_read_b128 v[166:169], v147 offset:16384
	ds_read_b128 v[170:173], v147 offset:17408
	ds_read_b128 v[174:177], v147 offset:18432
	ds_read_b128 v[178:181], v147 offset:19456
	ds_read_b128 v[182:185], v148
	ds_read_b128 v[186:189], v148 offset:1024
	ds_read_b128 v[190:193], v148 offset:2048
	ds_read_b128 v[194:197], v148 offset:3072
	s_mov_b32 m0, s57
	ds_read_b128 v[206:209], v148 offset:4096
	global_load_lds_dwordx4 v142, s[100:101]
	s_mov_b32 m0, s58
	ds_read_b128 v[224:227], v148 offset:5120
	global_load_lds_dwordx4 v144, s[100:101]
	s_add_i32 m0, s52, 0xc000
	ds_read_b128 v[228:231], v148 offset:6144
	global_load_lds_dwordx4 v142, s[44:45]
	s_add_i32 m0, s52, 0xe000
	ds_read_b128 v[232:235], v148 offset:7168
	global_load_lds_dwordx4 v144, s[44:45]
	s_waitcnt vmcnt(8) lgkmcnt(0)
	s_barrier
	s_setprio 1
	v_mfma_f32_16x16x32_bf16 v[130:133], v[150:153], v[182:185], v[130:133]
	v_mfma_f32_16x16x32_bf16 v[126:129], v[158:161], v[182:185], v[126:129]
	v_mfma_f32_16x16x32_bf16 v[114:117], v[150:153], v[190:193], v[114:117]
	v_mfma_f32_16x16x32_bf16 v[110:113], v[158:161], v[190:193], v[110:113]
	v_mfma_f32_16x16x32_bf16 v[98:101], v[150:153], v[206:209], v[98:101]
	v_mfma_f32_16x16x32_bf16 v[94:97], v[158:161], v[206:209], v[94:97]
	v_mfma_f32_16x16x32_bf16 v[82:85], v[150:153], v[228:231], v[82:85]
	v_mfma_f32_16x16x32_bf16 v[78:81], v[158:161], v[228:231], v[78:81]
	v_mfma_f32_16x16x32_bf16 v[130:133], v[154:157], v[186:189], v[130:133]
	v_mfma_f32_16x16x32_bf16 v[126:129], v[162:165], v[186:189], v[126:129]
	v_mfma_f32_16x16x32_bf16 v[114:117], v[154:157], v[194:197], v[114:117]
	v_mfma_f32_16x16x32_bf16 v[110:113], v[162:165], v[194:197], v[110:113]
	v_mfma_f32_16x16x32_bf16 v[98:101], v[154:157], v[224:227], v[98:101]
	v_mfma_f32_16x16x32_bf16 v[94:97], v[162:165], v[224:227], v[94:97]
	v_mfma_f32_16x16x32_bf16 v[82:85], v[154:157], v[232:235], v[82:85]
	v_mfma_f32_16x16x32_bf16 v[78:81], v[162:165], v[232:235], v[78:81]
	s_setprio 0
	s_setprio 1
	v_mfma_f32_16x16x32_bf16 v[122:125], v[166:169], v[182:185], v[122:125]
	v_mfma_f32_16x16x32_bf16 v[118:121], v[174:177], v[182:185], v[118:121]
	v_mfma_f32_16x16x32_bf16 v[106:109], v[166:169], v[190:193], v[106:109]
	v_mfma_f32_16x16x32_bf16 v[102:105], v[174:177], v[190:193], v[102:105]
	v_mfma_f32_16x16x32_bf16 v[90:93], v[166:169], v[206:209], v[90:93]
	v_mfma_f32_16x16x32_bf16 v[86:89], v[174:177], v[206:209], v[86:89]
	v_mfma_f32_16x16x32_bf16 v[74:77], v[166:169], v[228:231], v[74:77]
	v_mfma_f32_16x16x32_bf16 v[70:73], v[174:177], v[228:231], v[70:73]
	v_mfma_f32_16x16x32_bf16 v[122:125], v[170:173], v[186:189], v[122:125]
	v_mfma_f32_16x16x32_bf16 v[118:121], v[178:181], v[186:189], v[118:121]
	v_mfma_f32_16x16x32_bf16 v[106:109], v[170:173], v[194:197], v[106:109]
	v_mfma_f32_16x16x32_bf16 v[102:105], v[178:181], v[194:197], v[102:105]
	v_mfma_f32_16x16x32_bf16 v[90:93], v[170:173], v[224:227], v[90:93]
	v_mfma_f32_16x16x32_bf16 v[86:89], v[178:181], v[224:227], v[86:89]
	v_mfma_f32_16x16x32_bf16 v[74:77], v[170:173], v[232:235], v[74:77]
	v_mfma_f32_16x16x32_bf16 v[70:73], v[178:181], v[232:235], v[70:73]
	s_setprio 0
	s_barrier
	s_add_u32 s68, s46, 0x80000
	s_addc_u32 s69, s47, 0
	ds_read_b128 v[182:185], v148 offset:16384
	ds_read_b128 v[186:189], v148 offset:17408
	ds_read_b128 v[190:193], v148 offset:18432
	ds_read_b128 v[194:197], v148 offset:19456
	s_add_i32 m0, s51, 0x10000
	ds_read_b128 v[206:209], v148 offset:20480
	global_load_lds_dwordx4 v138, s[46:47]
	s_add_i32 m0, s51, 0x12000
	ds_read_b128 v[224:227], v148 offset:21504
	global_load_lds_dwordx4 v134, s[46:47]
	s_add_i32 m0, s51, 0x14000
	ds_read_b128 v[228:231], v148 offset:22528
	global_load_lds_dwordx4 v138, s[68:69]
	s_add_i32 m0, s51, 0x16000
	ds_read_b128 v[232:235], v148 offset:23552
	global_load_lds_dwordx4 v134, s[68:69]
	s_waitcnt vmcnt(6) lgkmcnt(0)
	s_barrier
	s_setprio 1
	v_mfma_f32_16x16x32_bf16 v[66:69], v[150:153], v[182:185], v[66:69]
	v_mfma_f32_16x16x32_bf16 v[62:65], v[158:161], v[182:185], v[62:65]
	v_mfma_f32_16x16x32_bf16 v[50:53], v[150:153], v[190:193], v[50:53]
	v_mfma_f32_16x16x32_bf16 v[46:49], v[158:161], v[190:193], v[46:49]
	v_mfma_f32_16x16x32_bf16 v[34:37], v[150:153], v[206:209], v[34:37]
	v_mfma_f32_16x16x32_bf16 v[30:33], v[158:161], v[206:209], v[30:33]
	v_mfma_f32_16x16x32_bf16 v[18:21], v[150:153], v[228:231], v[18:21]
	v_mfma_f32_16x16x32_bf16 v[14:17], v[158:161], v[228:231], v[14:17]
	v_mfma_f32_16x16x32_bf16 v[66:69], v[154:157], v[186:189], v[66:69]
	v_mfma_f32_16x16x32_bf16 v[62:65], v[162:165], v[186:189], v[62:65]
	v_mfma_f32_16x16x32_bf16 v[50:53], v[154:157], v[194:197], v[50:53]
	v_mfma_f32_16x16x32_bf16 v[46:49], v[162:165], v[194:197], v[46:49]
	v_mfma_f32_16x16x32_bf16 v[34:37], v[154:157], v[224:227], v[34:37]
	v_mfma_f32_16x16x32_bf16 v[30:33], v[162:165], v[224:227], v[30:33]
	v_mfma_f32_16x16x32_bf16 v[18:21], v[154:157], v[232:235], v[18:21]
	v_mfma_f32_16x16x32_bf16 v[14:17], v[162:165], v[232:235], v[14:17]
	s_setprio 0
	s_setprio 1
	v_mfma_f32_16x16x32_bf16 v[58:61], v[166:169], v[182:185], v[58:61]
	v_mfma_f32_16x16x32_bf16 v[54:57], v[174:177], v[182:185], v[54:57]
	v_mfma_f32_16x16x32_bf16 v[42:45], v[166:169], v[190:193], v[42:45]
	v_mfma_f32_16x16x32_bf16 v[38:41], v[174:177], v[190:193], v[38:41]
	v_mfma_f32_16x16x32_bf16 v[26:29], v[166:169], v[206:209], v[26:29]
	v_mfma_f32_16x16x32_bf16 v[22:25], v[174:177], v[206:209], v[22:25]
	v_mfma_f32_16x16x32_bf16 v[10:13], v[166:169], v[228:231], v[10:13]
	v_mfma_f32_16x16x32_bf16 v[4:7], v[174:177], v[228:231], v[6:9]
	v_mfma_f32_16x16x32_bf16 v[58:61], v[170:173], v[186:189], v[58:61]
	v_mfma_f32_16x16x32_bf16 v[54:57], v[178:181], v[186:189], v[54:57]
	v_mfma_f32_16x16x32_bf16 v[42:45], v[170:173], v[194:197], v[42:45]
	v_mfma_f32_16x16x32_bf16 v[38:41], v[178:181], v[194:197], v[38:41]
	v_mfma_f32_16x16x32_bf16 v[26:29], v[170:173], v[224:227], v[26:29]
	v_mfma_f32_16x16x32_bf16 v[22:25], v[178:181], v[224:227], v[22:25]
	v_mfma_f32_16x16x32_bf16 v[10:13], v[170:173], v[232:235], v[10:13]
	v_mfma_f32_16x16x32_bf16 v[4:7], v[178:181], v[232:235], v[4:7]
	s_setprio 0
	s_barrier
; #define PG8_STAGE(bufoff, gbase, voff) do { _Pragma("unroll") for (int _i = 0; _i < 2; ++_i) \
;         __builtin_amdgcn_global_load_lds((const unsigned*)((const char*)(gbase) + (voff)[_i]), (LAS unsigned*)(lds + (bufoff) + ldsw + _i * 8192), 16, 0, 0); } while (0)
; #define PG8_LDA(dst, b, h) do { _Pragma("unroll") for (int m = 0; m < 4; ++m) _Pragma("unroll") for (int k = 0; k < 2; ++k) dst[m][k] = *(const LAS bf16x8*)(lds + PG8_SA(b, h) + aoff + m * 2048 + k * 1024); } while (0)
; #define PG8_LDB(dst, b, h) do { _Pragma("unroll") for (int n = 0; n < 2; ++n) _Pragma("unroll") for (int k = 0; k < 2; ++k) dst[n][k] = *(const LAS bf16x8*)(lds + PG8_SB(b, h) + boff + n * 2048 + k * 1024); } while (0)
; #define PG8_MMA(ai, bj, At, Bt) do { __builtin_amdgcn_s_setprio(1); _Pragma("unroll") for (int m = 0; m < 4; ++m) _Pragma("unroll") for (int n = 0; n < 2; ++n) _Pragma("unroll") for (int k = 0; k < 2; ++k) \
;         acc[ai][bj][m][n] = __builtin_amdgcn_mfma_f32_16x16x32_bf16(Bt[n][k], At[m][k], acc[ai][bj][m][n], 0, 0, 0); __builtin_amdgcn_s_setprio(0); } while (0)
; #define PG8_WAIT_V(n) asm volatile("s_waitcnt vmcnt(" #n ")" ::: "memory")
; #define PG8_WAIT_L(n) asm volatile("s_waitcnt lgkmcnt(" #n ")" ::: "memory")
; #define PG8_BAR __builtin_amdgcn_s_barrier()
; #define PG8_SCHED __builtin_amdgcn_sched_barrier(0)
; template <class Epi, bool ALIGN_EPI = true>
; __device__ __forceinline__ void gemm_phase(LAS unsigned char* lds, const Gemm g, const Sched& S, const Epi& E) {
;     ...
;         for (int t = t_lo; t < t_hi; t += 2) {
;             const bool last = (t == nt - 2);
;     ...
;             PG8_LDB(B0, 1, 0); PG8_LDB(B1, 1, 1); PG8_SCHED; PG8_LDA(At, 1, 0); PG8_STAGE(PG8_SA(0, 1), a2 + hstepA, voffA);
;             PG8_WAIT_V(8); PG8_WAIT_L(0); PG8_BAR; PG8_MMA(0, 0, At, B0); PG8_MMA(0, 1, At, B1); PG8_BAR; PG8_SCHED;
;             PG8_LDA(At, 1, 1); PG8_STAGE(PG8_SB(1, 0), b3, voffB); PG8_STAGE(PG8_SB(1, 1), b3 + hstepB, voffB); PG8_STAGE(PG8_SA(1, 0), a3, voffA);
;             PG8_WAIT_V(8); PG8_WAIT_L(0); PG8_BAR; PG8_MMA(1, 0, At, B0); PG8_MMA(1, 1, At, B1); PG8_BAR; PG8_SCHED;
	s_mov_b64 s[100:101], s[48:49]
	s_add_u32 s48, s48, 0x80000
	s_addc_u32 s49, s49, 0
	ds_read_b128 v[150:153], v147 offset:32768
	ds_read_b128 v[154:157], v147 offset:33792
	ds_read_b128 v[158:161], v147 offset:34816
	ds_read_b128 v[162:165], v147 offset:35840
	ds_read_b128 v[166:169], v147 offset:49152
	ds_read_b128 v[170:173], v147 offset:50176
	ds_read_b128 v[174:177], v147 offset:51200
	ds_read_b128 v[178:181], v147 offset:52224
	ds_read_b128 v[182:185], v148 offset:32768
	ds_read_b128 v[186:189], v148 offset:33792
	ds_read_b128 v[190:193], v148 offset:34816
	ds_read_b128 v[194:197], v148 offset:35840
	s_mov_b32 m0, s52
	ds_read_b128 v[206:209], v148 offset:36864
	global_load_lds_dwordx4 v140, s[100:101]
	s_mov_b32 m0, s53
	ds_read_b128 v[224:227], v148 offset:37888
	global_load_lds_dwordx4 v136, s[100:101]
	s_mov_b32 m0, s54
	ds_read_b128 v[228:231], v148 offset:38912
	global_load_lds_dwordx4 v140, s[48:49]
	s_mov_b32 m0, s55
	ds_read_b128 v[232:235], v148 offset:39936
	global_load_lds_dwordx4 v136, s[48:49]
	s_waitcnt vmcnt(8) lgkmcnt(0)
	s_barrier
	s_setprio 1
	v_mfma_f32_16x16x32_bf16 v[130:133], v[150:153], v[182:185], v[130:133]
	v_mfma_f32_16x16x32_bf16 v[126:129], v[158:161], v[182:185], v[126:129]
	v_mfma_f32_16x16x32_bf16 v[114:117], v[150:153], v[190:193], v[114:117]
	v_mfma_f32_16x16x32_bf16 v[110:113], v[158:161], v[190:193], v[110:113]
	v_mfma_f32_16x16x32_bf16 v[98:101], v[150:153], v[206:209], v[98:101]
	v_mfma_f32_16x16x32_bf16 v[94:97], v[158:161], v[206:209], v[94:97]
	v_mfma_f32_16x16x32_bf16 v[82:85], v[150:153], v[228:231], v[82:85]
	v_mfma_f32_16x16x32_bf16 v[78:81], v[158:161], v[228:231], v[78:81]
	v_mfma_f32_16x16x32_bf16 v[130:133], v[154:157], v[186:189], v[130:133]
	v_mfma_f32_16x16x32_bf16 v[126:129], v[162:165], v[186:189], v[126:129]
	v_mfma_f32_16x16x32_bf16 v[114:117], v[154:157], v[194:197], v[114:117]
	v_mfma_f32_16x16x32_bf16 v[110:113], v[162:165], v[194:197], v[110:113]
	v_mfma_f32_16x16x32_bf16 v[98:101], v[154:157], v[224:227], v[98:101]
	v_mfma_f32_16x16x32_bf16 v[94:97], v[162:165], v[224:227], v[94:97]
	v_mfma_f32_16x16x32_bf16 v[82:85], v[154:157], v[232:235], v[82:85]
	v_mfma_f32_16x16x32_bf16 v[78:81], v[162:165], v[232:235], v[78:81]
	s_setprio 0
	s_setprio 1
	v_mfma_f32_16x16x32_bf16 v[122:125], v[166:169], v[182:185], v[122:125]
	v_mfma_f32_16x16x32_bf16 v[118:121], v[174:177], v[182:185], v[118:121]
	v_mfma_f32_16x16x32_bf16 v[106:109], v[166:169], v[190:193], v[106:109]
	v_mfma_f32_16x16x32_bf16 v[102:105], v[174:177], v[190:193], v[102:105]
	v_mfma_f32_16x16x32_bf16 v[90:93], v[166:169], v[206:209], v[90:93]
	v_mfma_f32_16x16x32_bf16 v[86:89], v[174:177], v[206:209], v[86:89]
	v_mfma_f32_16x16x32_bf16 v[74:77], v[166:169], v[228:231], v[74:77]
	v_mfma_f32_16x16x32_bf16 v[70:73], v[174:177], v[228:231], v[70:73]
	v_mfma_f32_16x16x32_bf16 v[122:125], v[170:173], v[186:189], v[122:125]
	v_mfma_f32_16x16x32_bf16 v[118:121], v[178:181], v[186:189], v[118:121]
	v_mfma_f32_16x16x32_bf16 v[106:109], v[170:173], v[194:197], v[106:109]
	v_mfma_f32_16x16x32_bf16 v[102:105], v[178:181], v[194:197], v[102:105]
	v_mfma_f32_16x16x32_bf16 v[90:93], v[170:173], v[224:227], v[90:93]
	v_mfma_f32_16x16x32_bf16 v[86:89], v[178:181], v[224:227], v[86:89]
	v_mfma_f32_16x16x32_bf16 v[74:77], v[170:173], v[232:235], v[74:77]
	v_mfma_f32_16x16x32_bf16 v[70:73], v[178:181], v[232:235], v[70:73]
	s_setprio 0
	s_barrier
	ds_read_b128 v[182:185], v148 offset:49152
	ds_read_b128 v[186:189], v148 offset:50176
	ds_read_b128 v[190:193], v148 offset:51200
	ds_read_b128 v[194:197], v148 offset:52224
	s_add_i32 m0, s51, 0x17f80
	ds_read_b128 v[206:209], v148 offset:53248
	global_load_lds_dwordx4 v138, s[46:47] offset:128
	s_add_i32 m0, s51, 0x19f80
	ds_read_b128 v[224:227], v148 offset:54272
	global_load_lds_dwordx4 v134, s[46:47] offset:128
	s_add_i32 m0, s51, 0x1c000
	s_add_u32 s46, s46, 0x80080
	s_addc_u32 s47, s47, 0
	ds_read_b128 v[228:231], v148 offset:55296
	global_load_lds_dwordx4 v138, s[46:47]
	s_add_i32 m0, s51, 0x1e000
	ds_read_b128 v[232:235], v148 offset:56320
	global_load_lds_dwordx4 v134, s[46:47]
	s_waitcnt vmcnt(6) lgkmcnt(0)
	s_barrier
	s_setprio 1
	v_mfma_f32_16x16x32_bf16 v[66:69], v[150:153], v[182:185], v[66:69]
	v_mfma_f32_16x16x32_bf16 v[62:65], v[158:161], v[182:185], v[62:65]
	v_mfma_f32_16x16x32_bf16 v[50:53], v[150:153], v[190:193], v[50:53]
	v_mfma_f32_16x16x32_bf16 v[46:49], v[158:161], v[190:193], v[46:49]
	v_mfma_f32_16x16x32_bf16 v[34:37], v[150:153], v[206:209], v[34:37]
	v_mfma_f32_16x16x32_bf16 v[30:33], v[158:161], v[206:209], v[30:33]
	v_mfma_f32_16x16x32_bf16 v[18:21], v[150:153], v[228:231], v[18:21]
	v_mfma_f32_16x16x32_bf16 v[14:17], v[158:161], v[228:231], v[14:17]
	v_mfma_f32_16x16x32_bf16 v[66:69], v[154:157], v[186:189], v[66:69]
	v_mfma_f32_16x16x32_bf16 v[62:65], v[162:165], v[186:189], v[62:65]
	v_mfma_f32_16x16x32_bf16 v[50:53], v[154:157], v[194:197], v[50:53]
	v_mfma_f32_16x16x32_bf16 v[46:49], v[162:165], v[194:197], v[46:49]
	v_mfma_f32_16x16x32_bf16 v[34:37], v[154:157], v[224:227], v[34:37]
	v_mfma_f32_16x16x32_bf16 v[30:33], v[162:165], v[224:227], v[30:33]
	v_mfma_f32_16x16x32_bf16 v[18:21], v[154:157], v[232:235], v[18:21]
	v_mfma_f32_16x16x32_bf16 v[14:17], v[162:165], v[232:235], v[14:17]
	s_setprio 0
	s_setprio 1
	v_mfma_f32_16x16x32_bf16 v[58:61], v[166:169], v[182:185], v[58:61]
	v_mfma_f32_16x16x32_bf16 v[54:57], v[174:177], v[182:185], v[54:57]
	v_mfma_f32_16x16x32_bf16 v[42:45], v[166:169], v[190:193], v[42:45]
	v_mfma_f32_16x16x32_bf16 v[38:41], v[174:177], v[190:193], v[38:41]
	v_mfma_f32_16x16x32_bf16 v[26:29], v[166:169], v[206:209], v[26:29]
	v_mfma_f32_16x16x32_bf16 v[22:25], v[174:177], v[206:209], v[22:25]
	v_mfma_f32_16x16x32_bf16 v[8:11], v[166:169], v[228:231], v[10:13]
	v_mfma_f32_16x16x32_bf16 v[4:7], v[174:177], v[228:231], v[4:7]
	v_mfma_f32_16x16x32_bf16 v[58:61], v[170:173], v[186:189], v[58:61]
	v_mfma_f32_16x16x32_bf16 v[54:57], v[178:181], v[186:189], v[54:57]
	v_mfma_f32_16x16x32_bf16 v[42:45], v[170:173], v[194:197], v[42:45]
	v_mfma_f32_16x16x32_bf16 v[38:41], v[178:181], v[194:197], v[38:41]
	v_mfma_f32_16x16x32_bf16 v[26:29], v[170:173], v[224:227], v[26:29]
	v_mfma_f32_16x16x32_bf16 v[22:25], v[178:181], v[224:227], v[22:25]
	v_mfma_f32_16x16x32_bf16 v[10:13], v[170:173], v[232:235], v[8:11]
	v_mfma_f32_16x16x32_bf16 v[6:9], v[178:181], v[232:235], v[4:7]
	s_setprio 0
	s_barrier
	s_add_u32 s44, s44, 0x100
	s_addc_u32 s45, s45, 0
	s_add_u32 s65, s65, 0x100
	s_addc_u32 s66, s66, 0
	s_cmp_ge_i32 s67, s56
	s_mov_b32 s46, s67
	s_cbranch_scc0 .LBB0_1402
	s_add_i32 s48, s51, 0x1c000
	s_mov_b32 s68, 0x18000
	s_mov_b32 s69, 0x1c000
	s_add_i32 s70, s51, 0x14000

; #define PG8_STAGE(bufoff, gbase, voff) do { _Pragma("unroll") for (int _i = 0; _i < 2; ++_i) \
;         __builtin_amdgcn_global_load_lds((const unsigned*)((const char*)(gbase) + (voff)[_i]), (LAS unsigned*)(lds + (bufoff) + ldsw + _i * 8192), 16, 0, 0); } while (0)
; #define PG8_LDA(dst, b, h) do { _Pragma("unroll") for (int m = 0; m < 4; ++m) _Pragma("unroll") for (int k = 0; k < 2; ++k) dst[m][k] = *(const LAS bf16x8*)(lds + PG8_SA(b, h) + aoff + m * 2048 + k * 1024); } while (0)
; #define PG8_LDB(dst, b, h) do { _Pragma("unroll") for (int n = 0; n < 2; ++n) _Pragma("unroll") for (int k = 0; k < 2; ++k) dst[n][k] = *(const LAS bf16x8*)(lds + PG8_SB(b, h) + boff + n * 2048 + k * 1024); } while (0)
; #define PG8_MMA(ai, bj, At, Bt) do { __builtin_amdgcn_s_setprio(1); _Pragma("unroll") for (int m = 0; m < 4; ++m) _Pragma("unroll") for (int n = 0; n < 2; ++n) _Pragma("unroll") for (int k = 0; k < 2; ++k) \
;         acc[ai][bj][m][n] = __builtin_amdgcn_mfma_f32_16x16x32_bf16(Bt[n][k], At[m][k], acc[ai][bj][m][n], 0, 0, 0); __builtin_amdgcn_s_setprio(0); } while (0)
; template <class Epi, bool ALIGN_EPI = true>
; __device__ __forceinline__ void gemm_phase(LAS unsigned char* lds, const Gemm g, const Sched& S, const Epi& E) {
;     ...
;         for (int t = t_lo; t < t_hi; t += 2) {
;             const bool last = (t == nt - 2);
;             const char* a1 = cA + (size_t)(t + 1) * kstep;
;             const char* a2 = last ? nA : cA + (size_t)(t + 2) * kstep; const char* b2 = last ? nB : cB + (size_t)(t + 2) * kstep;
;             const char* a3 = a2 + kstep; const char* b3 = b2 + kstep;
;             const int rflag = __builtin_amdgcn_readfirstlane(t | (int)(ui == 0));
;             PG8_LDB(B0, 0, 0); PG8_LDB(B1, 0, 1); PG8_SCHED; PG8_LDA(At, 0, 0); PG8_STAGE(PG8_SA(1, 1), a1 + hstepA, voffA);
;             if constexpr (Epi::NSTORES > 0) PG8_WAIT_RELAX(rflag, 8 + Epi::NSTORES); else PG8_WAIT_V(8);
;             PG8_WAIT_L(0); PG8_BAR; PG8_MMA(0, 0, At, B0); PG8_MMA(0, 1, At, B1); PG8_BAR; PG8_SCHED;
;             PG8_LDA(At, 0, 1); PG8_STAGE(PG8_SB(0, 0), b2, voffB); PG8_STAGE(PG8_SB(0, 1), b2 + hstepB, voffB); PG8_STAGE(PG8_SA(0, 0), a2, voffA);
;             if constexpr (Epi::NSTORES > 0) PG8_WAIT_RELAX(rflag, 8 + Epi::NSTORES); else PG8_WAIT_V(8);
;             PG8_WAIT_L(0); PG8_BAR; PG8_MMA(1, 0, At, B0); PG8_MMA(1, 1, At, B1); PG8_BAR; PG8_SCHED;
.LBB0_1929:
	s_add_i32 s67, s48, 2
	s_add_u32 s49, s46, 0xfffc0080
	s_addc_u32 s50, s47, -1
	s_cmp_eq_u32 s59, s48
	s_cselect_b32 s51, s21, s50
	s_cselect_b32 s50, s23, s49
	s_cselect_b32 s49, s63, s66
	s_cselect_b32 s48, s64, s65
	s_add_u32 s100, s46, 0xfffc0000
	s_addc_u32 s101, s47, -1
	ds_read_b128 v[150:153], v147
	ds_read_b128 v[154:157], v147 offset:1024
	ds_read_b128 v[158:161], v147 offset:2048
	ds_read_b128 v[162:165], v147 offset:3072
	ds_read_b128 v[166:169], v147 offset:16384
	ds_read_b128 v[170:173], v147 offset:17408
	ds_read_b128 v[174:177], v147 offset:18432
	ds_read_b128 v[178:181], v147 offset:19456
	ds_read_b128 v[182:185], v148
	ds_read_b128 v[186:189], v148 offset:1024
	ds_read_b128 v[190:193], v148 offset:2048
	ds_read_b128 v[194:197], v148 offset:3072
	s_mov_b32 m0, s57
	ds_read_b128 v[206:209], v148 offset:4096
	global_load_lds_dwordx4 v142, s[100:101]
	s_mov_b32 m0, s58
	ds_read_b128 v[224:227], v148 offset:5120
	global_load_lds_dwordx4 v144, s[100:101]
	s_add_i32 m0, s52, 0xc000
	ds_read_b128 v[228:231], v148 offset:6144
	global_load_lds_dwordx4 v142, s[46:47]
	s_add_i32 m0, s52, 0xe000
	ds_read_b128 v[232:235], v148 offset:7168
	global_load_lds_dwordx4 v144, s[46:47]
	s_waitcnt vmcnt(8) lgkmcnt(0)
	s_barrier
	s_setprio 1
	v_mfma_f32_16x16x32_bf16 v[130:133], v[150:153], v[182:185], v[130:133]
	v_mfma_f32_16x16x32_bf16 v[126:129], v[158:161], v[182:185], v[126:129]
	v_mfma_f32_16x16x32_bf16 v[114:117], v[150:153], v[190:193], v[114:117]
	v_mfma_f32_16x16x32_bf16 v[110:113], v[158:161], v[190:193], v[110:113]
	v_mfma_f32_16x16x32_bf16 v[98:101], v[150:153], v[206:209], v[98:101]
	v_mfma_f32_16x16x32_bf16 v[94:97], v[158:161], v[206:209], v[94:97]
	v_mfma_f32_16x16x32_bf16 v[82:85], v[150:153], v[228:231], v[82:85]
	v_mfma_f32_16x16x32_bf16 v[78:81], v[158:161], v[228:231], v[78:81]
	v_mfma_f32_16x16x32_bf16 v[130:133], v[154:157], v[186:189], v[130:133]
	v_mfma_f32_16x16x32_bf16 v[126:129], v[162:165], v[186:189], v[126:129]
	v_mfma_f32_16x16x32_bf16 v[114:117], v[154:157], v[194:197], v[114:117]
	v_mfma_f32_16x16x32_bf16 v[110:113], v[162:165], v[194:197], v[110:113]
	v_mfma_f32_16x16x32_bf16 v[98:101], v[154:157], v[224:227], v[98:101]
	v_mfma_f32_16x16x32_bf16 v[94:97], v[162:165], v[224:227], v[94:97]
	v_mfma_f32_16x16x32_bf16 v[82:85], v[154:157], v[232:235], v[82:85]
	v_mfma_f32_16x16x32_bf16 v[78:81], v[162:165], v[232:235], v[78:81]
	s_setprio 0
	s_setprio 1
	v_mfma_f32_16x16x32_bf16 v[122:125], v[166:169], v[182:185], v[122:125]
	v_mfma_f32_16x16x32_bf16 v[118:121], v[174:177], v[182:185], v[118:121]
	v_mfma_f32_16x16x32_bf16 v[106:109], v[166:169], v[190:193], v[106:109]
	v_mfma_f32_16x16x32_bf16 v[102:105], v[174:177], v[190:193], v[102:105]
	v_mfma_f32_16x16x32_bf16 v[90:93], v[166:169], v[206:209], v[90:93]
	v_mfma_f32_16x16x32_bf16 v[86:89], v[174:177], v[206:209], v[86:89]
	v_mfma_f32_16x16x32_bf16 v[74:77], v[166:169], v[228:231], v[74:77]
	v_mfma_f32_16x16x32_bf16 v[70:73], v[174:177], v[228:231], v[70:73]
	v_mfma_f32_16x16x32_bf16 v[122:125], v[170:173], v[186:189], v[122:125]
	v_mfma_f32_16x16x32_bf16 v[118:121], v[178:181], v[186:189], v[118:121]
	v_mfma_f32_16x16x32_bf16 v[106:109], v[170:173], v[194:197], v[106:109]
	v_mfma_f32_16x16x32_bf16 v[102:105], v[178:181], v[194:197], v[102:105]
	v_mfma_f32_16x16x32_bf16 v[90:93], v[170:173], v[224:227], v[90:93]
	v_mfma_f32_16x16x32_bf16 v[86:89], v[178:181], v[224:227], v[86:89]
	v_mfma_f32_16x16x32_bf16 v[74:77], v[170:173], v[232:235], v[74:77]
	v_mfma_f32_16x16x32_bf16 v[70:73], v[178:181], v[232:235], v[70:73]
	s_setprio 0
	s_barrier
	s_add_u32 s68, s48, 0x40000
	s_addc_u32 s69, s49, 0
	ds_read_b128 v[182:185], v148 offset:16384
	ds_read_b128 v[186:189], v148 offset:17408
	ds_read_b128 v[190:193], v148 offset:18432
	ds_read_b128 v[194:197], v148 offset:19456
	s_add_i32 m0, s37, 0x10000
	ds_read_b128 v[206:209], v148 offset:20480
	global_load_lds_dwordx4 v138, s[48:49]
	s_add_i32 m0, s37, 0x12000
	ds_read_b128 v[224:227], v148 offset:21504
	global_load_lds_dwordx4 v134, s[48:49]
	s_add_i32 m0, s37, 0x14000
	ds_read_b128 v[228:231], v148 offset:22528
	global_load_lds_dwordx4 v138, s[68:69]
	s_add_i32 m0, s37, 0x16000
	ds_read_b128 v[232:235], v148 offset:23552
	global_load_lds_dwordx4 v134, s[68:69]
	s_waitcnt vmcnt(6) lgkmcnt(0)
	s_barrier
	s_setprio 1
	v_mfma_f32_16x16x32_bf16 v[66:69], v[150:153], v[182:185], v[66:69]
	v_mfma_f32_16x16x32_bf16 v[62:65], v[158:161], v[182:185], v[62:65]
	v_mfma_f32_16x16x32_bf16 v[50:53], v[150:153], v[190:193], v[50:53]
	v_mfma_f32_16x16x32_bf16 v[46:49], v[158:161], v[190:193], v[46:49]
	v_mfma_f32_16x16x32_bf16 v[34:37], v[150:153], v[206:209], v[34:37]
	v_mfma_f32_16x16x32_bf16 v[30:33], v[158:161], v[206:209], v[30:33]
	v_mfma_f32_16x16x32_bf16 v[18:21], v[150:153], v[228:231], v[18:21]
	v_mfma_f32_16x16x32_bf16 v[14:17], v[158:161], v[228:231], v[14:17]
	v_mfma_f32_16x16x32_bf16 v[66:69], v[154:157], v[186:189], v[66:69]
	v_mfma_f32_16x16x32_bf16 v[62:65], v[162:165], v[186:189], v[62:65]
	v_mfma_f32_16x16x32_bf16 v[50:53], v[154:157], v[194:197], v[50:53]
	v_mfma_f32_16x16x32_bf16 v[46:49], v[162:165], v[194:197], v[46:49]
	v_mfma_f32_16x16x32_bf16 v[34:37], v[154:157], v[224:227], v[34:37]
	v_mfma_f32_16x16x32_bf16 v[30:33], v[162:165], v[224:227], v[30:33]
	v_mfma_f32_16x16x32_bf16 v[18:21], v[154:157], v[232:235], v[18:21]
	v_mfma_f32_16x16x32_bf16 v[14:17], v[162:165], v[232:235], v[14:17]
	s_setprio 0
	s_setprio 1
	v_mfma_f32_16x16x32_bf16 v[58:61], v[166:169], v[182:185], v[58:61]
	v_mfma_f32_16x16x32_bf16 v[54:57], v[174:177], v[182:185], v[54:57]
	v_mfma_f32_16x16x32_bf16 v[42:45], v[166:169], v[190:193], v[42:45]
	v_mfma_f32_16x16x32_bf16 v[38:41], v[174:177], v[190:193], v[38:41]
	v_mfma_f32_16x16x32_bf16 v[26:29], v[166:169], v[206:209], v[26:29]
	v_mfma_f32_16x16x32_bf16 v[22:25], v[174:177], v[206:209], v[22:25]
	v_mfma_f32_16x16x32_bf16 v[10:13], v[166:169], v[228:231], v[10:13]
	v_mfma_f32_16x16x32_bf16 v[4:7], v[174:177], v[228:231], v[6:9]
	v_mfma_f32_16x16x32_bf16 v[58:61], v[170:173], v[186:189], v[58:61]
	v_mfma_f32_16x16x32_bf16 v[54:57], v[178:181], v[186:189], v[54:57]
	v_mfma_f32_16x16x32_bf16 v[42:45], v[170:173], v[194:197], v[42:45]
	v_mfma_f32_16x16x32_bf16 v[38:41], v[178:181], v[194:197], v[38:41]
	v_mfma_f32_16x16x32_bf16 v[26:29], v[170:173], v[224:227], v[26:29]
	v_mfma_f32_16x16x32_bf16 v[22:25], v[178:181], v[224:227], v[22:25]
	v_mfma_f32_16x16x32_bf16 v[10:13], v[170:173], v[232:235], v[10:13]
	v_mfma_f32_16x16x32_bf16 v[4:7], v[178:181], v[232:235], v[4:7]
	s_setprio 0
	s_barrier
; #define PG8_STAGE(bufoff, gbase, voff) do { _Pragma("unroll") for (int _i = 0; _i < 2; ++_i) \
;         __builtin_amdgcn_global_load_lds((const unsigned*)((const char*)(gbase) + (voff)[_i]), (LAS unsigned*)(lds + (bufoff) + ldsw + _i * 8192), 16, 0, 0); } while (0)
; #define PG8_LDA(dst, b, h) do { _Pragma("unroll") for (int m = 0; m < 4; ++m) _Pragma("unroll") for (int k = 0; k < 2; ++k) dst[m][k] = *(const LAS bf16x8*)(lds + PG8_SA(b, h) + aoff + m * 2048 + k * 1024); } while (0)
; #define PG8_LDB(dst, b, h) do { _Pragma("unroll") for (int n = 0; n < 2; ++n) _Pragma("unroll") for (int k = 0; k < 2; ++k) dst[n][k] = *(const LAS bf16x8*)(lds + PG8_SB(b, h) + boff + n * 2048 + k * 1024); } while (0)
; #define PG8_MMA(ai, bj, At, Bt) do { __builtin_amdgcn_s_setprio(1); _Pragma("unroll") for (int m = 0; m < 4; ++m) _Pragma("unroll") for (int n = 0; n < 2; ++n) _Pragma("unroll") for (int k = 0; k < 2; ++k) \
;         acc[ai][bj][m][n] = __builtin_amdgcn_mfma_f32_16x16x32_bf16(Bt[n][k], At[m][k], acc[ai][bj][m][n], 0, 0, 0); __builtin_amdgcn_s_setprio(0); } while (0)
; #define PG8_WAIT_V(n) asm volatile("s_waitcnt vmcnt(" #n ")" ::: "memory")
; #define PG8_WAIT_L(n) asm volatile("s_waitcnt lgkmcnt(" #n ")" ::: "memory")
; #define PG8_BAR __builtin_amdgcn_s_barrier()
; #define PG8_SCHED __builtin_amdgcn_sched_barrier(0)
; template <class Epi, bool ALIGN_EPI = true>
; __device__ __forceinline__ void gemm_phase(LAS unsigned char* lds, const Gemm g, const Sched& S, const Epi& E) {
;     ...
;         for (int t = t_lo; t < t_hi; t += 2) {
;             const bool last = (t == nt - 2);
;     ...
;             PG8_LDB(B0, 1, 0); PG8_LDB(B1, 1, 1); PG8_SCHED; PG8_LDA(At, 1, 0); PG8_STAGE(PG8_SA(0, 1), a2 + hstepA, voffA);
;             PG8_WAIT_V(8); PG8_WAIT_L(0); PG8_BAR; PG8_MMA(0, 0, At, B0); PG8_MMA(0, 1, At, B1); PG8_BAR; PG8_SCHED;
;             PG8_LDA(At, 1, 1); PG8_STAGE(PG8_SB(1, 0), b3, voffB); PG8_STAGE(PG8_SB(1, 1), b3 + hstepB, voffB); PG8_STAGE(PG8_SA(1, 0), a3, voffA);
;             PG8_WAIT_V(8); PG8_WAIT_L(0); PG8_BAR; PG8_MMA(1, 0, At, B0); PG8_MMA(1, 1, At, B1); PG8_BAR; PG8_SCHED;
	s_mov_b64 s[100:101], s[50:51]
	s_add_u32 s50, s50, 0x40000
	s_addc_u32 s51, s51, 0
	ds_read_b128 v[150:153], v147 offset:32768
	ds_read_b128 v[154:157], v147 offset:33792
	ds_read_b128 v[158:161], v147 offset:34816
	ds_read_b128 v[162:165], v147 offset:35840
	ds_read_b128 v[166:169], v147 offset:49152
	ds_read_b128 v[170:173], v147 offset:50176
	ds_read_b128 v[174:177], v147 offset:51200
	ds_read_b128 v[178:181], v147 offset:52224
	ds_read_b128 v[182:185], v148 offset:32768
	ds_read_b128 v[186:189], v148 offset:33792
	ds_read_b128 v[190:193], v148 offset:34816
	ds_read_b128 v[194:197], v148 offset:35840
	s_mov_b32 m0, s52
	ds_read_b128 v[206:209], v148 offset:36864
	global_load_lds_dwordx4 v140, s[100:101]
	s_mov_b32 m0, s53
	ds_read_b128 v[224:227], v148 offset:37888
	global_load_lds_dwordx4 v136, s[100:101]
	s_mov_b32 m0, s54
	ds_read_b128 v[228:231], v148 offset:38912
	global_load_lds_dwordx4 v140, s[50:51]
	s_mov_b32 m0, s55
	ds_read_b128 v[232:235], v148 offset:39936
	global_load_lds_dwordx4 v136, s[50:51]
	s_waitcnt vmcnt(8) lgkmcnt(0)
	s_barrier
	s_setprio 1
	v_mfma_f32_16x16x32_bf16 v[130:133], v[150:153], v[182:185], v[130:133]
	v_mfma_f32_16x16x32_bf16 v[126:129], v[158:161], v[182:185], v[126:129]
	v_mfma_f32_16x16x32_bf16 v[114:117], v[150:153], v[190:193], v[114:117]
	v_mfma_f32_16x16x32_bf16 v[110:113], v[158:161], v[190:193], v[110:113]
	v_mfma_f32_16x16x32_bf16 v[98:101], v[150:153], v[206:209], v[98:101]
	v_mfma_f32_16x16x32_bf16 v[94:97], v[158:161], v[206:209], v[94:97]
	v_mfma_f32_16x16x32_bf16 v[82:85], v[150:153], v[228:231], v[82:85]
	v_mfma_f32_16x16x32_bf16 v[78:81], v[158:161], v[228:231], v[78:81]
	v_mfma_f32_16x16x32_bf16 v[130:133], v[154:157], v[186:189], v[130:133]
	v_mfma_f32_16x16x32_bf16 v[126:129], v[162:165], v[186:189], v[126:129]
	v_mfma_f32_16x16x32_bf16 v[114:117], v[154:157], v[194:197], v[114:117]
	v_mfma_f32_16x16x32_bf16 v[110:113], v[162:165], v[194:197], v[110:113]
	v_mfma_f32_16x16x32_bf16 v[98:101], v[154:157], v[224:227], v[98:101]
	v_mfma_f32_16x16x32_bf16 v[94:97], v[162:165], v[224:227], v[94:97]
	v_mfma_f32_16x16x32_bf16 v[82:85], v[154:157], v[232:235], v[82:85]
	v_mfma_f32_16x16x32_bf16 v[78:81], v[162:165], v[232:235], v[78:81]
	s_setprio 0
	s_setprio 1
	v_mfma_f32_16x16x32_bf16 v[122:125], v[166:169], v[182:185], v[122:125]
	v_mfma_f32_16x16x32_bf16 v[118:121], v[174:177], v[182:185], v[118:121]
	v_mfma_f32_16x16x32_bf16 v[106:109], v[166:169], v[190:193], v[106:109]
	v_mfma_f32_16x16x32_bf16 v[102:105], v[174:177], v[190:193], v[102:105]
	v_mfma_f32_16x16x32_bf16 v[90:93], v[166:169], v[206:209], v[90:93]
	v_mfma_f32_16x16x32_bf16 v[86:89], v[174:177], v[206:209], v[86:89]
	v_mfma_f32_16x16x32_bf16 v[74:77], v[166:169], v[228:231], v[74:77]
	v_mfma_f32_16x16x32_bf16 v[70:73], v[174:177], v[228:231], v[70:73]
	v_mfma_f32_16x16x32_bf16 v[122:125], v[170:173], v[186:189], v[122:125]
	v_mfma_f32_16x16x32_bf16 v[118:121], v[178:181], v[186:189], v[118:121]
	v_mfma_f32_16x16x32_bf16 v[106:109], v[170:173], v[194:197], v[106:109]
	v_mfma_f32_16x16x32_bf16 v[102:105], v[178:181], v[194:197], v[102:105]
	v_mfma_f32_16x16x32_bf16 v[90:93], v[170:173], v[224:227], v[90:93]
	v_mfma_f32_16x16x32_bf16 v[86:89], v[178:181], v[224:227], v[86:89]
	v_mfma_f32_16x16x32_bf16 v[74:77], v[170:173], v[232:235], v[74:77]
	v_mfma_f32_16x16x32_bf16 v[70:73], v[178:181], v[232:235], v[70:73]
	s_setprio 0
	s_barrier
	ds_read_b128 v[182:185], v148 offset:49152
	ds_read_b128 v[186:189], v148 offset:50176
	ds_read_b128 v[190:193], v148 offset:51200
	ds_read_b128 v[194:197], v148 offset:52224
	s_add_i32 m0, s37, 0x17f80
	ds_read_b128 v[206:209], v148 offset:53248
	global_load_lds_dwordx4 v138, s[48:49] offset:128
	s_add_i32 m0, s37, 0x19f80
	ds_read_b128 v[224:227], v148 offset:54272
	global_load_lds_dwordx4 v134, s[48:49] offset:128
	s_add_i32 m0, s37, 0x1c000
	s_add_u32 s48, s48, 0x40080
	s_addc_u32 s49, s49, 0
	ds_read_b128 v[228:231], v148 offset:55296
	global_load_lds_dwordx4 v138, s[48:49]
	s_add_i32 m0, s37, 0x1e000
	ds_read_b128 v[232:235], v148 offset:56320
	global_load_lds_dwordx4 v134, s[48:49]
	s_waitcnt vmcnt(6) lgkmcnt(0)
	s_barrier
	s_setprio 1
	v_mfma_f32_16x16x32_bf16 v[66:69], v[150:153], v[182:185], v[66:69]
	v_mfma_f32_16x16x32_bf16 v[62:65], v[158:161], v[182:185], v[62:65]
	v_mfma_f32_16x16x32_bf16 v[50:53], v[150:153], v[190:193], v[50:53]
	v_mfma_f32_16x16x32_bf16 v[46:49], v[158:161], v[190:193], v[46:49]
	v_mfma_f32_16x16x32_bf16 v[34:37], v[150:153], v[206:209], v[34:37]
	v_mfma_f32_16x16x32_bf16 v[30:33], v[158:161], v[206:209], v[30:33]
	v_mfma_f32_16x16x32_bf16 v[18:21], v[150:153], v[228:231], v[18:21]
	v_mfma_f32_16x16x32_bf16 v[14:17], v[158:161], v[228:231], v[14:17]
	v_mfma_f32_16x16x32_bf16 v[66:69], v[154:157], v[186:189], v[66:69]
	v_mfma_f32_16x16x32_bf16 v[62:65], v[162:165], v[186:189], v[62:65]
	v_mfma_f32_16x16x32_bf16 v[50:53], v[154:157], v[194:197], v[50:53]
	v_mfma_f32_16x16x32_bf16 v[46:49], v[162:165], v[194:197], v[46:49]
	v_mfma_f32_16x16x32_bf16 v[34:37], v[154:157], v[224:227], v[34:37]
	v_mfma_f32_16x16x32_bf16 v[30:33], v[162:165], v[224:227], v[30:33]
	v_mfma_f32_16x16x32_bf16 v[18:21], v[154:157], v[232:235], v[18:21]
	v_mfma_f32_16x16x32_bf16 v[14:17], v[162:165], v[232:235], v[14:17]
	s_setprio 0
	s_setprio 1
	v_mfma_f32_16x16x32_bf16 v[58:61], v[166:169], v[182:185], v[58:61]
	v_mfma_f32_16x16x32_bf16 v[54:57], v[174:177], v[182:185], v[54:57]
	v_mfma_f32_16x16x32_bf16 v[42:45], v[166:169], v[190:193], v[42:45]
	v_mfma_f32_16x16x32_bf16 v[38:41], v[174:177], v[190:193], v[38:41]
	v_mfma_f32_16x16x32_bf16 v[26:29], v[166:169], v[206:209], v[26:29]
	v_mfma_f32_16x16x32_bf16 v[22:25], v[174:177], v[206:209], v[22:25]
	v_mfma_f32_16x16x32_bf16 v[8:11], v[166:169], v[228:231], v[10:13]
	v_mfma_f32_16x16x32_bf16 v[4:7], v[174:177], v[228:231], v[4:7]
	v_mfma_f32_16x16x32_bf16 v[58:61], v[170:173], v[186:189], v[58:61]
	v_mfma_f32_16x16x32_bf16 v[54:57], v[178:181], v[186:189], v[54:57]
	v_mfma_f32_16x16x32_bf16 v[42:45], v[170:173], v[194:197], v[42:45]
	v_mfma_f32_16x16x32_bf16 v[38:41], v[178:181], v[194:197], v[38:41]
	v_mfma_f32_16x16x32_bf16 v[26:29], v[170:173], v[224:227], v[26:29]
	v_mfma_f32_16x16x32_bf16 v[22:25], v[178:181], v[224:227], v[22:25]
	v_mfma_f32_16x16x32_bf16 v[10:13], v[170:173], v[232:235], v[8:11]
	v_mfma_f32_16x16x32_bf16 v[6:9], v[178:181], v[232:235], v[4:7]
	s_setprio 0
	s_barrier
	s_add_u32 s46, s46, 0x100
	s_addc_u32 s47, s47, 0
	s_add_u32 s65, s65, 0x100
	s_addc_u32 s66, s66, 0
	s_cmp_ge_i32 s67, s56
	s_mov_b32 s48, s67
	s_cbranch_scc0 .LBB0_1929
	s_add_i32 s50, s37, 0x1c000
	s_mov_b32 s68, 0x18000
	s_mov_b32 s69, 0x1c000
	s_add_i32 s70, s37, 0x14000

; #define PG8_STAGE(bufoff, gbase, voff) do { _Pragma("unroll") for (int _i = 0; _i < 2; ++_i) \
;         __builtin_amdgcn_global_load_lds((const unsigned*)((const char*)(gbase) + (voff)[_i]), (LAS unsigned*)(lds + (bufoff) + ldsw + _i * 8192), 16, 0, 0); } while (0)
; #define PG8_LDA(dst, b, h) do { _Pragma("unroll") for (int m = 0; m < 4; ++m) _Pragma("unroll") for (int k = 0; k < 2; ++k) dst[m][k] = *(const LAS bf16x8*)(lds + PG8_SA(b, h) + aoff + m * 2048 + k * 1024); } while (0)
; #define PG8_LDB(dst, b, h) do { _Pragma("unroll") for (int n = 0; n < 2; ++n) _Pragma("unroll") for (int k = 0; k < 2; ++k) dst[n][k] = *(const LAS bf16x8*)(lds + PG8_SB(b, h) + boff + n * 2048 + k * 1024); } while (0)
; #define PG8_MMA(ai, bj, At, Bt) do { __builtin_amdgcn_s_setprio(1); _Pragma("unroll") for (int m = 0; m < 4; ++m) _Pragma("unroll") for (int n = 0; n < 2; ++n) _Pragma("unroll") for (int k = 0; k < 2; ++k) \
;         acc[ai][bj][m][n] = __builtin_amdgcn_mfma_f32_16x16x32_bf16(Bt[n][k], At[m][k], acc[ai][bj][m][n], 0, 0, 0); __builtin_amdgcn_s_setprio(0); } while (0)
; #define PG8_WAIT_V(n) asm volatile("s_waitcnt vmcnt(" #n ")" ::: "memory")
; #define PG8_WAIT_L(n) asm volatile("s_waitcnt lgkmcnt(" #n ")" ::: "memory")
; #define PG8_BAR __builtin_amdgcn_s_barrier()
; #define PG8_WAIT_RELAX(flag, n) asm volatile("s_cmp_eq_u32 %0, 0\n\ts_cbranch_scc1 .Lrw%=\n\ts_waitcnt vmcnt(8)\n.Lrw%=:\n\ts_waitcnt vmcnt(%1)" :: "s"(flag), "n"(n) : "scc", "memory")
; #define PG8_SCHED __builtin_amdgcn_sched_barrier(0)
; template <class Epi, bool ALIGN_EPI = true>
; __device__ __forceinline__ void gemm_phase(LAS unsigned char* lds, const Gemm g, const Sched& S, const Epi& E) {
;     ...
;             const int rflag = __builtin_amdgcn_readfirstlane(t | (int)(ui == 0));
;             PG8_LDB(B0, 0, 0); PG8_LDB(B1, 0, 1); PG8_SCHED; PG8_LDA(At, 0, 0); PG8_STAGE(PG8_SA(1, 1), a1 + hstepA, voffA);
;             if constexpr (Epi::NSTORES > 0) PG8_WAIT_RELAX(rflag, 8 + Epi::NSTORES); else PG8_WAIT_V(8);
;             PG8_WAIT_L(0); PG8_BAR; PG8_MMA(0, 0, At, B0); PG8_MMA(0, 1, At, B1); PG8_BAR; PG8_SCHED;
;             PG8_LDA(At, 0, 1); PG8_STAGE(PG8_SB(0, 0), b2, voffB); PG8_STAGE(PG8_SB(0, 1), b2 + hstepB, voffB); PG8_STAGE(PG8_SA(0, 0), a2, voffA);
;             if constexpr (Epi::NSTORES > 0) PG8_WAIT_RELAX(rflag, 8 + Epi::NSTORES); else PG8_WAIT_V(8);
.LBB0_2023:
	s_add_i32 s69, s46, 2
	s_add_u32 s47, s26, 0xfff80080
	s_addc_u32 s48, s27, -1
	s_cmp_eq_u32 s58, s46
	v_add_u32_e32 v153, s46, v2
	s_cselect_b32 s49, s19, s48
	s_cselect_b32 s48, s21, s47
	s_cselect_b32 s47, s65, s68
	s_cselect_b32 s46, s66, s67
	v_readfirstlane_b32 s73, v153
	s_add_u32 s100, s26, 0xfff80000
	s_addc_u32 s101, s27, -1
	ds_read_b128 v[146:149], v151
	ds_read_b128 v[154:157], v151 offset:1024
	ds_read_b128 v[158:161], v151 offset:2048
	ds_read_b128 v[162:165], v151 offset:3072
	ds_read_b128 v[166:169], v151 offset:16384
	ds_read_b128 v[170:173], v151 offset:17408
	ds_read_b128 v[174:177], v151 offset:18432
	ds_read_b128 v[178:181], v151 offset:19456
	ds_read_b128 v[182:185], v152
	ds_read_b128 v[186:189], v152 offset:1024
	ds_read_b128 v[190:193], v152 offset:2048
	ds_read_b128 v[194:197], v152 offset:3072
	s_mov_b32 m0, s56
	ds_read_b128 v[206:209], v152 offset:4096
	global_load_lds_dwordx4 v142, s[100:101]
	s_mov_b32 m0, s57
	ds_read_b128 v[224:227], v152 offset:5120
	global_load_lds_dwordx4 v144, s[100:101]
	s_add_i32 m0, s36, 0xc000
	ds_read_b128 v[228:231], v152 offset:6144
	global_load_lds_dwordx4 v142, s[26:27]
	s_add_i32 m0, s36, 0xe000
	ds_read_b128 v[232:235], v152 offset:7168
	global_load_lds_dwordx4 v144, s[26:27]
	s_cmp_eq_u32 s73, 0
	s_cbranch_scc1 .Lrw18
	s_waitcnt vmcnt(8)
.Lrw18:
	s_waitcnt vmcnt(16) lgkmcnt(0)
	s_barrier
	s_setprio 1
	v_mfma_f32_16x16x32_bf16 v[130:133], v[146:149], v[182:185], v[130:133]
	v_mfma_f32_16x16x32_bf16 v[126:129], v[158:161], v[182:185], v[126:129]
	v_mfma_f32_16x16x32_bf16 v[122:125], v[146:149], v[190:193], v[122:125]
	v_mfma_f32_16x16x32_bf16 v[118:121], v[158:161], v[190:193], v[118:121]
	v_mfma_f32_16x16x32_bf16 v[114:117], v[146:149], v[206:209], v[114:117]
	v_mfma_f32_16x16x32_bf16 v[110:113], v[158:161], v[206:209], v[110:113]
	v_mfma_f32_16x16x32_bf16 v[106:109], v[146:149], v[228:231], v[106:109]
	v_mfma_f32_16x16x32_bf16 v[102:105], v[158:161], v[228:231], v[102:105]
	v_mfma_f32_16x16x32_bf16 v[130:133], v[154:157], v[186:189], v[130:133]
	v_mfma_f32_16x16x32_bf16 v[126:129], v[162:165], v[186:189], v[126:129]
	v_mfma_f32_16x16x32_bf16 v[122:125], v[154:157], v[194:197], v[122:125]
	v_mfma_f32_16x16x32_bf16 v[118:121], v[162:165], v[194:197], v[118:121]
	v_mfma_f32_16x16x32_bf16 v[114:117], v[154:157], v[224:227], v[114:117]
	v_mfma_f32_16x16x32_bf16 v[110:113], v[162:165], v[224:227], v[110:113]
	v_mfma_f32_16x16x32_bf16 v[106:109], v[154:157], v[232:235], v[106:109]
	v_mfma_f32_16x16x32_bf16 v[102:105], v[162:165], v[232:235], v[102:105]
	s_setprio 0
	s_setprio 1
	v_mfma_f32_16x16x32_bf16 v[98:101], v[166:169], v[182:185], v[98:101]
	v_mfma_f32_16x16x32_bf16 v[94:97], v[174:177], v[182:185], v[94:97]
	v_mfma_f32_16x16x32_bf16 v[90:93], v[166:169], v[190:193], v[90:93]
	v_mfma_f32_16x16x32_bf16 v[86:89], v[174:177], v[190:193], v[86:89]
	v_mfma_f32_16x16x32_bf16 v[82:85], v[166:169], v[206:209], v[82:85]
	v_mfma_f32_16x16x32_bf16 v[78:81], v[174:177], v[206:209], v[78:81]
	v_mfma_f32_16x16x32_bf16 v[74:77], v[166:169], v[228:231], v[74:77]
	v_mfma_f32_16x16x32_bf16 v[70:73], v[174:177], v[228:231], v[70:73]
	v_mfma_f32_16x16x32_bf16 v[98:101], v[170:173], v[186:189], v[98:101]
	v_mfma_f32_16x16x32_bf16 v[94:97], v[178:181], v[186:189], v[94:97]
	v_mfma_f32_16x16x32_bf16 v[90:93], v[170:173], v[194:197], v[90:93]
	v_mfma_f32_16x16x32_bf16 v[86:89], v[178:181], v[194:197], v[86:89]
	v_mfma_f32_16x16x32_bf16 v[82:85], v[170:173], v[224:227], v[82:85]
	v_mfma_f32_16x16x32_bf16 v[78:81], v[178:181], v[224:227], v[78:81]
	v_mfma_f32_16x16x32_bf16 v[74:77], v[170:173], v[232:235], v[74:77]
	v_mfma_f32_16x16x32_bf16 v[70:73], v[178:181], v[232:235], v[70:73]
	s_setprio 0
	s_barrier
	s_add_u32 s70, s46, 0x80000
	s_addc_u32 s71, s47, 0
	ds_read_b128 v[182:185], v152 offset:16384
	ds_read_b128 v[186:189], v152 offset:17408
	ds_read_b128 v[190:193], v152 offset:18432
	ds_read_b128 v[194:197], v152 offset:19456
	s_add_i32 m0, s35, 0x10000
	ds_read_b128 v[206:209], v152 offset:20480
	global_load_lds_dwordx4 v136, s[46:47]
	s_add_i32 m0, s35, 0x12000
	ds_read_b128 v[224:227], v152 offset:21504
	global_load_lds_dwordx4 v140, s[46:47]
	s_add_i32 m0, s35, 0x14000
	ds_read_b128 v[228:231], v152 offset:22528
	global_load_lds_dwordx4 v136, s[70:71]
	s_add_i32 m0, s35, 0x16000
	ds_read_b128 v[232:235], v152 offset:23552
	global_load_lds_dwordx4 v140, s[70:71]
	s_waitcnt vmcnt(6) lgkmcnt(0)
; #define PG8_STAGE(bufoff, gbase, voff) do { _Pragma("unroll") for (int _i = 0; _i < 2; ++_i) \
;         __builtin_amdgcn_global_load_lds((const unsigned*)((const char*)(gbase) + (voff)[_i]), (LAS unsigned*)(lds + (bufoff) + ldsw + _i * 8192), 16, 0, 0); } while (0)
; #define PG8_LDA(dst, b, h) do { _Pragma("unroll") for (int m = 0; m < 4; ++m) _Pragma("unroll") for (int k = 0; k < 2; ++k) dst[m][k] = *(const LAS bf16x8*)(lds + PG8_SA(b, h) + aoff + m * 2048 + k * 1024); } while (0)
; #define PG8_LDB(dst, b, h) do { _Pragma("unroll") for (int n = 0; n < 2; ++n) _Pragma("unroll") for (int k = 0; k < 2; ++k) dst[n][k] = *(const LAS bf16x8*)(lds + PG8_SB(b, h) + boff + n * 2048 + k * 1024); } while (0)
; #define PG8_MMA(ai, bj, At, Bt) do { __builtin_amdgcn_s_setprio(1); _Pragma("unroll") for (int m = 0; m < 4; ++m) _Pragma("unroll") for (int n = 0; n < 2; ++n) _Pragma("unroll") for (int k = 0; k < 2; ++k) \
;         acc[ai][bj][m][n] = __builtin_amdgcn_mfma_f32_16x16x32_bf16(Bt[n][k], At[m][k], acc[ai][bj][m][n], 0, 0, 0); __builtin_amdgcn_s_setprio(0); } while (0)
; #define PG8_WAIT_V(n) asm volatile("s_waitcnt vmcnt(" #n ")" ::: "memory")
; #define PG8_WAIT_L(n) asm volatile("s_waitcnt lgkmcnt(" #n ")" ::: "memory")
; #define PG8_BAR __builtin_amdgcn_s_barrier()
; #define PG8_WAIT_RELAX(flag, n) asm volatile("s_cmp_eq_u32 %0, 0\n\ts_cbranch_scc1 .Lrw%=\n\ts_waitcnt vmcnt(8)\n.Lrw%=:\n\ts_waitcnt vmcnt(%1)" :: "s"(flag), "n"(n) : "scc", "memory")
; #define PG8_SCHED __builtin_amdgcn_sched_barrier(0)
; template <class Epi, bool ALIGN_EPI = true>
; __device__ __forceinline__ void gemm_phase(LAS unsigned char* lds, const Gemm g, const Sched& S, const Epi& E) {
;     ...
;             if constexpr (Epi::NSTORES > 0) PG8_WAIT_RELAX(rflag, 8 + Epi::NSTORES); else PG8_WAIT_V(8);
;             PG8_WAIT_L(0); PG8_BAR; PG8_MMA(1, 0, At, B0); PG8_MMA(1, 1, At, B1); PG8_BAR; PG8_SCHED;
;             PG8_LDB(B0, 1, 0); PG8_LDB(B1, 1, 1); PG8_SCHED; PG8_LDA(At, 1, 0); PG8_STAGE(PG8_SA(0, 1), a2 + hstepA, voffA);
;             PG8_WAIT_V(8); PG8_WAIT_L(0); PG8_BAR; PG8_MMA(0, 0, At, B0); PG8_MMA(0, 1, At, B1); PG8_BAR; PG8_SCHED;
.Lrw19:
	s_barrier
	s_setprio 1
	v_mfma_f32_16x16x32_bf16 v[66:69], v[146:149], v[182:185], v[66:69]
	v_mfma_f32_16x16x32_bf16 v[62:65], v[158:161], v[182:185], v[62:65]
	v_mfma_f32_16x16x32_bf16 v[58:61], v[146:149], v[190:193], v[58:61]
	v_mfma_f32_16x16x32_bf16 v[54:57], v[158:161], v[190:193], v[54:57]
	v_mfma_f32_16x16x32_bf16 v[50:53], v[146:149], v[206:209], v[50:53]
	v_mfma_f32_16x16x32_bf16 v[46:49], v[158:161], v[206:209], v[46:49]
	v_mfma_f32_16x16x32_bf16 v[42:45], v[146:149], v[228:231], v[42:45]
	v_mfma_f32_16x16x32_bf16 v[38:41], v[158:161], v[228:231], v[38:41]
	v_mfma_f32_16x16x32_bf16 v[66:69], v[154:157], v[186:189], v[66:69]
	v_mfma_f32_16x16x32_bf16 v[62:65], v[162:165], v[186:189], v[62:65]
	v_mfma_f32_16x16x32_bf16 v[58:61], v[154:157], v[194:197], v[58:61]
	v_mfma_f32_16x16x32_bf16 v[54:57], v[162:165], v[194:197], v[54:57]
	v_mfma_f32_16x16x32_bf16 v[50:53], v[154:157], v[224:227], v[50:53]
	v_mfma_f32_16x16x32_bf16 v[46:49], v[162:165], v[224:227], v[46:49]
	v_mfma_f32_16x16x32_bf16 v[42:45], v[154:157], v[232:235], v[42:45]
	v_mfma_f32_16x16x32_bf16 v[38:41], v[162:165], v[232:235], v[38:41]
	s_setprio 0
	s_setprio 1
	v_mfma_f32_16x16x32_bf16 v[34:37], v[166:169], v[182:185], v[34:37]
	v_mfma_f32_16x16x32_bf16 v[30:33], v[174:177], v[182:185], v[30:33]
	v_mfma_f32_16x16x32_bf16 v[26:29], v[166:169], v[190:193], v[26:29]
	v_mfma_f32_16x16x32_bf16 v[22:25], v[174:177], v[190:193], v[22:25]
	v_mfma_f32_16x16x32_bf16 v[18:21], v[166:169], v[206:209], v[18:21]
	v_mfma_f32_16x16x32_bf16 v[14:17], v[174:177], v[206:209], v[14:17]
	v_mfma_f32_16x16x32_bf16 v[10:13], v[166:169], v[228:231], v[10:13]
	v_mfma_f32_16x16x32_bf16 v[4:7], v[174:177], v[228:231], v[6:9]
	v_mfma_f32_16x16x32_bf16 v[34:37], v[170:173], v[186:189], v[34:37]
	v_mfma_f32_16x16x32_bf16 v[30:33], v[178:181], v[186:189], v[30:33]
	v_mfma_f32_16x16x32_bf16 v[26:29], v[170:173], v[194:197], v[26:29]
	v_mfma_f32_16x16x32_bf16 v[22:25], v[178:181], v[194:197], v[22:25]
	v_mfma_f32_16x16x32_bf16 v[18:21], v[170:173], v[224:227], v[18:21]
	v_mfma_f32_16x16x32_bf16 v[14:17], v[178:181], v[224:227], v[14:17]
	v_mfma_f32_16x16x32_bf16 v[10:13], v[170:173], v[232:235], v[10:13]
	v_mfma_f32_16x16x32_bf16 v[4:7], v[178:181], v[232:235], v[4:7]
	s_setprio 0
	s_barrier
	s_mov_b64 s[100:101], s[48:49]
	s_add_u32 s48, s48, 0x80000
	s_addc_u32 s49, s49, 0
	ds_read_b128 v[146:149], v151 offset:32768
	ds_read_b128 v[154:157], v151 offset:33792
	ds_read_b128 v[158:161], v151 offset:34816
	ds_read_b128 v[162:165], v151 offset:35840
	ds_read_b128 v[166:169], v151 offset:49152
	ds_read_b128 v[170:173], v151 offset:50176
	ds_read_b128 v[174:177], v151 offset:51200
	ds_read_b128 v[178:181], v151 offset:52224
	ds_read_b128 v[182:185], v152 offset:32768
	ds_read_b128 v[186:189], v152 offset:33792
	ds_read_b128 v[190:193], v152 offset:34816
	ds_read_b128 v[194:197], v152 offset:35840
	s_mov_b32 m0, s36
	ds_read_b128 v[206:209], v152 offset:36864
	global_load_lds_dwordx4 v134, s[100:101]
	s_mov_b32 m0, s37
	ds_read_b128 v[224:227], v152 offset:37888
	global_load_lds_dwordx4 v138, s[100:101]
	s_mov_b32 m0, s50
	ds_read_b128 v[228:231], v152 offset:38912
	global_load_lds_dwordx4 v134, s[48:49]
	s_mov_b32 m0, s51
	ds_read_b128 v[232:235], v152 offset:39936
	global_load_lds_dwordx4 v138, s[48:49]
	s_waitcnt vmcnt(8) lgkmcnt(0)
	s_barrier
; #define PG8_STAGE(bufoff, gbase, voff) do { _Pragma("unroll") for (int _i = 0; _i < 2; ++_i) \
;         __builtin_amdgcn_global_load_lds((const unsigned*)((const char*)(gbase) + (voff)[_i]), (LAS unsigned*)(lds + (bufoff) + ldsw + _i * 8192), 16, 0, 0); } while (0)
; #define PG8_LDA(dst, b, h) do { _Pragma("unroll") for (int m = 0; m < 4; ++m) _Pragma("unroll") for (int k = 0; k < 2; ++k) dst[m][k] = *(const LAS bf16x8*)(lds + PG8_SA(b, h) + aoff + m * 2048 + k * 1024); } while (0)
; #define PG8_MMA(ai, bj, At, Bt) do { __builtin_amdgcn_s_setprio(1); _Pragma("unroll") for (int m = 0; m < 4; ++m) _Pragma("unroll") for (int n = 0; n < 2; ++n) _Pragma("unroll") for (int k = 0; k < 2; ++k) \
;         acc[ai][bj][m][n] = __builtin_amdgcn_mfma_f32_16x16x32_bf16(Bt[n][k], At[m][k], acc[ai][bj][m][n], 0, 0, 0); __builtin_amdgcn_s_setprio(0); } while (0)
; #define PG8_WAIT_V(n) asm volatile("s_waitcnt vmcnt(" #n ")" ::: "memory")
; #define PG8_WAIT_L(n) asm volatile("s_waitcnt lgkmcnt(" #n ")" ::: "memory")
; #define PG8_BAR __builtin_amdgcn_s_barrier()
; #define PG8_SCHED __builtin_amdgcn_sched_barrier(0)
; template <class Epi, bool ALIGN_EPI = true>
; __device__ __forceinline__ void gemm_phase(LAS unsigned char* lds, const Gemm g, const Sched& S, const Epi& E) {
;     ...
;         for (int t = t_lo; t < t_hi; t += 2) {
;             const bool last = (t == nt - 2);
;     ...
;             PG8_WAIT_V(8); PG8_WAIT_L(0); PG8_BAR; PG8_MMA(0, 0, At, B0); PG8_MMA(0, 1, At, B1); PG8_BAR; PG8_SCHED;
;             PG8_LDA(At, 1, 1); PG8_STAGE(PG8_SB(1, 0), b3, voffB); PG8_STAGE(PG8_SB(1, 1), b3 + hstepB, voffB); PG8_STAGE(PG8_SA(1, 0), a3, voffA);
;             PG8_WAIT_V(8); PG8_WAIT_L(0); PG8_BAR; PG8_MMA(1, 0, At, B0); PG8_MMA(1, 1, At, B1); PG8_BAR; PG8_SCHED;
	s_setprio 1
	v_mfma_f32_16x16x32_bf16 v[130:133], v[146:149], v[182:185], v[130:133]
	v_mfma_f32_16x16x32_bf16 v[126:129], v[158:161], v[182:185], v[126:129]
	v_mfma_f32_16x16x32_bf16 v[122:125], v[146:149], v[190:193], v[122:125]
	v_mfma_f32_16x16x32_bf16 v[118:121], v[158:161], v[190:193], v[118:121]
	v_mfma_f32_16x16x32_bf16 v[114:117], v[146:149], v[206:209], v[114:117]
	v_mfma_f32_16x16x32_bf16 v[110:113], v[158:161], v[206:209], v[110:113]
	v_mfma_f32_16x16x32_bf16 v[106:109], v[146:149], v[228:231], v[106:109]
	v_mfma_f32_16x16x32_bf16 v[102:105], v[158:161], v[228:231], v[102:105]
	v_mfma_f32_16x16x32_bf16 v[130:133], v[154:157], v[186:189], v[130:133]
	v_mfma_f32_16x16x32_bf16 v[126:129], v[162:165], v[186:189], v[126:129]
	v_mfma_f32_16x16x32_bf16 v[122:125], v[154:157], v[194:197], v[122:125]
	v_mfma_f32_16x16x32_bf16 v[118:121], v[162:165], v[194:197], v[118:121]
	v_mfma_f32_16x16x32_bf16 v[114:117], v[154:157], v[224:227], v[114:117]
	v_mfma_f32_16x16x32_bf16 v[110:113], v[162:165], v[224:227], v[110:113]
	v_mfma_f32_16x16x32_bf16 v[106:109], v[154:157], v[232:235], v[106:109]
	v_mfma_f32_16x16x32_bf16 v[102:105], v[162:165], v[232:235], v[102:105]
	s_setprio 0
	s_setprio 1
	v_mfma_f32_16x16x32_bf16 v[98:101], v[166:169], v[182:185], v[98:101]
	v_mfma_f32_16x16x32_bf16 v[94:97], v[174:177], v[182:185], v[94:97]
	v_mfma_f32_16x16x32_bf16 v[90:93], v[166:169], v[190:193], v[90:93]
	v_mfma_f32_16x16x32_bf16 v[86:89], v[174:177], v[190:193], v[86:89]
	v_mfma_f32_16x16x32_bf16 v[82:85], v[166:169], v[206:209], v[82:85]
	v_mfma_f32_16x16x32_bf16 v[78:81], v[174:177], v[206:209], v[78:81]
	v_mfma_f32_16x16x32_bf16 v[74:77], v[166:169], v[228:231], v[74:77]
	v_mfma_f32_16x16x32_bf16 v[70:73], v[174:177], v[228:231], v[70:73]
	v_mfma_f32_16x16x32_bf16 v[98:101], v[170:173], v[186:189], v[98:101]
	v_mfma_f32_16x16x32_bf16 v[94:97], v[178:181], v[186:189], v[94:97]
	v_mfma_f32_16x16x32_bf16 v[90:93], v[170:173], v[194:197], v[90:93]
	v_mfma_f32_16x16x32_bf16 v[86:89], v[178:181], v[194:197], v[86:89]
	v_mfma_f32_16x16x32_bf16 v[82:85], v[170:173], v[224:227], v[82:85]
	v_mfma_f32_16x16x32_bf16 v[78:81], v[178:181], v[224:227], v[78:81]
	v_mfma_f32_16x16x32_bf16 v[74:77], v[170:173], v[232:235], v[74:77]
	v_mfma_f32_16x16x32_bf16 v[70:73], v[178:181], v[232:235], v[70:73]
	s_setprio 0
	s_barrier
	ds_read_b128 v[182:185], v152 offset:49152
	ds_read_b128 v[186:189], v152 offset:50176
	ds_read_b128 v[190:193], v152 offset:51200
	ds_read_b128 v[194:197], v152 offset:52224
	s_add_i32 m0, s35, 0x17f80
	ds_read_b128 v[206:209], v152 offset:53248
	global_load_lds_dwordx4 v136, s[46:47] offset:128
	s_add_i32 m0, s35, 0x19f80
	ds_read_b128 v[224:227], v152 offset:54272
	global_load_lds_dwordx4 v140, s[46:47] offset:128
	s_add_i32 m0, s35, 0x1c000
	s_add_u32 s46, s46, 0x80080
	s_addc_u32 s47, s47, 0
	ds_read_b128 v[228:231], v152 offset:55296
	global_load_lds_dwordx4 v136, s[46:47]
	s_add_i32 m0, s35, 0x1e000
	ds_read_b128 v[232:235], v152 offset:56320
	global_load_lds_dwordx4 v140, s[46:47]
	s_waitcnt vmcnt(6) lgkmcnt(0)
	s_barrier
	s_setprio 1
	v_mfma_f32_16x16x32_bf16 v[66:69], v[146:149], v[182:185], v[66:69]
	v_mfma_f32_16x16x32_bf16 v[62:65], v[158:161], v[182:185], v[62:65]
	v_mfma_f32_16x16x32_bf16 v[58:61], v[146:149], v[190:193], v[58:61]
	v_mfma_f32_16x16x32_bf16 v[54:57], v[158:161], v[190:193], v[54:57]
	v_mfma_f32_16x16x32_bf16 v[50:53], v[146:149], v[206:209], v[50:53]
	v_mfma_f32_16x16x32_bf16 v[46:49], v[158:161], v[206:209], v[46:49]
	v_mfma_f32_16x16x32_bf16 v[42:45], v[146:149], v[228:231], v[42:45]
	v_mfma_f32_16x16x32_bf16 v[38:41], v[158:161], v[228:231], v[38:41]
	v_mfma_f32_16x16x32_bf16 v[66:69], v[154:157], v[186:189], v[66:69]
	v_mfma_f32_16x16x32_bf16 v[62:65], v[162:165], v[186:189], v[62:65]
	v_mfma_f32_16x16x32_bf16 v[58:61], v[154:157], v[194:197], v[58:61]
	v_mfma_f32_16x16x32_bf16 v[54:57], v[162:165], v[194:197], v[54:57]
	v_mfma_f32_16x16x32_bf16 v[50:53], v[154:157], v[224:227], v[50:53]
	v_mfma_f32_16x16x32_bf16 v[46:49], v[162:165], v[224:227], v[46:49]
	v_mfma_f32_16x16x32_bf16 v[42:45], v[154:157], v[232:235], v[42:45]
	v_mfma_f32_16x16x32_bf16 v[38:41], v[162:165], v[232:235], v[38:41]
	s_setprio 0
	s_setprio 1
	v_mfma_f32_16x16x32_bf16 v[34:37], v[166:169], v[182:185], v[34:37]
	v_mfma_f32_16x16x32_bf16 v[30:33], v[174:177], v[182:185], v[30:33]
	v_mfma_f32_16x16x32_bf16 v[26:29], v[166:169], v[190:193], v[26:29]
	v_mfma_f32_16x16x32_bf16 v[22:25], v[174:177], v[190:193], v[22:25]
	v_mfma_f32_16x16x32_bf16 v[18:21], v[166:169], v[206:209], v[18:21]
	v_mfma_f32_16x16x32_bf16 v[14:17], v[174:177], v[206:209], v[14:17]
	v_mfma_f32_16x16x32_bf16 v[8:11], v[166:169], v[228:231], v[10:13]
	v_mfma_f32_16x16x32_bf16 v[4:7], v[174:177], v[228:231], v[4:7]
	v_mfma_f32_16x16x32_bf16 v[34:37], v[170:173], v[186:189], v[34:37]
	v_mfma_f32_16x16x32_bf16 v[30:33], v[178:181], v[186:189], v[30:33]
	v_mfma_f32_16x16x32_bf16 v[26:29], v[170:173], v[194:197], v[26:29]
	v_mfma_f32_16x16x32_bf16 v[22:25], v[178:181], v[194:197], v[22:25]
	v_mfma_f32_16x16x32_bf16 v[18:21], v[170:173], v[224:227], v[18:21]
	v_mfma_f32_16x16x32_bf16 v[14:17], v[178:181], v[224:227], v[14:17]
	v_mfma_f32_16x16x32_bf16 v[10:13], v[170:173], v[232:235], v[8:11]
	v_mfma_f32_16x16x32_bf16 v[6:9], v[178:181], v[232:235], v[4:7]
	s_setprio 0
	s_barrier
	s_add_u32 s26, s26, 0x100
	s_addc_u32 s27, s27, 0
	s_add_u32 s67, s67, 0x100
	s_addc_u32 s68, s68, 0
	s_cmp_ge_i32 s69, s54
	s_mov_b32 s46, s69
	s_cbranch_scc0 .LBB0_2023
	s_add_i32 s48, s35, 0x1c000
	s_mov_b32 s70, 0x18000
	s_mov_b32 s71, 0x1c000
	s_add_i32 s72, s35, 0x14000
	s_mov_b32 s72, 0x8000

; #define PG8_STAGE(bufoff, gbase, voff) do { _Pragma("unroll") for (int _i = 0; _i < 2; ++_i) \
;         __builtin_amdgcn_global_load_lds((const unsigned*)((const char*)(gbase) + (voff)[_i]), (LAS unsigned*)(lds + (bufoff) + ldsw + _i * 8192), 16, 0, 0); } while (0)
; #define PG8_LDA(dst, b, h) do { _Pragma("unroll") for (int m = 0; m < 4; ++m) _Pragma("unroll") for (int k = 0; k < 2; ++k) dst[m][k] = *(const LAS bf16x8*)(lds + PG8_SA(b, h) + aoff + m * 2048 + k * 1024); } while (0)
; #define PG8_LDB(dst, b, h) do { _Pragma("unroll") for (int n = 0; n < 2; ++n) _Pragma("unroll") for (int k = 0; k < 2; ++k) dst[n][k] = *(const LAS bf16x8*)(lds + PG8_SB(b, h) + boff + n * 2048 + k * 1024); } while (0)
; #define PG8_MMA(ai, bj, At, Bt) do { __builtin_amdgcn_s_setprio(1); _Pragma("unroll") for (int m = 0; m < 4; ++m) _Pragma("unroll") for (int n = 0; n < 2; ++n) _Pragma("unroll") for (int k = 0; k < 2; ++k) \
;         acc[ai][bj][m][n] = __builtin_amdgcn_mfma_f32_16x16x32_bf16(Bt[n][k], At[m][k], acc[ai][bj][m][n], 0, 0, 0); __builtin_amdgcn_s_setprio(0); } while (0)
; template <class Epi, bool ALIGN_EPI = true>
; __device__ __forceinline__ void gemm_phase(LAS unsigned char* lds, const Gemm g, const Sched& S, const Epi& E) {
;     ...
;         for (int t = t_lo; t < t_hi; t += 2) {
;             const bool last = (t == nt - 2);
;             const char* a1 = cA + (size_t)(t + 1) * kstep;
;             const char* a2 = last ? nA : cA + (size_t)(t + 2) * kstep; const char* b2 = last ? nB : cB + (size_t)(t + 2) * kstep;
;             const char* a3 = a2 + kstep; const char* b3 = b2 + kstep;
;             const int rflag = __builtin_amdgcn_readfirstlane(t | (int)(ui == 0));
;             PG8_LDB(B0, 0, 0); PG8_LDB(B1, 0, 1); PG8_SCHED; PG8_LDA(At, 0, 0); PG8_STAGE(PG8_SA(1, 1), a1 + hstepA, voffA);
;             if constexpr (Epi::NSTORES > 0) PG8_WAIT_RELAX(rflag, 8 + Epi::NSTORES); else PG8_WAIT_V(8);
;             PG8_WAIT_L(0); PG8_BAR; PG8_MMA(0, 0, At, B0); PG8_MMA(0, 1, At, B1); PG8_BAR; PG8_SCHED;
;             PG8_LDA(At, 0, 1); PG8_STAGE(PG8_SB(0, 0), b2, voffB); PG8_STAGE(PG8_SB(0, 1), b2 + hstepB, voffB); PG8_STAGE(PG8_SA(0, 0), a2, voffA);
;             if constexpr (Epi::NSTORES > 0) PG8_WAIT_RELAX(rflag, 8 + Epi::NSTORES); else PG8_WAIT_V(8);
;             PG8_WAIT_L(0); PG8_BAR; PG8_MMA(1, 0, At, B0); PG8_MMA(1, 1, At, B1); PG8_BAR; PG8_SCHED;
.LBB0_2287:
	s_add_i32 s69, s44, 2
	s_add_u32 s42, s48, 0x100
	s_addc_u32 s43, s49, 0
	s_cmp_eq_u32 s57, s44
	s_cselect_b32 s47, s63, s43
	s_cselect_b32 s46, s64, s42
	s_cselect_b32 s45, s65, s68
	s_cselect_b32 s44, s66, s67
	s_add_u32 s100, s48, 0xffea0000
	s_addc_u32 s101, s49, -1
	ds_read_b128 v[150:153], v147
	ds_read_b128 v[154:157], v147 offset:1024
	ds_read_b128 v[158:161], v147 offset:2048
	ds_read_b128 v[162:165], v147 offset:3072
	ds_read_b128 v[166:169], v147 offset:16384
	ds_read_b128 v[170:173], v147 offset:17408
	ds_read_b128 v[174:177], v147 offset:18432
	ds_read_b128 v[178:181], v147 offset:19456
	ds_read_b128 v[182:185], v148
	ds_read_b128 v[186:189], v148 offset:1024
	ds_read_b128 v[190:193], v148 offset:2048
	ds_read_b128 v[194:197], v148 offset:3072
	s_mov_b32 m0, s55
	ds_read_b128 v[206:209], v148 offset:4096
	global_load_lds_dwordx4 v142, s[100:101]
	s_mov_b32 m0, s56
	ds_read_b128 v[224:227], v148 offset:5120
	global_load_lds_dwordx4 v144, s[100:101]
	s_add_i32 m0, s50, 0xc000
	ds_read_b128 v[228:231], v148 offset:6144
	global_load_lds_dwordx4 v142, s[48:49]
	s_add_i32 m0, s50, 0xe000
	ds_read_b128 v[232:235], v148 offset:7168
	global_load_lds_dwordx4 v144, s[48:49]
	s_waitcnt vmcnt(8) lgkmcnt(0)
	s_barrier
	s_setprio 1
	v_mfma_f32_16x16x32_bf16 v[130:133], v[150:153], v[182:185], v[130:133]
	v_mfma_f32_16x16x32_bf16 v[126:129], v[158:161], v[182:185], v[126:129]
	v_mfma_f32_16x16x32_bf16 v[114:117], v[150:153], v[190:193], v[114:117]
	v_mfma_f32_16x16x32_bf16 v[110:113], v[158:161], v[190:193], v[110:113]
	v_mfma_f32_16x16x32_bf16 v[98:101], v[150:153], v[206:209], v[98:101]
	v_mfma_f32_16x16x32_bf16 v[94:97], v[158:161], v[206:209], v[94:97]
	v_mfma_f32_16x16x32_bf16 v[82:85], v[150:153], v[228:231], v[82:85]
	v_mfma_f32_16x16x32_bf16 v[78:81], v[158:161], v[228:231], v[78:81]
	v_mfma_f32_16x16x32_bf16 v[130:133], v[154:157], v[186:189], v[130:133]
	v_mfma_f32_16x16x32_bf16 v[126:129], v[162:165], v[186:189], v[126:129]
	v_mfma_f32_16x16x32_bf16 v[114:117], v[154:157], v[194:197], v[114:117]
	v_mfma_f32_16x16x32_bf16 v[110:113], v[162:165], v[194:197], v[110:113]
	v_mfma_f32_16x16x32_bf16 v[98:101], v[154:157], v[224:227], v[98:101]
	v_mfma_f32_16x16x32_bf16 v[94:97], v[162:165], v[224:227], v[94:97]
	v_mfma_f32_16x16x32_bf16 v[82:85], v[154:157], v[232:235], v[82:85]
	v_mfma_f32_16x16x32_bf16 v[78:81], v[162:165], v[232:235], v[78:81]
	s_setprio 0
	s_setprio 1
	v_mfma_f32_16x16x32_bf16 v[122:125], v[166:169], v[182:185], v[122:125]
	v_mfma_f32_16x16x32_bf16 v[118:121], v[174:177], v[182:185], v[118:121]
	v_mfma_f32_16x16x32_bf16 v[106:109], v[166:169], v[190:193], v[106:109]
	v_mfma_f32_16x16x32_bf16 v[102:105], v[174:177], v[190:193], v[102:105]
	v_mfma_f32_16x16x32_bf16 v[90:93], v[166:169], v[206:209], v[90:93]
	v_mfma_f32_16x16x32_bf16 v[86:89], v[174:177], v[206:209], v[86:89]
	v_mfma_f32_16x16x32_bf16 v[74:77], v[166:169], v[228:231], v[74:77]
	v_mfma_f32_16x16x32_bf16 v[70:73], v[174:177], v[228:231], v[70:73]
	v_mfma_f32_16x16x32_bf16 v[122:125], v[170:173], v[186:189], v[122:125]
	v_mfma_f32_16x16x32_bf16 v[118:121], v[178:181], v[186:189], v[118:121]
	v_mfma_f32_16x16x32_bf16 v[106:109], v[170:173], v[194:197], v[106:109]
	v_mfma_f32_16x16x32_bf16 v[102:105], v[178:181], v[194:197], v[102:105]
	v_mfma_f32_16x16x32_bf16 v[90:93], v[170:173], v[224:227], v[90:93]
	v_mfma_f32_16x16x32_bf16 v[86:89], v[178:181], v[224:227], v[86:89]
	v_mfma_f32_16x16x32_bf16 v[74:77], v[170:173], v[232:235], v[74:77]
	v_mfma_f32_16x16x32_bf16 v[70:73], v[178:181], v[232:235], v[70:73]
	s_setprio 0
	s_barrier
	s_add_u32 s48, s44, 0x160000
	s_addc_u32 s49, s45, 0
	ds_read_b128 v[182:185], v148 offset:16384
	ds_read_b128 v[186:189], v148 offset:17408
	ds_read_b128 v[190:193], v148 offset:18432
	ds_read_b128 v[194:197], v148 offset:19456
	s_add_i32 m0, s37, 0x10000
	ds_read_b128 v[206:209], v148 offset:20480
	global_load_lds_dwordx4 v138, s[44:45]
	s_add_i32 m0, s37, 0x12000
	ds_read_b128 v[224:227], v148 offset:21504
	global_load_lds_dwordx4 v134, s[44:45]
	s_add_i32 m0, s37, 0x14000
	ds_read_b128 v[228:231], v148 offset:22528
	global_load_lds_dwordx4 v138, s[48:49]
	s_add_i32 m0, s37, 0x16000
	ds_read_b128 v[232:235], v148 offset:23552
	global_load_lds_dwordx4 v134, s[48:49]
	s_waitcnt vmcnt(6) lgkmcnt(0)
	s_barrier
	s_setprio 1
	v_mfma_f32_16x16x32_bf16 v[66:69], v[150:153], v[182:185], v[66:69]
	v_mfma_f32_16x16x32_bf16 v[62:65], v[158:161], v[182:185], v[62:65]
	v_mfma_f32_16x16x32_bf16 v[50:53], v[150:153], v[190:193], v[50:53]
	v_mfma_f32_16x16x32_bf16 v[46:49], v[158:161], v[190:193], v[46:49]
	v_mfma_f32_16x16x32_bf16 v[34:37], v[150:153], v[206:209], v[34:37]
	v_mfma_f32_16x16x32_bf16 v[30:33], v[158:161], v[206:209], v[30:33]
	v_mfma_f32_16x16x32_bf16 v[18:21], v[150:153], v[228:231], v[18:21]
	v_mfma_f32_16x16x32_bf16 v[14:17], v[158:161], v[228:231], v[14:17]
	v_mfma_f32_16x16x32_bf16 v[66:69], v[154:157], v[186:189], v[66:69]
	v_mfma_f32_16x16x32_bf16 v[62:65], v[162:165], v[186:189], v[62:65]
	v_mfma_f32_16x16x32_bf16 v[50:53], v[154:157], v[194:197], v[50:53]
	v_mfma_f32_16x16x32_bf16 v[46:49], v[162:165], v[194:197], v[46:49]
	v_mfma_f32_16x16x32_bf16 v[34:37], v[154:157], v[224:227], v[34:37]
	v_mfma_f32_16x16x32_bf16 v[30:33], v[162:165], v[224:227], v[30:33]
	v_mfma_f32_16x16x32_bf16 v[18:21], v[154:157], v[232:235], v[18:21]
	v_mfma_f32_16x16x32_bf16 v[14:17], v[162:165], v[232:235], v[14:17]
	s_setprio 0
	s_setprio 1
	v_mfma_f32_16x16x32_bf16 v[58:61], v[166:169], v[182:185], v[58:61]
	v_mfma_f32_16x16x32_bf16 v[54:57], v[174:177], v[182:185], v[54:57]
	v_mfma_f32_16x16x32_bf16 v[42:45], v[166:169], v[190:193], v[42:45]
	v_mfma_f32_16x16x32_bf16 v[38:41], v[174:177], v[190:193], v[38:41]
	v_mfma_f32_16x16x32_bf16 v[26:29], v[166:169], v[206:209], v[26:29]
	v_mfma_f32_16x16x32_bf16 v[22:25], v[174:177], v[206:209], v[22:25]
	v_mfma_f32_16x16x32_bf16 v[10:13], v[166:169], v[228:231], v[10:13]
	v_mfma_f32_16x16x32_bf16 v[4:7], v[174:177], v[228:231], v[6:9]
	v_mfma_f32_16x16x32_bf16 v[58:61], v[170:173], v[186:189], v[58:61]
	v_mfma_f32_16x16x32_bf16 v[54:57], v[178:181], v[186:189], v[54:57]
	v_mfma_f32_16x16x32_bf16 v[42:45], v[170:173], v[194:197], v[42:45]
	v_mfma_f32_16x16x32_bf16 v[38:41], v[178:181], v[194:197], v[38:41]
	v_mfma_f32_16x16x32_bf16 v[26:29], v[170:173], v[224:227], v[26:29]
	v_mfma_f32_16x16x32_bf16 v[22:25], v[178:181], v[224:227], v[22:25]
	v_mfma_f32_16x16x32_bf16 v[10:13], v[170:173], v[232:235], v[10:13]
	v_mfma_f32_16x16x32_bf16 v[4:7], v[178:181], v[232:235], v[4:7]
	s_setprio 0
	s_barrier
; #define PG8_STAGE(bufoff, gbase, voff) do { _Pragma("unroll") for (int _i = 0; _i < 2; ++_i) \
;         __builtin_amdgcn_global_load_lds((const unsigned*)((const char*)(gbase) + (voff)[_i]), (LAS unsigned*)(lds + (bufoff) + ldsw + _i * 8192), 16, 0, 0); } while (0)
; #define PG8_LDA(dst, b, h) do { _Pragma("unroll") for (int m = 0; m < 4; ++m) _Pragma("unroll") for (int k = 0; k < 2; ++k) dst[m][k] = *(const LAS bf16x8*)(lds + PG8_SA(b, h) + aoff + m * 2048 + k * 1024); } while (0)
; #define PG8_LDB(dst, b, h) do { _Pragma("unroll") for (int n = 0; n < 2; ++n) _Pragma("unroll") for (int k = 0; k < 2; ++k) dst[n][k] = *(const LAS bf16x8*)(lds + PG8_SB(b, h) + boff + n * 2048 + k * 1024); } while (0)
; #define PG8_MMA(ai, bj, At, Bt) do { __builtin_amdgcn_s_setprio(1); _Pragma("unroll") for (int m = 0; m < 4; ++m) _Pragma("unroll") for (int n = 0; n < 2; ++n) _Pragma("unroll") for (int k = 0; k < 2; ++k) \
;         acc[ai][bj][m][n] = __builtin_amdgcn_mfma_f32_16x16x32_bf16(Bt[n][k], At[m][k], acc[ai][bj][m][n], 0, 0, 0); __builtin_amdgcn_s_setprio(0); } while (0)
; #define PG8_WAIT_V(n) asm volatile("s_waitcnt vmcnt(" #n ")" ::: "memory")
; #define PG8_WAIT_L(n) asm volatile("s_waitcnt lgkmcnt(" #n ")" ::: "memory")
; #define PG8_BAR __builtin_amdgcn_s_barrier()
; #define PG8_SCHED __builtin_amdgcn_sched_barrier(0)
; template <class Epi, bool ALIGN_EPI = true>
; __device__ __forceinline__ void gemm_phase(LAS unsigned char* lds, const Gemm g, const Sched& S, const Epi& E) {
;     ...
;         for (int t = t_lo; t < t_hi; t += 2) {
;             const bool last = (t == nt - 2);
;     ...
;             PG8_LDB(B0, 1, 0); PG8_LDB(B1, 1, 1); PG8_SCHED; PG8_LDA(At, 1, 0); PG8_STAGE(PG8_SA(0, 1), a2 + hstepA, voffA);
;             PG8_WAIT_V(8); PG8_WAIT_L(0); PG8_BAR; PG8_MMA(0, 0, At, B0); PG8_MMA(0, 1, At, B1); PG8_BAR; PG8_SCHED;
;             PG8_LDA(At, 1, 1); PG8_STAGE(PG8_SB(1, 0), b3, voffB); PG8_STAGE(PG8_SB(1, 1), b3 + hstepB, voffB); PG8_STAGE(PG8_SA(1, 0), a3, voffA);
;             PG8_WAIT_V(8); PG8_WAIT_L(0); PG8_BAR; PG8_MMA(1, 0, At, B0); PG8_MMA(1, 1, At, B1); PG8_BAR; PG8_SCHED;
	s_mov_b64 s[100:101], s[46:47]
	s_add_u32 s46, s46, 0x160000
	s_addc_u32 s47, s47, 0
	ds_read_b128 v[150:153], v147 offset:32768
	ds_read_b128 v[154:157], v147 offset:33792
	ds_read_b128 v[158:161], v147 offset:34816
	ds_read_b128 v[162:165], v147 offset:35840
	ds_read_b128 v[166:169], v147 offset:49152
	ds_read_b128 v[170:173], v147 offset:50176
	ds_read_b128 v[174:177], v147 offset:51200
	ds_read_b128 v[178:181], v147 offset:52224
	ds_read_b128 v[182:185], v148 offset:32768
	ds_read_b128 v[186:189], v148 offset:33792
	ds_read_b128 v[190:193], v148 offset:34816
	ds_read_b128 v[194:197], v148 offset:35840
	s_mov_b32 m0, s50
	ds_read_b128 v[206:209], v148 offset:36864
	global_load_lds_dwordx4 v140, s[100:101]
	s_mov_b32 m0, s51
	ds_read_b128 v[224:227], v148 offset:37888
	global_load_lds_dwordx4 v136, s[100:101]
	s_mov_b32 m0, s52
	ds_read_b128 v[228:231], v148 offset:38912
	global_load_lds_dwordx4 v140, s[46:47]
	s_mov_b32 m0, s53
	ds_read_b128 v[232:235], v148 offset:39936
	global_load_lds_dwordx4 v136, s[46:47]
	s_waitcnt vmcnt(8) lgkmcnt(0)
	s_barrier
	s_setprio 1
	v_mfma_f32_16x16x32_bf16 v[130:133], v[150:153], v[182:185], v[130:133]
	v_mfma_f32_16x16x32_bf16 v[126:129], v[158:161], v[182:185], v[126:129]
	v_mfma_f32_16x16x32_bf16 v[114:117], v[150:153], v[190:193], v[114:117]
	v_mfma_f32_16x16x32_bf16 v[110:113], v[158:161], v[190:193], v[110:113]
	v_mfma_f32_16x16x32_bf16 v[98:101], v[150:153], v[206:209], v[98:101]
	v_mfma_f32_16x16x32_bf16 v[94:97], v[158:161], v[206:209], v[94:97]
	v_mfma_f32_16x16x32_bf16 v[82:85], v[150:153], v[228:231], v[82:85]
	v_mfma_f32_16x16x32_bf16 v[78:81], v[158:161], v[228:231], v[78:81]
	v_mfma_f32_16x16x32_bf16 v[130:133], v[154:157], v[186:189], v[130:133]
	v_mfma_f32_16x16x32_bf16 v[126:129], v[162:165], v[186:189], v[126:129]
	v_mfma_f32_16x16x32_bf16 v[114:117], v[154:157], v[194:197], v[114:117]
	v_mfma_f32_16x16x32_bf16 v[110:113], v[162:165], v[194:197], v[110:113]
	v_mfma_f32_16x16x32_bf16 v[98:101], v[154:157], v[224:227], v[98:101]
	v_mfma_f32_16x16x32_bf16 v[94:97], v[162:165], v[224:227], v[94:97]
	v_mfma_f32_16x16x32_bf16 v[82:85], v[154:157], v[232:235], v[82:85]
	v_mfma_f32_16x16x32_bf16 v[78:81], v[162:165], v[232:235], v[78:81]
	s_setprio 0
	s_setprio 1
	v_mfma_f32_16x16x32_bf16 v[122:125], v[166:169], v[182:185], v[122:125]
	v_mfma_f32_16x16x32_bf16 v[118:121], v[174:177], v[182:185], v[118:121]
	v_mfma_f32_16x16x32_bf16 v[106:109], v[166:169], v[190:193], v[106:109]
	v_mfma_f32_16x16x32_bf16 v[102:105], v[174:177], v[190:193], v[102:105]
	v_mfma_f32_16x16x32_bf16 v[90:93], v[166:169], v[206:209], v[90:93]
	v_mfma_f32_16x16x32_bf16 v[86:89], v[174:177], v[206:209], v[86:89]
	v_mfma_f32_16x16x32_bf16 v[74:77], v[166:169], v[228:231], v[74:77]
	v_mfma_f32_16x16x32_bf16 v[70:73], v[174:177], v[228:231], v[70:73]
	v_mfma_f32_16x16x32_bf16 v[122:125], v[170:173], v[186:189], v[122:125]
	v_mfma_f32_16x16x32_bf16 v[118:121], v[178:181], v[186:189], v[118:121]
	v_mfma_f32_16x16x32_bf16 v[106:109], v[170:173], v[194:197], v[106:109]
	v_mfma_f32_16x16x32_bf16 v[102:105], v[178:181], v[194:197], v[102:105]
	v_mfma_f32_16x16x32_bf16 v[90:93], v[170:173], v[224:227], v[90:93]
	v_mfma_f32_16x16x32_bf16 v[86:89], v[178:181], v[224:227], v[86:89]
	v_mfma_f32_16x16x32_bf16 v[74:77], v[170:173], v[232:235], v[74:77]
	v_mfma_f32_16x16x32_bf16 v[70:73], v[178:181], v[232:235], v[70:73]
	s_setprio 0
	s_barrier
	ds_read_b128 v[182:185], v148 offset:49152
	ds_read_b128 v[186:189], v148 offset:50176
	ds_read_b128 v[190:193], v148 offset:51200
	ds_read_b128 v[194:197], v148 offset:52224
	s_add_i32 m0, s37, 0x17f80
	ds_read_b128 v[206:209], v148 offset:53248
	global_load_lds_dwordx4 v138, s[44:45] offset:128
	s_add_i32 m0, s37, 0x19f80
	ds_read_b128 v[224:227], v148 offset:54272
	global_load_lds_dwordx4 v134, s[44:45] offset:128
	s_add_i32 m0, s37, 0x1c000
	s_add_u32 s44, s44, 0x160080
	s_addc_u32 s45, s45, 0
	ds_read_b128 v[228:231], v148 offset:55296
	global_load_lds_dwordx4 v138, s[44:45]
	s_add_i32 m0, s37, 0x1e000
	ds_read_b128 v[232:235], v148 offset:56320
	global_load_lds_dwordx4 v134, s[44:45]
	s_waitcnt vmcnt(6) lgkmcnt(0)
	s_barrier
	s_setprio 1
	v_mfma_f32_16x16x32_bf16 v[66:69], v[150:153], v[182:185], v[66:69]
	v_mfma_f32_16x16x32_bf16 v[62:65], v[158:161], v[182:185], v[62:65]
	v_mfma_f32_16x16x32_bf16 v[50:53], v[150:153], v[190:193], v[50:53]
	v_mfma_f32_16x16x32_bf16 v[46:49], v[158:161], v[190:193], v[46:49]
	v_mfma_f32_16x16x32_bf16 v[34:37], v[150:153], v[206:209], v[34:37]
	v_mfma_f32_16x16x32_bf16 v[30:33], v[158:161], v[206:209], v[30:33]
	v_mfma_f32_16x16x32_bf16 v[18:21], v[150:153], v[228:231], v[18:21]
	v_mfma_f32_16x16x32_bf16 v[14:17], v[158:161], v[228:231], v[14:17]
	v_mfma_f32_16x16x32_bf16 v[66:69], v[154:157], v[186:189], v[66:69]
	v_mfma_f32_16x16x32_bf16 v[62:65], v[162:165], v[186:189], v[62:65]
	v_mfma_f32_16x16x32_bf16 v[50:53], v[154:157], v[194:197], v[50:53]
	v_mfma_f32_16x16x32_bf16 v[46:49], v[162:165], v[194:197], v[46:49]
	v_mfma_f32_16x16x32_bf16 v[34:37], v[154:157], v[224:227], v[34:37]
	v_mfma_f32_16x16x32_bf16 v[30:33], v[162:165], v[224:227], v[30:33]
	v_mfma_f32_16x16x32_bf16 v[18:21], v[154:157], v[232:235], v[18:21]
	v_mfma_f32_16x16x32_bf16 v[14:17], v[162:165], v[232:235], v[14:17]
	s_setprio 0
	s_setprio 1
	v_mfma_f32_16x16x32_bf16 v[58:61], v[166:169], v[182:185], v[58:61]
	v_mfma_f32_16x16x32_bf16 v[54:57], v[174:177], v[182:185], v[54:57]
	v_mfma_f32_16x16x32_bf16 v[42:45], v[166:169], v[190:193], v[42:45]
	v_mfma_f32_16x16x32_bf16 v[38:41], v[174:177], v[190:193], v[38:41]
	v_mfma_f32_16x16x32_bf16 v[26:29], v[166:169], v[206:209], v[26:29]
	v_mfma_f32_16x16x32_bf16 v[22:25], v[174:177], v[206:209], v[22:25]
	v_mfma_f32_16x16x32_bf16 v[8:11], v[166:169], v[228:231], v[10:13]
	v_mfma_f32_16x16x32_bf16 v[4:7], v[174:177], v[228:231], v[4:7]
	v_mfma_f32_16x16x32_bf16 v[58:61], v[170:173], v[186:189], v[58:61]
	v_mfma_f32_16x16x32_bf16 v[54:57], v[178:181], v[186:189], v[54:57]
	v_mfma_f32_16x16x32_bf16 v[42:45], v[170:173], v[194:197], v[42:45]
	v_mfma_f32_16x16x32_bf16 v[38:41], v[178:181], v[194:197], v[38:41]
	v_mfma_f32_16x16x32_bf16 v[26:29], v[170:173], v[224:227], v[26:29]
	v_mfma_f32_16x16x32_bf16 v[22:25], v[178:181], v[224:227], v[22:25]
	v_mfma_f32_16x16x32_bf16 v[10:13], v[170:173], v[232:235], v[8:11]
	v_mfma_f32_16x16x32_bf16 v[6:9], v[178:181], v[232:235], v[4:7]
	s_setprio 0
	s_barrier
	s_add_u32 s67, s67, 0x100
	s_addc_u32 s68, s68, 0
	s_cmp_ge_i32 s69, s54
	s_mov_b64 s[48:49], s[42:43]
	s_mov_b32 s44, s69
	s_cbranch_scc0 .LBB0_2287
	s_add_i32 s46, s37, 0x1c000
	s_add_i32 s70, s37, 0x14000
	s_mov_b32 s71, 0x14000
